# LDS fragment read lookahead D=5 (was 4) in the inproj 256x128 loops
# speedup vs baseline: 1.0082x; 1.0082x over previous
.LBB0_171:
	s_lshr_b32 s88, s75, 3
	s_lshl_b32 s88, s88, 4
	s_and_b32 s90, s75, 7
	s_or_b32 s88, s88, s90
	s_lshl_b32 s90, s89, 3
	s_add_i32 s88, s88, s90
	s_ashr_i32 s1, s88, 31
	s_lshr_b32 s1, s1, 23
	s_add_i32 s1, s88, s1
	s_ashr_i32 s1, s1, 9
	s_and_b32 s0, s88, 7
	s_lshl_b32 s1, s1, 3
	s_or_b32 s34, s1, s0
	s_mul_hi_i32 s0, s34, 0x92492493
	s_add_i32 s0, s0, s34
	s_lshr_b32 s1, s0, 31
	s_ashr_i32 s70, s0, 2
	s_add_i32 s70, s70, s1
	s_lshl_b32 s0, s70, 3
	s_bfe_u32 s1, s88, 0x30003
	s_or_b32 s66, s0, s1
	s_mul_i32 s0, s70, 7
	s_sub_i32 s77, s34, s0
	s_lshl_b32 s0, s77, 3
	s_bfe_u32 s76, s88, 0x30006
	s_or_b32 s0, s0, s76
	s_ashr_i32 s67, s66, 31
	s_ashr_i32 s1, s0, 31
	s_lshl_b64 s[4:5], s[0:1], 18
	s_lshl_b64 s[6:7], s[66:67], 18
	s_cmp_lg_u32 s89, 0
	s_cbranch_scc1 .Lmy_ip0_pass2
	s_barrier
	s_setprio 2
	s_lshl_b64 s[64:65], s[66:67], 17
	s_add_u32 s84, s50, 0x3a00000
	s_addc_u32 s85, s51, 0
	s_add_u32 s84, s84, s6
	s_addc_u32 s85, s85, s7
	s_add_u32 s92, s84, 0x40000
	s_addc_u32 s93, s85, 0
	s_add_u32 s86, s50, 0x1a00000
	s_addc_u32 s87, s51, 0
	s_add_u32 s86, s86, s4
	s_addc_u32 s87, s87, s5
	v_readfirstlane_b32 s1, v129
	v_and_b32_e32 v200, 15, v131
	v_bfe_u32 v201, v131, 4, 2
	v_and_b32_e32 v202, 63, v131
	v_lshlrev_b32_e32 v202, 4, v202
	v_lshrrev_b32_e32 v203, 6, v131
	v_lshl_add_u32 v142, v203, 16, v202
	v_add_u32_e32 v150, 0x8000, v142
	v_bfe_u32 v202, v131, 1, 3
	v_xor_b32_e32 v202, v201, v202
	v_lshlrev_b32_e32 v202, 4, v202
	v_lshl_or_b32 v212, v200, 7, v202
	v_xor_b32_e32 v213, 64, v212
	v_bfe_u32 v200, v131, 4, 3
	v_and_b32_e32 v201, 7, v131
	v_xor_b32_e32 v200, v200, v201
	v_lshlrev_b32_e32 v200, 4, v200
	v_lshrrev_b32_e32 v201, 3, v131
	v_lshl_or_b32 v151, v201, 11, v200
	v_add_u32_e32 v156, 65536, v151
	v_add_u32_e32 v158, 131072, v151
	v_add_u32_e32 v159, 196608, v151
	s_add_u32 m0, s1, 0
	v_mov_b32_e32 v0, 0
	v_mov_b32_e32 v1, 0
	global_load_lds_dwordx4 v151, s[86:87]
	v_mov_b32_e32 v2, 0
	v_mov_b32_e32 v3, 0
	v_mov_b32_e32 v4, 0
	s_add_u32 m0, s1, 4096
	v_mov_b32_e32 v5, 0
	v_mov_b32_e32 v6, 0
	global_load_lds_dwordx4 v156, s[86:87]
	v_mov_b32_e32 v7, 0
	v_mov_b32_e32 v8, 0
	v_mov_b32_e32 v9, 0
	s_add_u32 m0, s1, 8192
	v_mov_b32_e32 v10, 0
	v_mov_b32_e32 v11, 0
	global_load_lds_dwordx4 v158, s[86:87]
	v_mov_b32_e32 v12, 0
	v_mov_b32_e32 v13, 0
	v_mov_b32_e32 v14, 0
	s_add_u32 m0, s1, 12288
	v_mov_b32_e32 v15, 0
	v_mov_b32_e32 v16, 0
	global_load_lds_dwordx4 v159, s[86:87]
	s_add_u32 s86, s86, 128
	s_addc_u32 s87, s87, 0
	v_mov_b32_e32 v17, 0
	v_mov_b32_e32 v18, 0
	v_mov_b32_e32 v19, 0
	global_load_dwordx4 v[64:67], v142, s[84:85] offset:0
	v_mov_b32_e32 v20, 0
	v_mov_b32_e32 v21, 0
	v_mov_b32_e32 v22, 0
	global_load_dwordx4 v[68:71], v150, s[84:85] offset:0
	v_mov_b32_e32 v23, 0
	v_mov_b32_e32 v24, 0
	v_mov_b32_e32 v25, 0
	global_load_dwordx4 v[72:75], v142, s[92:93] offset:0
	v_mov_b32_e32 v26, 0
	v_mov_b32_e32 v27, 0
	v_mov_b32_e32 v28, 0
	global_load_dwordx4 v[76:79], v150, s[92:93] offset:0
	v_mov_b32_e32 v29, 0
	v_mov_b32_e32 v30, 0
	v_mov_b32_e32 v31, 0
	global_load_dwordx4 v[80:83], v142, s[84:85] offset:1024
	v_mov_b32_e32 v32, 0
	v_mov_b32_e32 v33, 0
	v_mov_b32_e32 v34, 0
	global_load_dwordx4 v[84:87], v150, s[84:85] offset:1024
	v_mov_b32_e32 v35, 0
	v_mov_b32_e32 v36, 0
	v_mov_b32_e32 v37, 0
	global_load_dwordx4 v[88:91], v142, s[92:93] offset:1024
	v_mov_b32_e32 v38, 0
	v_mov_b32_e32 v39, 0
	v_mov_b32_e32 v40, 0
	global_load_dwordx4 v[92:95], v150, s[92:93] offset:1024
	s_add_u32 s84, s84, 0x800
	s_addc_u32 s85, s85, 0
	s_add_u32 s92, s92, 0x800
	s_addc_u32 s93, s93, 0
	v_mov_b32_e32 v41, 0
	v_mov_b32_e32 v42, 0
	v_mov_b32_e32 v43, 0
	s_add_u32 m0, s1, 16384
	v_mov_b32_e32 v44, 0
	v_mov_b32_e32 v45, 0
	global_load_lds_dwordx4 v151, s[86:87]
	v_mov_b32_e32 v46, 0
	v_mov_b32_e32 v47, 0
	v_mov_b32_e32 v48, 0
	s_add_u32 m0, s1, 20480
	v_mov_b32_e32 v49, 0
	v_mov_b32_e32 v50, 0
	global_load_lds_dwordx4 v156, s[86:87]
	v_mov_b32_e32 v51, 0
	v_mov_b32_e32 v52, 0
	v_mov_b32_e32 v53, 0
	s_add_u32 m0, s1, 24576
	v_mov_b32_e32 v54, 0
	v_mov_b32_e32 v55, 0
	global_load_lds_dwordx4 v158, s[86:87]
	v_mov_b32_e32 v56, 0
	v_mov_b32_e32 v57, 0
	v_mov_b32_e32 v58, 0
	s_add_u32 m0, s1, 28672
	v_mov_b32_e32 v59, 0
	v_mov_b32_e32 v60, 0
	global_load_lds_dwordx4 v159, s[86:87]
	s_add_u32 s86, s86, 128
	s_addc_u32 s87, s87, 0
	v_mov_b32_e32 v61, 0
	v_mov_b32_e32 v62, 0
	v_mov_b32_e32 v63, 0
	s_add_u32 m0, s1, 32768
	v_mov_b32_e32 v144, 0
	v_mov_b32_e32 v145, 0
	global_load_lds_dwordx4 v151, s[86:87]
	v_mov_b32_e32 v146, 0
	v_mov_b32_e32 v147, 0
	v_mov_b32_e32 v184, 0
	s_add_u32 m0, s1, 36864
	v_mov_b32_e32 v185, 0
	v_mov_b32_e32 v186, 0
	global_load_lds_dwordx4 v156, s[86:87]
	v_mov_b32_e32 v187, 0
	v_mov_b32_e32 v204, 0
	v_mov_b32_e32 v205, 0
	s_add_u32 m0, s1, 40960
	v_mov_b32_e32 v206, 0
	v_mov_b32_e32 v207, 0
	global_load_lds_dwordx4 v158, s[86:87]
	v_mov_b32_e32 v208, 0
	v_mov_b32_e32 v209, 0
	v_mov_b32_e32 v210, 0
	s_add_u32 m0, s1, 45056
	v_mov_b32_e32 v211, 0
	v_mov_b32_e32 v232, 0
	global_load_lds_dwordx4 v159, s[86:87]
	s_add_u32 s86, s86, 128
	s_addc_u32 s87, s87, 0
	v_mov_b32_e32 v233, 0
	v_mov_b32_e32 v234, 0
	v_mov_b32_e32 v235, 0
	v_mov_b32_e32 v236, 0
	v_mov_b32_e32 v237, 0
	v_mov_b32_e32 v238, 0
	v_mov_b32_e32 v239, 0
	v_mov_b32_e32 v240, 0
	v_mov_b32_e32 v241, 0
	v_mov_b32_e32 v242, 0
	v_mov_b32_e32 v243, 0
	v_mov_b32_e32 v248, 0
	v_mov_b32_e32 v249, 0
	v_mov_b32_e32 v250, 0
	v_mov_b32_e32 v251, 0
	v_mov_b32_e32 v252, 0
	v_mov_b32_e32 v253, 0
	v_mov_b32_e32 v254, 0
	v_mov_b32_e32 v255, 0
	v_mov_b32_e32 v100, 0
	v_mov_b32_e32 v101, 0
	v_mov_b32_e32 v102, 0
	v_mov_b32_e32 v103, 0
	v_mov_b32_e32 v104, 0
	v_mov_b32_e32 v105, 0
	v_mov_b32_e32 v106, 0
	v_mov_b32_e32 v107, 0
	v_mov_b32_e32 v108, 0
	v_mov_b32_e32 v109, 0
	v_mov_b32_e32 v110, 0
	v_mov_b32_e32 v111, 0
	v_mov_b32_e32 v112, 0
	v_mov_b32_e32 v113, 0
	v_mov_b32_e32 v114, 0
	v_mov_b32_e32 v115, 0
	v_mov_b32_e32 v116, 0
	v_mov_b32_e32 v117, 0
	v_mov_b32_e32 v118, 0
	v_mov_b32_e32 v119, 0
	v_mov_b32_e32 v120, 0
	v_mov_b32_e32 v121, 0
	v_mov_b32_e32 v122, 0
	v_mov_b32_e32 v123, 0
	v_mov_b32_e32 v124, 0
	v_mov_b32_e32 v125, 0
	v_mov_b32_e32 v126, 0
	v_mov_b32_e32 v127, 0
	s_waitcnt vmcnt(12)
	s_barrier
	ds_read_b128 v[160:163], v212 offset:0
	ds_read_b128 v[176:179], v212 offset:2048
	ds_read_b128 v[180:183], v212 offset:4096
	ds_read_b128 v[188:191], v212 offset:6144
	ds_read_b128 v[192:195], v212 offset:8192
	ds_read_b128 v[196:199], v212 offset:10240
	global_load_dwordx4 v[96:99], v142, s[84:85] offset:0
	s_waitcnt lgkmcnt(5)
	v_mfma_f32_16x16x32_bf16 v[0:3], v[64:67], v[160:163], v[0:3]
	v_mfma_f32_16x16x32_bf16 v[32:35], v[68:71], v[160:163], v[32:35]
	v_mfma_f32_16x16x32_bf16 v[144:147], v[72:75], v[160:163], v[144:147]
	v_mfma_f32_16x16x32_bf16 v[252:255], v[76:79], v[160:163], v[252:255]
	ds_read_b128 v[160:163], v212 offset:12288
	global_load_dwordx4 v[164:167], v150, s[84:85] offset:0
	s_waitcnt lgkmcnt(5)
	v_mfma_f32_16x16x32_bf16 v[4:7], v[64:67], v[176:179], v[4:7]
	v_mfma_f32_16x16x32_bf16 v[36:39], v[68:71], v[176:179], v[36:39]
	v_mfma_f32_16x16x32_bf16 v[184:187], v[72:75], v[176:179], v[184:187]
	v_mfma_f32_16x16x32_bf16 v[100:103], v[76:79], v[176:179], v[100:103]
	ds_read_b128 v[176:179], v212 offset:14336
	global_load_dwordx4 v[168:171], v142, s[92:93] offset:0
	s_waitcnt lgkmcnt(5)
	v_mfma_f32_16x16x32_bf16 v[8:11], v[64:67], v[180:183], v[8:11]
	v_mfma_f32_16x16x32_bf16 v[40:43], v[68:71], v[180:183], v[40:43]
	v_mfma_f32_16x16x32_bf16 v[204:207], v[72:75], v[180:183], v[204:207]
	v_mfma_f32_16x16x32_bf16 v[104:107], v[76:79], v[180:183], v[104:107]
	ds_read_b128 v[180:183], v213 offset:0
	global_load_dwordx4 v[172:175], v150, s[92:93] offset:0
	s_waitcnt lgkmcnt(5)
	v_mfma_f32_16x16x32_bf16 v[12:15], v[64:67], v[188:191], v[12:15]
	v_mfma_f32_16x16x32_bf16 v[44:47], v[68:71], v[188:191], v[44:47]
	v_mfma_f32_16x16x32_bf16 v[208:211], v[72:75], v[188:191], v[208:211]
	v_mfma_f32_16x16x32_bf16 v[108:111], v[76:79], v[188:191], v[108:111]
	ds_read_b128 v[188:191], v213 offset:2048
	s_waitcnt lgkmcnt(5)
	v_mfma_f32_16x16x32_bf16 v[16:19], v[64:67], v[192:195], v[16:19]
	v_mfma_f32_16x16x32_bf16 v[48:51], v[68:71], v[192:195], v[48:51]
	v_mfma_f32_16x16x32_bf16 v[232:235], v[72:75], v[192:195], v[232:235]
	v_mfma_f32_16x16x32_bf16 v[112:115], v[76:79], v[192:195], v[112:115]
	ds_read_b128 v[192:195], v213 offset:4096
	s_waitcnt lgkmcnt(5)
	v_mfma_f32_16x16x32_bf16 v[20:23], v[64:67], v[196:199], v[20:23]
	v_mfma_f32_16x16x32_bf16 v[52:55], v[68:71], v[196:199], v[52:55]
	v_mfma_f32_16x16x32_bf16 v[236:239], v[72:75], v[196:199], v[236:239]
	v_mfma_f32_16x16x32_bf16 v[116:119], v[76:79], v[196:199], v[116:119]
	ds_read_b128 v[196:199], v213 offset:6144
	s_waitcnt lgkmcnt(5)
	v_mfma_f32_16x16x32_bf16 v[24:27], v[64:67], v[160:163], v[24:27]
	v_mfma_f32_16x16x32_bf16 v[56:59], v[68:71], v[160:163], v[56:59]
	v_mfma_f32_16x16x32_bf16 v[240:243], v[72:75], v[160:163], v[240:243]
	v_mfma_f32_16x16x32_bf16 v[120:123], v[76:79], v[160:163], v[120:123]
	ds_read_b128 v[160:163], v213 offset:8192
	s_waitcnt lgkmcnt(5)
	v_mfma_f32_16x16x32_bf16 v[28:31], v[64:67], v[176:179], v[28:31]
	v_mfma_f32_16x16x32_bf16 v[60:63], v[68:71], v[176:179], v[60:63]
	v_mfma_f32_16x16x32_bf16 v[248:251], v[72:75], v[176:179], v[248:251]
	v_mfma_f32_16x16x32_bf16 v[124:127], v[76:79], v[176:179], v[124:127]
	s_waitcnt vmcnt(8)
	s_barrier
	s_waitcnt vmcnt(12)
	ds_read_b128 v[176:179], v213 offset:10240
	global_load_dwordx4 v[64:67], v142, s[84:85] offset:1024
	s_waitcnt lgkmcnt(5)
	v_mfma_f32_16x16x32_bf16 v[0:3], v[80:83], v[180:183], v[0:3]
	v_mfma_f32_16x16x32_bf16 v[32:35], v[84:87], v[180:183], v[32:35]
	v_mfma_f32_16x16x32_bf16 v[144:147], v[88:91], v[180:183], v[144:147]
	v_mfma_f32_16x16x32_bf16 v[252:255], v[92:95], v[180:183], v[252:255]
	ds_read_b128 v[180:183], v213 offset:12288
	global_load_dwordx4 v[68:71], v150, s[84:85] offset:1024
	s_waitcnt lgkmcnt(5)
	v_mfma_f32_16x16x32_bf16 v[4:7], v[80:83], v[188:191], v[4:7]
	v_mfma_f32_16x16x32_bf16 v[36:39], v[84:87], v[188:191], v[36:39]
	v_mfma_f32_16x16x32_bf16 v[184:187], v[88:91], v[188:191], v[184:187]
	v_mfma_f32_16x16x32_bf16 v[100:103], v[92:95], v[188:191], v[100:103]
	ds_read_b128 v[188:191], v213 offset:14336
	global_load_dwordx4 v[72:75], v142, s[92:93] offset:1024
	s_waitcnt lgkmcnt(5)
	v_mfma_f32_16x16x32_bf16 v[8:11], v[80:83], v[192:195], v[8:11]
	v_mfma_f32_16x16x32_bf16 v[40:43], v[84:87], v[192:195], v[40:43]
	v_mfma_f32_16x16x32_bf16 v[204:207], v[88:91], v[192:195], v[204:207]
	v_mfma_f32_16x16x32_bf16 v[104:107], v[92:95], v[192:195], v[104:107]
	ds_read_b128 v[192:195], v212 offset:16384
	global_load_dwordx4 v[76:79], v150, s[92:93] offset:1024
	s_add_u32 s84, s84, 0x800
	s_addc_u32 s85, s85, 0
	s_add_u32 s92, s92, 0x800
	s_addc_u32 s93, s93, 0
	s_waitcnt lgkmcnt(5)
	v_mfma_f32_16x16x32_bf16 v[12:15], v[80:83], v[196:199], v[12:15]
	v_mfma_f32_16x16x32_bf16 v[44:47], v[84:87], v[196:199], v[44:47]
	v_mfma_f32_16x16x32_bf16 v[208:211], v[88:91], v[196:199], v[208:211]
	v_mfma_f32_16x16x32_bf16 v[108:111], v[92:95], v[196:199], v[108:111]
	ds_read_b128 v[196:199], v212 offset:18432
	s_add_u32 m0, s1, 49152
	s_nop 0
	global_load_lds_dwordx4 v151, s[86:87]
	s_waitcnt lgkmcnt(5)
	v_mfma_f32_16x16x32_bf16 v[16:19], v[80:83], v[160:163], v[16:19]
	v_mfma_f32_16x16x32_bf16 v[48:51], v[84:87], v[160:163], v[48:51]
	v_mfma_f32_16x16x32_bf16 v[232:235], v[88:91], v[160:163], v[232:235]
	v_mfma_f32_16x16x32_bf16 v[112:115], v[92:95], v[160:163], v[112:115]
	ds_read_b128 v[160:163], v212 offset:20480
	s_add_u32 m0, s1, 53248
	s_nop 0
	global_load_lds_dwordx4 v156, s[86:87]
	s_waitcnt lgkmcnt(5)
	v_mfma_f32_16x16x32_bf16 v[20:23], v[80:83], v[176:179], v[20:23]
	v_mfma_f32_16x16x32_bf16 v[52:55], v[84:87], v[176:179], v[52:55]
	v_mfma_f32_16x16x32_bf16 v[236:239], v[88:91], v[176:179], v[236:239]
	v_mfma_f32_16x16x32_bf16 v[116:119], v[92:95], v[176:179], v[116:119]
	ds_read_b128 v[176:179], v212 offset:22528
	s_add_u32 m0, s1, 57344
	s_nop 0
	global_load_lds_dwordx4 v158, s[86:87]
	s_waitcnt lgkmcnt(5)
	v_mfma_f32_16x16x32_bf16 v[24:27], v[80:83], v[180:183], v[24:27]
	v_mfma_f32_16x16x32_bf16 v[56:59], v[84:87], v[180:183], v[56:59]
	v_mfma_f32_16x16x32_bf16 v[240:243], v[88:91], v[180:183], v[240:243]
	v_mfma_f32_16x16x32_bf16 v[120:123], v[92:95], v[180:183], v[120:123]
	ds_read_b128 v[180:183], v212 offset:24576
	s_add_u32 m0, s1, 61440
	s_nop 0
	global_load_lds_dwordx4 v159, s[86:87]
	s_add_u32 s86, s86, 128
	s_addc_u32 s87, s87, 0
	s_waitcnt lgkmcnt(5)
	v_mfma_f32_16x16x32_bf16 v[28:31], v[80:83], v[188:191], v[28:31]
	v_mfma_f32_16x16x32_bf16 v[60:63], v[84:87], v[188:191], v[60:63]
	v_mfma_f32_16x16x32_bf16 v[248:251], v[88:91], v[188:191], v[248:251]
	v_mfma_f32_16x16x32_bf16 v[124:127], v[92:95], v[188:191], v[124:127]
	s_waitcnt vmcnt(8)
	ds_read_b128 v[188:191], v212 offset:26624
	global_load_dwordx4 v[80:83], v142, s[84:85] offset:0
	s_waitcnt lgkmcnt(5)
	v_mfma_f32_16x16x32_bf16 v[0:3], v[96:99], v[192:195], v[0:3]
	v_mfma_f32_16x16x32_bf16 v[32:35], v[164:167], v[192:195], v[32:35]
	v_mfma_f32_16x16x32_bf16 v[144:147], v[168:171], v[192:195], v[144:147]
	v_mfma_f32_16x16x32_bf16 v[252:255], v[172:175], v[192:195], v[252:255]
	ds_read_b128 v[192:195], v212 offset:28672
	global_load_dwordx4 v[84:87], v150, s[84:85] offset:0
	s_waitcnt lgkmcnt(5)
	v_mfma_f32_16x16x32_bf16 v[4:7], v[96:99], v[196:199], v[4:7]
	v_mfma_f32_16x16x32_bf16 v[36:39], v[164:167], v[196:199], v[36:39]
	v_mfma_f32_16x16x32_bf16 v[184:187], v[168:171], v[196:199], v[184:187]
	v_mfma_f32_16x16x32_bf16 v[100:103], v[172:175], v[196:199], v[100:103]
	ds_read_b128 v[196:199], v212 offset:30720
	global_load_dwordx4 v[88:91], v142, s[92:93] offset:0
	s_waitcnt lgkmcnt(5)
	v_mfma_f32_16x16x32_bf16 v[8:11], v[96:99], v[160:163], v[8:11]
	v_mfma_f32_16x16x32_bf16 v[40:43], v[164:167], v[160:163], v[40:43]
	v_mfma_f32_16x16x32_bf16 v[204:207], v[168:171], v[160:163], v[204:207]
	v_mfma_f32_16x16x32_bf16 v[104:107], v[172:175], v[160:163], v[104:107]
	ds_read_b128 v[160:163], v213 offset:16384
	global_load_dwordx4 v[92:95], v150, s[92:93] offset:0
	s_waitcnt lgkmcnt(5)
	v_mfma_f32_16x16x32_bf16 v[12:15], v[96:99], v[176:179], v[12:15]
	v_mfma_f32_16x16x32_bf16 v[44:47], v[164:167], v[176:179], v[44:47]
	v_mfma_f32_16x16x32_bf16 v[208:211], v[168:171], v[176:179], v[208:211]
	v_mfma_f32_16x16x32_bf16 v[108:111], v[172:175], v[176:179], v[108:111]
	ds_read_b128 v[176:179], v213 offset:18432
	s_waitcnt lgkmcnt(5)
	v_mfma_f32_16x16x32_bf16 v[16:19], v[96:99], v[180:183], v[16:19]
	v_mfma_f32_16x16x32_bf16 v[48:51], v[164:167], v[180:183], v[48:51]
	v_mfma_f32_16x16x32_bf16 v[232:235], v[168:171], v[180:183], v[232:235]
	v_mfma_f32_16x16x32_bf16 v[112:115], v[172:175], v[180:183], v[112:115]
	ds_read_b128 v[180:183], v213 offset:20480
	s_waitcnt lgkmcnt(5)
	v_mfma_f32_16x16x32_bf16 v[20:23], v[96:99], v[188:191], v[20:23]
	v_mfma_f32_16x16x32_bf16 v[52:55], v[164:167], v[188:191], v[52:55]
	v_mfma_f32_16x16x32_bf16 v[236:239], v[168:171], v[188:191], v[236:239]
	v_mfma_f32_16x16x32_bf16 v[116:119], v[172:175], v[188:191], v[116:119]
	ds_read_b128 v[188:191], v213 offset:22528
	s_waitcnt lgkmcnt(5)
	v_mfma_f32_16x16x32_bf16 v[24:27], v[96:99], v[192:195], v[24:27]
	v_mfma_f32_16x16x32_bf16 v[56:59], v[164:167], v[192:195], v[56:59]
	v_mfma_f32_16x16x32_bf16 v[240:243], v[168:171], v[192:195], v[240:243]
	v_mfma_f32_16x16x32_bf16 v[120:123], v[172:175], v[192:195], v[120:123]
	ds_read_b128 v[192:195], v213 offset:24576
	s_waitcnt lgkmcnt(5)
	v_mfma_f32_16x16x32_bf16 v[28:31], v[96:99], v[196:199], v[28:31]
	v_mfma_f32_16x16x32_bf16 v[60:63], v[164:167], v[196:199], v[60:63]
	v_mfma_f32_16x16x32_bf16 v[248:251], v[168:171], v[196:199], v[248:251]
	v_mfma_f32_16x16x32_bf16 v[124:127], v[172:175], v[196:199], v[124:127]
	s_waitcnt vmcnt(16)
	s_barrier
	s_waitcnt vmcnt(8)
	ds_read_b128 v[196:199], v213 offset:26624
	global_load_dwordx4 v[96:99], v142, s[84:85] offset:1024
	s_waitcnt lgkmcnt(5)
	v_mfma_f32_16x16x32_bf16 v[0:3], v[64:67], v[160:163], v[0:3]
	v_mfma_f32_16x16x32_bf16 v[32:35], v[68:71], v[160:163], v[32:35]
	v_mfma_f32_16x16x32_bf16 v[144:147], v[72:75], v[160:163], v[144:147]
	v_mfma_f32_16x16x32_bf16 v[252:255], v[76:79], v[160:163], v[252:255]
	ds_read_b128 v[160:163], v213 offset:28672
	global_load_dwordx4 v[164:167], v150, s[84:85] offset:1024
	s_waitcnt lgkmcnt(5)
	v_mfma_f32_16x16x32_bf16 v[4:7], v[64:67], v[176:179], v[4:7]
	v_mfma_f32_16x16x32_bf16 v[36:39], v[68:71], v[176:179], v[36:39]
	v_mfma_f32_16x16x32_bf16 v[184:187], v[72:75], v[176:179], v[184:187]
	v_mfma_f32_16x16x32_bf16 v[100:103], v[76:79], v[176:179], v[100:103]
	ds_read_b128 v[176:179], v213 offset:30720
	global_load_dwordx4 v[168:171], v142, s[92:93] offset:1024
	s_waitcnt lgkmcnt(5)
	v_mfma_f32_16x16x32_bf16 v[8:11], v[64:67], v[180:183], v[8:11]
	v_mfma_f32_16x16x32_bf16 v[40:43], v[68:71], v[180:183], v[40:43]
	v_mfma_f32_16x16x32_bf16 v[204:207], v[72:75], v[180:183], v[204:207]
	v_mfma_f32_16x16x32_bf16 v[104:107], v[76:79], v[180:183], v[104:107]
	ds_read_b128 v[180:183], v212 offset:32768
	global_load_dwordx4 v[172:175], v150, s[92:93] offset:1024
	s_add_u32 s84, s84, 0x800
	s_addc_u32 s85, s85, 0
	s_add_u32 s92, s92, 0x800
	s_addc_u32 s93, s93, 0
	s_waitcnt lgkmcnt(5)
	v_mfma_f32_16x16x32_bf16 v[12:15], v[64:67], v[188:191], v[12:15]
	v_mfma_f32_16x16x32_bf16 v[44:47], v[68:71], v[188:191], v[44:47]
	v_mfma_f32_16x16x32_bf16 v[208:211], v[72:75], v[188:191], v[208:211]
	v_mfma_f32_16x16x32_bf16 v[108:111], v[76:79], v[188:191], v[108:111]
	ds_read_b128 v[188:191], v212 offset:34816
	s_add_u32 m0, s1, 0
	s_nop 0
	global_load_lds_dwordx4 v151, s[86:87]
	s_waitcnt lgkmcnt(5)
	v_mfma_f32_16x16x32_bf16 v[16:19], v[64:67], v[192:195], v[16:19]
	v_mfma_f32_16x16x32_bf16 v[48:51], v[68:71], v[192:195], v[48:51]
	v_mfma_f32_16x16x32_bf16 v[232:235], v[72:75], v[192:195], v[232:235]
	v_mfma_f32_16x16x32_bf16 v[112:115], v[76:79], v[192:195], v[112:115]
	ds_read_b128 v[192:195], v212 offset:36864
	s_add_u32 m0, s1, 4096
	s_nop 0
	global_load_lds_dwordx4 v156, s[86:87]
	s_waitcnt lgkmcnt(5)
	v_mfma_f32_16x16x32_bf16 v[20:23], v[64:67], v[196:199], v[20:23]
	v_mfma_f32_16x16x32_bf16 v[52:55], v[68:71], v[196:199], v[52:55]
	v_mfma_f32_16x16x32_bf16 v[236:239], v[72:75], v[196:199], v[236:239]
	v_mfma_f32_16x16x32_bf16 v[116:119], v[76:79], v[196:199], v[116:119]
	ds_read_b128 v[196:199], v212 offset:38912
	s_add_u32 m0, s1, 8192
	s_nop 0
	global_load_lds_dwordx4 v158, s[86:87]
	s_waitcnt lgkmcnt(5)
	v_mfma_f32_16x16x32_bf16 v[24:27], v[64:67], v[160:163], v[24:27]
	v_mfma_f32_16x16x32_bf16 v[56:59], v[68:71], v[160:163], v[56:59]
	v_mfma_f32_16x16x32_bf16 v[240:243], v[72:75], v[160:163], v[240:243]
	v_mfma_f32_16x16x32_bf16 v[120:123], v[76:79], v[160:163], v[120:123]
	ds_read_b128 v[160:163], v212 offset:40960
	s_add_u32 m0, s1, 12288
	s_nop 0
	global_load_lds_dwordx4 v159, s[86:87]
	s_add_u32 s86, s86, 128
	s_addc_u32 s87, s87, 0
	s_waitcnt lgkmcnt(5)
	v_mfma_f32_16x16x32_bf16 v[28:31], v[64:67], v[176:179], v[28:31]
	v_mfma_f32_16x16x32_bf16 v[60:63], v[68:71], v[176:179], v[60:63]
	v_mfma_f32_16x16x32_bf16 v[248:251], v[72:75], v[176:179], v[248:251]
	v_mfma_f32_16x16x32_bf16 v[124:127], v[76:79], v[176:179], v[124:127]
	s_waitcnt vmcnt(8)
	ds_read_b128 v[176:179], v212 offset:43008
	global_load_dwordx4 v[64:67], v142, s[84:85] offset:0
	s_waitcnt lgkmcnt(5)
	v_mfma_f32_16x16x32_bf16 v[0:3], v[80:83], v[180:183], v[0:3]
	v_mfma_f32_16x16x32_bf16 v[32:35], v[84:87], v[180:183], v[32:35]
	v_mfma_f32_16x16x32_bf16 v[144:147], v[88:91], v[180:183], v[144:147]
	v_mfma_f32_16x16x32_bf16 v[252:255], v[92:95], v[180:183], v[252:255]
	ds_read_b128 v[180:183], v212 offset:45056
	global_load_dwordx4 v[68:71], v150, s[84:85] offset:0
	s_waitcnt lgkmcnt(5)
	v_mfma_f32_16x16x32_bf16 v[4:7], v[80:83], v[188:191], v[4:7]
	v_mfma_f32_16x16x32_bf16 v[36:39], v[84:87], v[188:191], v[36:39]
	v_mfma_f32_16x16x32_bf16 v[184:187], v[88:91], v[188:191], v[184:187]
	v_mfma_f32_16x16x32_bf16 v[100:103], v[92:95], v[188:191], v[100:103]
	ds_read_b128 v[188:191], v212 offset:47104
	global_load_dwordx4 v[72:75], v142, s[92:93] offset:0
	s_waitcnt lgkmcnt(5)
	v_mfma_f32_16x16x32_bf16 v[8:11], v[80:83], v[192:195], v[8:11]
	v_mfma_f32_16x16x32_bf16 v[40:43], v[84:87], v[192:195], v[40:43]
	v_mfma_f32_16x16x32_bf16 v[204:207], v[88:91], v[192:195], v[204:207]
	v_mfma_f32_16x16x32_bf16 v[104:107], v[92:95], v[192:195], v[104:107]
	ds_read_b128 v[192:195], v213 offset:32768
	global_load_dwordx4 v[76:79], v150, s[92:93] offset:0
	s_waitcnt lgkmcnt(5)
	v_mfma_f32_16x16x32_bf16 v[12:15], v[80:83], v[196:199], v[12:15]
	v_mfma_f32_16x16x32_bf16 v[44:47], v[84:87], v[196:199], v[44:47]
	v_mfma_f32_16x16x32_bf16 v[208:211], v[88:91], v[196:199], v[208:211]
	v_mfma_f32_16x16x32_bf16 v[108:111], v[92:95], v[196:199], v[108:111]
	ds_read_b128 v[196:199], v213 offset:34816
	s_waitcnt lgkmcnt(5)
	v_mfma_f32_16x16x32_bf16 v[16:19], v[80:83], v[160:163], v[16:19]
	v_mfma_f32_16x16x32_bf16 v[48:51], v[84:87], v[160:163], v[48:51]
	v_mfma_f32_16x16x32_bf16 v[232:235], v[88:91], v[160:163], v[232:235]
	v_mfma_f32_16x16x32_bf16 v[112:115], v[92:95], v[160:163], v[112:115]
	ds_read_b128 v[160:163], v213 offset:36864
	s_waitcnt lgkmcnt(5)
	v_mfma_f32_16x16x32_bf16 v[20:23], v[80:83], v[176:179], v[20:23]
	v_mfma_f32_16x16x32_bf16 v[52:55], v[84:87], v[176:179], v[52:55]
	v_mfma_f32_16x16x32_bf16 v[236:239], v[88:91], v[176:179], v[236:239]
	v_mfma_f32_16x16x32_bf16 v[116:119], v[92:95], v[176:179], v[116:119]
	ds_read_b128 v[176:179], v213 offset:38912
	s_waitcnt lgkmcnt(5)
	v_mfma_f32_16x16x32_bf16 v[24:27], v[80:83], v[180:183], v[24:27]
	v_mfma_f32_16x16x32_bf16 v[56:59], v[84:87], v[180:183], v[56:59]
	v_mfma_f32_16x16x32_bf16 v[240:243], v[88:91], v[180:183], v[240:243]
	v_mfma_f32_16x16x32_bf16 v[120:123], v[92:95], v[180:183], v[120:123]
	ds_read_b128 v[180:183], v213 offset:40960
	s_waitcnt lgkmcnt(5)
	v_mfma_f32_16x16x32_bf16 v[28:31], v[80:83], v[188:191], v[28:31]
	v_mfma_f32_16x16x32_bf16 v[60:63], v[84:87], v[188:191], v[60:63]
	v_mfma_f32_16x16x32_bf16 v[248:251], v[88:91], v[188:191], v[248:251]
	v_mfma_f32_16x16x32_bf16 v[124:127], v[92:95], v[188:191], v[124:127]
	s_waitcnt vmcnt(16)
	s_barrier
	s_waitcnt vmcnt(8)
	ds_read_b128 v[188:191], v213 offset:43008
	global_load_dwordx4 v[80:83], v142, s[84:85] offset:1024
	s_waitcnt lgkmcnt(5)
	v_mfma_f32_16x16x32_bf16 v[0:3], v[96:99], v[192:195], v[0:3]
	v_mfma_f32_16x16x32_bf16 v[32:35], v[164:167], v[192:195], v[32:35]
	v_mfma_f32_16x16x32_bf16 v[144:147], v[168:171], v[192:195], v[144:147]
	v_mfma_f32_16x16x32_bf16 v[252:255], v[172:175], v[192:195], v[252:255]
	ds_read_b128 v[192:195], v213 offset:45056
	global_load_dwordx4 v[84:87], v150, s[84:85] offset:1024
	s_waitcnt lgkmcnt(5)
	v_mfma_f32_16x16x32_bf16 v[4:7], v[96:99], v[196:199], v[4:7]
	v_mfma_f32_16x16x32_bf16 v[36:39], v[164:167], v[196:199], v[36:39]
	v_mfma_f32_16x16x32_bf16 v[184:187], v[168:171], v[196:199], v[184:187]
	v_mfma_f32_16x16x32_bf16 v[100:103], v[172:175], v[196:199], v[100:103]
	ds_read_b128 v[196:199], v213 offset:47104
	global_load_dwordx4 v[88:91], v142, s[92:93] offset:1024
	s_waitcnt lgkmcnt(5)
	v_mfma_f32_16x16x32_bf16 v[8:11], v[96:99], v[160:163], v[8:11]
	v_mfma_f32_16x16x32_bf16 v[40:43], v[164:167], v[160:163], v[40:43]
	v_mfma_f32_16x16x32_bf16 v[204:207], v[168:171], v[160:163], v[204:207]
	v_mfma_f32_16x16x32_bf16 v[104:107], v[172:175], v[160:163], v[104:107]
	ds_read_b128 v[160:163], v212 offset:49152
	global_load_dwordx4 v[92:95], v150, s[92:93] offset:1024
	s_add_u32 s84, s84, 0x800
	s_addc_u32 s85, s85, 0
	s_add_u32 s92, s92, 0x800
	s_addc_u32 s93, s93, 0
	s_waitcnt lgkmcnt(5)
	v_mfma_f32_16x16x32_bf16 v[12:15], v[96:99], v[176:179], v[12:15]
	v_mfma_f32_16x16x32_bf16 v[44:47], v[164:167], v[176:179], v[44:47]
	v_mfma_f32_16x16x32_bf16 v[208:211], v[168:171], v[176:179], v[208:211]
	v_mfma_f32_16x16x32_bf16 v[108:111], v[172:175], v[176:179], v[108:111]
	ds_read_b128 v[176:179], v212 offset:51200
	s_add_u32 m0, s1, 16384
	s_nop 0
	global_load_lds_dwordx4 v151, s[86:87]
	s_waitcnt lgkmcnt(5)
	v_mfma_f32_16x16x32_bf16 v[16:19], v[96:99], v[180:183], v[16:19]
	v_mfma_f32_16x16x32_bf16 v[48:51], v[164:167], v[180:183], v[48:51]
	v_mfma_f32_16x16x32_bf16 v[232:235], v[168:171], v[180:183], v[232:235]
	v_mfma_f32_16x16x32_bf16 v[112:115], v[172:175], v[180:183], v[112:115]
	ds_read_b128 v[180:183], v212 offset:53248
	s_add_u32 m0, s1, 20480
	s_nop 0
	global_load_lds_dwordx4 v156, s[86:87]
	s_waitcnt lgkmcnt(5)
	v_mfma_f32_16x16x32_bf16 v[20:23], v[96:99], v[188:191], v[20:23]
	v_mfma_f32_16x16x32_bf16 v[52:55], v[164:167], v[188:191], v[52:55]
	v_mfma_f32_16x16x32_bf16 v[236:239], v[168:171], v[188:191], v[236:239]
	v_mfma_f32_16x16x32_bf16 v[116:119], v[172:175], v[188:191], v[116:119]
	ds_read_b128 v[188:191], v212 offset:55296
	s_add_u32 m0, s1, 24576
	s_nop 0
	global_load_lds_dwordx4 v158, s[86:87]
	s_waitcnt lgkmcnt(5)
	v_mfma_f32_16x16x32_bf16 v[24:27], v[96:99], v[192:195], v[24:27]
	v_mfma_f32_16x16x32_bf16 v[56:59], v[164:167], v[192:195], v[56:59]
	v_mfma_f32_16x16x32_bf16 v[240:243], v[168:171], v[192:195], v[240:243]
	v_mfma_f32_16x16x32_bf16 v[120:123], v[172:175], v[192:195], v[120:123]
	ds_read_b128 v[192:195], v212 offset:57344
	s_add_u32 m0, s1, 28672
	s_nop 0
	global_load_lds_dwordx4 v159, s[86:87]
	s_add_u32 s86, s86, 128
	s_addc_u32 s87, s87, 0
	s_waitcnt lgkmcnt(5)
	v_mfma_f32_16x16x32_bf16 v[28:31], v[96:99], v[196:199], v[28:31]
	v_mfma_f32_16x16x32_bf16 v[60:63], v[164:167], v[196:199], v[60:63]
	v_mfma_f32_16x16x32_bf16 v[248:251], v[168:171], v[196:199], v[248:251]
	v_mfma_f32_16x16x32_bf16 v[124:127], v[172:175], v[196:199], v[124:127]
	s_waitcnt vmcnt(8)
	ds_read_b128 v[196:199], v212 offset:59392
	global_load_dwordx4 v[96:99], v142, s[84:85] offset:0
	s_waitcnt lgkmcnt(5)
	v_mfma_f32_16x16x32_bf16 v[0:3], v[64:67], v[160:163], v[0:3]
	v_mfma_f32_16x16x32_bf16 v[32:35], v[68:71], v[160:163], v[32:35]
	v_mfma_f32_16x16x32_bf16 v[144:147], v[72:75], v[160:163], v[144:147]
	v_mfma_f32_16x16x32_bf16 v[252:255], v[76:79], v[160:163], v[252:255]
	ds_read_b128 v[160:163], v212 offset:61440
	global_load_dwordx4 v[164:167], v150, s[84:85] offset:0
	s_waitcnt lgkmcnt(5)
	v_mfma_f32_16x16x32_bf16 v[4:7], v[64:67], v[176:179], v[4:7]
	v_mfma_f32_16x16x32_bf16 v[36:39], v[68:71], v[176:179], v[36:39]
	v_mfma_f32_16x16x32_bf16 v[184:187], v[72:75], v[176:179], v[184:187]
	v_mfma_f32_16x16x32_bf16 v[100:103], v[76:79], v[176:179], v[100:103]
	ds_read_b128 v[176:179], v212 offset:63488
	global_load_dwordx4 v[168:171], v142, s[92:93] offset:0
	s_waitcnt lgkmcnt(5)
	v_mfma_f32_16x16x32_bf16 v[8:11], v[64:67], v[180:183], v[8:11]
	v_mfma_f32_16x16x32_bf16 v[40:43], v[68:71], v[180:183], v[40:43]
	v_mfma_f32_16x16x32_bf16 v[204:207], v[72:75], v[180:183], v[204:207]
	v_mfma_f32_16x16x32_bf16 v[104:107], v[76:79], v[180:183], v[104:107]
	ds_read_b128 v[180:183], v213 offset:49152
	global_load_dwordx4 v[172:175], v150, s[92:93] offset:0
	s_waitcnt lgkmcnt(5)
	v_mfma_f32_16x16x32_bf16 v[12:15], v[64:67], v[188:191], v[12:15]
	v_mfma_f32_16x16x32_bf16 v[44:47], v[68:71], v[188:191], v[44:47]
	v_mfma_f32_16x16x32_bf16 v[208:211], v[72:75], v[188:191], v[208:211]
	v_mfma_f32_16x16x32_bf16 v[108:111], v[76:79], v[188:191], v[108:111]
	ds_read_b128 v[188:191], v213 offset:51200
	s_waitcnt lgkmcnt(5)
	v_mfma_f32_16x16x32_bf16 v[16:19], v[64:67], v[192:195], v[16:19]
	v_mfma_f32_16x16x32_bf16 v[48:51], v[68:71], v[192:195], v[48:51]
	v_mfma_f32_16x16x32_bf16 v[232:235], v[72:75], v[192:195], v[232:235]
	v_mfma_f32_16x16x32_bf16 v[112:115], v[76:79], v[192:195], v[112:115]
	ds_read_b128 v[192:195], v213 offset:53248
	s_waitcnt lgkmcnt(5)
	v_mfma_f32_16x16x32_bf16 v[20:23], v[64:67], v[196:199], v[20:23]
	v_mfma_f32_16x16x32_bf16 v[52:55], v[68:71], v[196:199], v[52:55]
	v_mfma_f32_16x16x32_bf16 v[236:239], v[72:75], v[196:199], v[236:239]
	v_mfma_f32_16x16x32_bf16 v[116:119], v[76:79], v[196:199], v[116:119]
	ds_read_b128 v[196:199], v213 offset:55296
	s_waitcnt lgkmcnt(5)
	v_mfma_f32_16x16x32_bf16 v[24:27], v[64:67], v[160:163], v[24:27]
	v_mfma_f32_16x16x32_bf16 v[56:59], v[68:71], v[160:163], v[56:59]
	v_mfma_f32_16x16x32_bf16 v[240:243], v[72:75], v[160:163], v[240:243]
	v_mfma_f32_16x16x32_bf16 v[120:123], v[76:79], v[160:163], v[120:123]
	ds_read_b128 v[160:163], v213 offset:57344
	s_waitcnt lgkmcnt(5)
	v_mfma_f32_16x16x32_bf16 v[28:31], v[64:67], v[176:179], v[28:31]
	v_mfma_f32_16x16x32_bf16 v[60:63], v[68:71], v[176:179], v[60:63]
	v_mfma_f32_16x16x32_bf16 v[248:251], v[72:75], v[176:179], v[248:251]
	v_mfma_f32_16x16x32_bf16 v[124:127], v[76:79], v[176:179], v[124:127]
	s_waitcnt vmcnt(16)
	s_barrier
	s_waitcnt vmcnt(8)
	ds_read_b128 v[176:179], v213 offset:59392
	global_load_dwordx4 v[64:67], v142, s[84:85] offset:1024
	s_waitcnt lgkmcnt(5)
	v_mfma_f32_16x16x32_bf16 v[0:3], v[80:83], v[180:183], v[0:3]
	v_mfma_f32_16x16x32_bf16 v[32:35], v[84:87], v[180:183], v[32:35]
	v_mfma_f32_16x16x32_bf16 v[144:147], v[88:91], v[180:183], v[144:147]
	v_mfma_f32_16x16x32_bf16 v[252:255], v[92:95], v[180:183], v[252:255]
	ds_read_b128 v[180:183], v213 offset:61440
	global_load_dwordx4 v[68:71], v150, s[84:85] offset:1024
	s_waitcnt lgkmcnt(5)
	v_mfma_f32_16x16x32_bf16 v[4:7], v[80:83], v[188:191], v[4:7]
	v_mfma_f32_16x16x32_bf16 v[36:39], v[84:87], v[188:191], v[36:39]
	v_mfma_f32_16x16x32_bf16 v[184:187], v[88:91], v[188:191], v[184:187]
	v_mfma_f32_16x16x32_bf16 v[100:103], v[92:95], v[188:191], v[100:103]
	ds_read_b128 v[188:191], v213 offset:63488
	global_load_dwordx4 v[72:75], v142, s[92:93] offset:1024
	s_waitcnt lgkmcnt(5)
	v_mfma_f32_16x16x32_bf16 v[8:11], v[80:83], v[192:195], v[8:11]
	v_mfma_f32_16x16x32_bf16 v[40:43], v[84:87], v[192:195], v[40:43]
	v_mfma_f32_16x16x32_bf16 v[204:207], v[88:91], v[192:195], v[204:207]
	v_mfma_f32_16x16x32_bf16 v[104:107], v[92:95], v[192:195], v[104:107]
	ds_read_b128 v[192:195], v212 offset:0
	global_load_dwordx4 v[76:79], v150, s[92:93] offset:1024
	s_add_u32 s84, s84, 0x800
	s_addc_u32 s85, s85, 0
	s_add_u32 s92, s92, 0x800
	s_addc_u32 s93, s93, 0
	s_waitcnt lgkmcnt(5)
	v_mfma_f32_16x16x32_bf16 v[12:15], v[80:83], v[196:199], v[12:15]
	v_mfma_f32_16x16x32_bf16 v[44:47], v[84:87], v[196:199], v[44:47]
	v_mfma_f32_16x16x32_bf16 v[208:211], v[88:91], v[196:199], v[208:211]
	v_mfma_f32_16x16x32_bf16 v[108:111], v[92:95], v[196:199], v[108:111]
	ds_read_b128 v[196:199], v212 offset:2048
	s_add_u32 m0, s1, 32768
	s_nop 0
	global_load_lds_dwordx4 v151, s[86:87]
	s_waitcnt lgkmcnt(5)
	v_mfma_f32_16x16x32_bf16 v[16:19], v[80:83], v[160:163], v[16:19]
	v_mfma_f32_16x16x32_bf16 v[48:51], v[84:87], v[160:163], v[48:51]
	v_mfma_f32_16x16x32_bf16 v[232:235], v[88:91], v[160:163], v[232:235]
	v_mfma_f32_16x16x32_bf16 v[112:115], v[92:95], v[160:163], v[112:115]
	ds_read_b128 v[160:163], v212 offset:4096
	s_add_u32 m0, s1, 36864
	s_nop 0
	global_load_lds_dwordx4 v156, s[86:87]
	s_waitcnt lgkmcnt(5)
	v_mfma_f32_16x16x32_bf16 v[20:23], v[80:83], v[176:179], v[20:23]
	v_mfma_f32_16x16x32_bf16 v[52:55], v[84:87], v[176:179], v[52:55]
	v_mfma_f32_16x16x32_bf16 v[236:239], v[88:91], v[176:179], v[236:239]
	v_mfma_f32_16x16x32_bf16 v[116:119], v[92:95], v[176:179], v[116:119]
	ds_read_b128 v[176:179], v212 offset:6144
	s_add_u32 m0, s1, 40960
	s_nop 0
	global_load_lds_dwordx4 v158, s[86:87]
	s_waitcnt lgkmcnt(5)
	v_mfma_f32_16x16x32_bf16 v[24:27], v[80:83], v[180:183], v[24:27]
	v_mfma_f32_16x16x32_bf16 v[56:59], v[84:87], v[180:183], v[56:59]
	v_mfma_f32_16x16x32_bf16 v[240:243], v[88:91], v[180:183], v[240:243]
	v_mfma_f32_16x16x32_bf16 v[120:123], v[92:95], v[180:183], v[120:123]
	ds_read_b128 v[180:183], v212 offset:8192
	s_add_u32 m0, s1, 45056
	s_nop 0
	global_load_lds_dwordx4 v159, s[86:87]
	s_add_u32 s86, s86, 128
	s_addc_u32 s87, s87, 0
	s_waitcnt lgkmcnt(5)
	v_mfma_f32_16x16x32_bf16 v[28:31], v[80:83], v[188:191], v[28:31]
	v_mfma_f32_16x16x32_bf16 v[60:63], v[84:87], v[188:191], v[60:63]
	v_mfma_f32_16x16x32_bf16 v[248:251], v[88:91], v[188:191], v[248:251]
	v_mfma_f32_16x16x32_bf16 v[124:127], v[92:95], v[188:191], v[124:127]
	s_waitcnt vmcnt(8)
	ds_read_b128 v[188:191], v212 offset:10240
	global_load_dwordx4 v[80:83], v142, s[84:85] offset:0
	s_waitcnt lgkmcnt(5)
	v_mfma_f32_16x16x32_bf16 v[0:3], v[96:99], v[192:195], v[0:3]
	v_mfma_f32_16x16x32_bf16 v[32:35], v[164:167], v[192:195], v[32:35]
	v_mfma_f32_16x16x32_bf16 v[144:147], v[168:171], v[192:195], v[144:147]
	v_mfma_f32_16x16x32_bf16 v[252:255], v[172:175], v[192:195], v[252:255]
	ds_read_b128 v[192:195], v212 offset:12288
	global_load_dwordx4 v[84:87], v150, s[84:85] offset:0
	s_waitcnt lgkmcnt(5)
	v_mfma_f32_16x16x32_bf16 v[4:7], v[96:99], v[196:199], v[4:7]
	v_mfma_f32_16x16x32_bf16 v[36:39], v[164:167], v[196:199], v[36:39]
	v_mfma_f32_16x16x32_bf16 v[184:187], v[168:171], v[196:199], v[184:187]
	v_mfma_f32_16x16x32_bf16 v[100:103], v[172:175], v[196:199], v[100:103]
	ds_read_b128 v[196:199], v212 offset:14336
	global_load_dwordx4 v[88:91], v142, s[92:93] offset:0
	s_waitcnt lgkmcnt(5)
	v_mfma_f32_16x16x32_bf16 v[8:11], v[96:99], v[160:163], v[8:11]
	v_mfma_f32_16x16x32_bf16 v[40:43], v[164:167], v[160:163], v[40:43]
	v_mfma_f32_16x16x32_bf16 v[204:207], v[168:171], v[160:163], v[204:207]
	v_mfma_f32_16x16x32_bf16 v[104:107], v[172:175], v[160:163], v[104:107]
	ds_read_b128 v[160:163], v213 offset:0
	global_load_dwordx4 v[92:95], v150, s[92:93] offset:0
	s_waitcnt lgkmcnt(5)
	v_mfma_f32_16x16x32_bf16 v[12:15], v[96:99], v[176:179], v[12:15]
	v_mfma_f32_16x16x32_bf16 v[44:47], v[164:167], v[176:179], v[44:47]
	v_mfma_f32_16x16x32_bf16 v[208:211], v[168:171], v[176:179], v[208:211]
	v_mfma_f32_16x16x32_bf16 v[108:111], v[172:175], v[176:179], v[108:111]
	ds_read_b128 v[176:179], v213 offset:2048
	s_waitcnt lgkmcnt(5)
	v_mfma_f32_16x16x32_bf16 v[16:19], v[96:99], v[180:183], v[16:19]
	v_mfma_f32_16x16x32_bf16 v[48:51], v[164:167], v[180:183], v[48:51]
	v_mfma_f32_16x16x32_bf16 v[232:235], v[168:171], v[180:183], v[232:235]
	v_mfma_f32_16x16x32_bf16 v[112:115], v[172:175], v[180:183], v[112:115]
	ds_read_b128 v[180:183], v213 offset:4096
	s_waitcnt lgkmcnt(5)
	v_mfma_f32_16x16x32_bf16 v[20:23], v[96:99], v[188:191], v[20:23]
	v_mfma_f32_16x16x32_bf16 v[52:55], v[164:167], v[188:191], v[52:55]
	v_mfma_f32_16x16x32_bf16 v[236:239], v[168:171], v[188:191], v[236:239]
	v_mfma_f32_16x16x32_bf16 v[116:119], v[172:175], v[188:191], v[116:119]
	ds_read_b128 v[188:191], v213 offset:6144
	s_waitcnt lgkmcnt(5)
	v_mfma_f32_16x16x32_bf16 v[24:27], v[96:99], v[192:195], v[24:27]
	v_mfma_f32_16x16x32_bf16 v[56:59], v[164:167], v[192:195], v[56:59]
	v_mfma_f32_16x16x32_bf16 v[240:243], v[168:171], v[192:195], v[240:243]
	v_mfma_f32_16x16x32_bf16 v[120:123], v[172:175], v[192:195], v[120:123]
	ds_read_b128 v[192:195], v213 offset:8192
	s_waitcnt lgkmcnt(5)
	v_mfma_f32_16x16x32_bf16 v[28:31], v[96:99], v[196:199], v[28:31]
	v_mfma_f32_16x16x32_bf16 v[60:63], v[164:167], v[196:199], v[60:63]
	v_mfma_f32_16x16x32_bf16 v[248:251], v[168:171], v[196:199], v[248:251]
	v_mfma_f32_16x16x32_bf16 v[124:127], v[172:175], v[196:199], v[124:127]
	s_waitcnt vmcnt(16)
	s_barrier
	s_waitcnt vmcnt(8)
	ds_read_b128 v[196:199], v213 offset:10240
	global_load_dwordx4 v[96:99], v142, s[84:85] offset:1024
	s_waitcnt lgkmcnt(5)
	v_mfma_f32_16x16x32_bf16 v[0:3], v[64:67], v[160:163], v[0:3]
	v_mfma_f32_16x16x32_bf16 v[32:35], v[68:71], v[160:163], v[32:35]
	v_mfma_f32_16x16x32_bf16 v[144:147], v[72:75], v[160:163], v[144:147]
	v_mfma_f32_16x16x32_bf16 v[252:255], v[76:79], v[160:163], v[252:255]
	ds_read_b128 v[160:163], v213 offset:12288
	global_load_dwordx4 v[164:167], v150, s[84:85] offset:1024
	s_waitcnt lgkmcnt(5)
	v_mfma_f32_16x16x32_bf16 v[4:7], v[64:67], v[176:179], v[4:7]
	v_mfma_f32_16x16x32_bf16 v[36:39], v[68:71], v[176:179], v[36:39]
	v_mfma_f32_16x16x32_bf16 v[184:187], v[72:75], v[176:179], v[184:187]
	v_mfma_f32_16x16x32_bf16 v[100:103], v[76:79], v[176:179], v[100:103]
	ds_read_b128 v[176:179], v213 offset:14336
	global_load_dwordx4 v[168:171], v142, s[92:93] offset:1024
	s_waitcnt lgkmcnt(5)
	v_mfma_f32_16x16x32_bf16 v[8:11], v[64:67], v[180:183], v[8:11]
	v_mfma_f32_16x16x32_bf16 v[40:43], v[68:71], v[180:183], v[40:43]
	v_mfma_f32_16x16x32_bf16 v[204:207], v[72:75], v[180:183], v[204:207]
	v_mfma_f32_16x16x32_bf16 v[104:107], v[76:79], v[180:183], v[104:107]
	ds_read_b128 v[180:183], v212 offset:16384
	global_load_dwordx4 v[172:175], v150, s[92:93] offset:1024
	s_add_u32 s84, s84, 0x800
	s_addc_u32 s85, s85, 0
	s_add_u32 s92, s92, 0x800
	s_addc_u32 s93, s93, 0
	s_waitcnt lgkmcnt(5)
	v_mfma_f32_16x16x32_bf16 v[12:15], v[64:67], v[188:191], v[12:15]
	v_mfma_f32_16x16x32_bf16 v[44:47], v[68:71], v[188:191], v[44:47]
	v_mfma_f32_16x16x32_bf16 v[208:211], v[72:75], v[188:191], v[208:211]
	v_mfma_f32_16x16x32_bf16 v[108:111], v[76:79], v[188:191], v[108:111]
	ds_read_b128 v[188:191], v212 offset:18432
	s_add_u32 m0, s1, 49152
	s_nop 0
	global_load_lds_dwordx4 v151, s[86:87]
	s_waitcnt lgkmcnt(5)
	v_mfma_f32_16x16x32_bf16 v[16:19], v[64:67], v[192:195], v[16:19]
	v_mfma_f32_16x16x32_bf16 v[48:51], v[68:71], v[192:195], v[48:51]
	v_mfma_f32_16x16x32_bf16 v[232:235], v[72:75], v[192:195], v[232:235]
	v_mfma_f32_16x16x32_bf16 v[112:115], v[76:79], v[192:195], v[112:115]
	ds_read_b128 v[192:195], v212 offset:20480
	s_add_u32 m0, s1, 53248
	s_nop 0
	global_load_lds_dwordx4 v156, s[86:87]
	s_waitcnt lgkmcnt(5)
	v_mfma_f32_16x16x32_bf16 v[20:23], v[64:67], v[196:199], v[20:23]
	v_mfma_f32_16x16x32_bf16 v[52:55], v[68:71], v[196:199], v[52:55]
	v_mfma_f32_16x16x32_bf16 v[236:239], v[72:75], v[196:199], v[236:239]
	v_mfma_f32_16x16x32_bf16 v[116:119], v[76:79], v[196:199], v[116:119]
	ds_read_b128 v[196:199], v212 offset:22528
	s_add_u32 m0, s1, 57344
	s_nop 0
	global_load_lds_dwordx4 v158, s[86:87]
	s_waitcnt lgkmcnt(5)
	v_mfma_f32_16x16x32_bf16 v[24:27], v[64:67], v[160:163], v[24:27]
	v_mfma_f32_16x16x32_bf16 v[56:59], v[68:71], v[160:163], v[56:59]
	v_mfma_f32_16x16x32_bf16 v[240:243], v[72:75], v[160:163], v[240:243]
	v_mfma_f32_16x16x32_bf16 v[120:123], v[76:79], v[160:163], v[120:123]
	ds_read_b128 v[160:163], v212 offset:24576
	s_add_u32 m0, s1, 61440
	s_nop 0
	global_load_lds_dwordx4 v159, s[86:87]
	s_add_u32 s86, s86, 128
	s_addc_u32 s87, s87, 0
	s_waitcnt lgkmcnt(5)
	v_mfma_f32_16x16x32_bf16 v[28:31], v[64:67], v[176:179], v[28:31]
	v_mfma_f32_16x16x32_bf16 v[60:63], v[68:71], v[176:179], v[60:63]
	v_mfma_f32_16x16x32_bf16 v[248:251], v[72:75], v[176:179], v[248:251]
	v_mfma_f32_16x16x32_bf16 v[124:127], v[76:79], v[176:179], v[124:127]
	s_waitcnt vmcnt(8)
	ds_read_b128 v[176:179], v212 offset:26624
	global_load_dwordx4 v[64:67], v142, s[84:85] offset:0
	s_waitcnt lgkmcnt(5)
	v_mfma_f32_16x16x32_bf16 v[0:3], v[80:83], v[180:183], v[0:3]
	v_mfma_f32_16x16x32_bf16 v[32:35], v[84:87], v[180:183], v[32:35]
	v_mfma_f32_16x16x32_bf16 v[144:147], v[88:91], v[180:183], v[144:147]
	v_mfma_f32_16x16x32_bf16 v[252:255], v[92:95], v[180:183], v[252:255]
	ds_read_b128 v[180:183], v212 offset:28672
	global_load_dwordx4 v[68:71], v150, s[84:85] offset:0
	s_waitcnt lgkmcnt(5)
	v_mfma_f32_16x16x32_bf16 v[4:7], v[80:83], v[188:191], v[4:7]
	v_mfma_f32_16x16x32_bf16 v[36:39], v[84:87], v[188:191], v[36:39]
	v_mfma_f32_16x16x32_bf16 v[184:187], v[88:91], v[188:191], v[184:187]
	v_mfma_f32_16x16x32_bf16 v[100:103], v[92:95], v[188:191], v[100:103]
	ds_read_b128 v[188:191], v212 offset:30720
	global_load_dwordx4 v[72:75], v142, s[92:93] offset:0
	s_waitcnt lgkmcnt(5)
	v_mfma_f32_16x16x32_bf16 v[8:11], v[80:83], v[192:195], v[8:11]
	v_mfma_f32_16x16x32_bf16 v[40:43], v[84:87], v[192:195], v[40:43]
	v_mfma_f32_16x16x32_bf16 v[204:207], v[88:91], v[192:195], v[204:207]
	v_mfma_f32_16x16x32_bf16 v[104:107], v[92:95], v[192:195], v[104:107]
	ds_read_b128 v[192:195], v213 offset:16384
	global_load_dwordx4 v[76:79], v150, s[92:93] offset:0
	s_waitcnt lgkmcnt(5)
	v_mfma_f32_16x16x32_bf16 v[12:15], v[80:83], v[196:199], v[12:15]
	v_mfma_f32_16x16x32_bf16 v[44:47], v[84:87], v[196:199], v[44:47]
	v_mfma_f32_16x16x32_bf16 v[208:211], v[88:91], v[196:199], v[208:211]
	v_mfma_f32_16x16x32_bf16 v[108:111], v[92:95], v[196:199], v[108:111]
	ds_read_b128 v[196:199], v213 offset:18432
	s_waitcnt lgkmcnt(5)
	v_mfma_f32_16x16x32_bf16 v[16:19], v[80:83], v[160:163], v[16:19]
	v_mfma_f32_16x16x32_bf16 v[48:51], v[84:87], v[160:163], v[48:51]
	v_mfma_f32_16x16x32_bf16 v[232:235], v[88:91], v[160:163], v[232:235]
	v_mfma_f32_16x16x32_bf16 v[112:115], v[92:95], v[160:163], v[112:115]
	ds_read_b128 v[160:163], v213 offset:20480
	s_waitcnt lgkmcnt(5)
	v_mfma_f32_16x16x32_bf16 v[20:23], v[80:83], v[176:179], v[20:23]
	v_mfma_f32_16x16x32_bf16 v[52:55], v[84:87], v[176:179], v[52:55]
	v_mfma_f32_16x16x32_bf16 v[236:239], v[88:91], v[176:179], v[236:239]
	v_mfma_f32_16x16x32_bf16 v[116:119], v[92:95], v[176:179], v[116:119]
	ds_read_b128 v[176:179], v213 offset:22528
	s_waitcnt lgkmcnt(5)
	v_mfma_f32_16x16x32_bf16 v[24:27], v[80:83], v[180:183], v[24:27]
	v_mfma_f32_16x16x32_bf16 v[56:59], v[84:87], v[180:183], v[56:59]
	v_mfma_f32_16x16x32_bf16 v[240:243], v[88:91], v[180:183], v[240:243]
	v_mfma_f32_16x16x32_bf16 v[120:123], v[92:95], v[180:183], v[120:123]
	ds_read_b128 v[180:183], v213 offset:24576
	s_waitcnt lgkmcnt(5)
	v_mfma_f32_16x16x32_bf16 v[28:31], v[80:83], v[188:191], v[28:31]
	v_mfma_f32_16x16x32_bf16 v[60:63], v[84:87], v[188:191], v[60:63]
	v_mfma_f32_16x16x32_bf16 v[248:251], v[88:91], v[188:191], v[248:251]
	v_mfma_f32_16x16x32_bf16 v[124:127], v[92:95], v[188:191], v[124:127]
	s_waitcnt vmcnt(16)
	s_barrier
	s_waitcnt vmcnt(8)
	ds_read_b128 v[188:191], v213 offset:26624
	global_load_dwordx4 v[80:83], v142, s[84:85] offset:1024
	s_waitcnt lgkmcnt(5)
	v_mfma_f32_16x16x32_bf16 v[0:3], v[96:99], v[192:195], v[0:3]
	v_mfma_f32_16x16x32_bf16 v[32:35], v[164:167], v[192:195], v[32:35]
	v_mfma_f32_16x16x32_bf16 v[144:147], v[168:171], v[192:195], v[144:147]
	v_mfma_f32_16x16x32_bf16 v[252:255], v[172:175], v[192:195], v[252:255]
	ds_read_b128 v[192:195], v213 offset:28672
	global_load_dwordx4 v[84:87], v150, s[84:85] offset:1024
	s_waitcnt lgkmcnt(5)
	v_mfma_f32_16x16x32_bf16 v[4:7], v[96:99], v[196:199], v[4:7]
	v_mfma_f32_16x16x32_bf16 v[36:39], v[164:167], v[196:199], v[36:39]
	v_mfma_f32_16x16x32_bf16 v[184:187], v[168:171], v[196:199], v[184:187]
	v_mfma_f32_16x16x32_bf16 v[100:103], v[172:175], v[196:199], v[100:103]
	ds_read_b128 v[196:199], v213 offset:30720
	global_load_dwordx4 v[88:91], v142, s[92:93] offset:1024
	s_waitcnt lgkmcnt(5)
	v_mfma_f32_16x16x32_bf16 v[8:11], v[96:99], v[160:163], v[8:11]
	v_mfma_f32_16x16x32_bf16 v[40:43], v[164:167], v[160:163], v[40:43]
	v_mfma_f32_16x16x32_bf16 v[204:207], v[168:171], v[160:163], v[204:207]
	v_mfma_f32_16x16x32_bf16 v[104:107], v[172:175], v[160:163], v[104:107]
	ds_read_b128 v[160:163], v212 offset:32768
	global_load_dwordx4 v[92:95], v150, s[92:93] offset:1024
	s_add_u32 s84, s84, 0x800
	s_addc_u32 s85, s85, 0
	s_add_u32 s92, s92, 0x800
	s_addc_u32 s93, s93, 0
	s_waitcnt lgkmcnt(5)
	v_mfma_f32_16x16x32_bf16 v[12:15], v[96:99], v[176:179], v[12:15]
	v_mfma_f32_16x16x32_bf16 v[44:47], v[164:167], v[176:179], v[44:47]
	v_mfma_f32_16x16x32_bf16 v[208:211], v[168:171], v[176:179], v[208:211]
	v_mfma_f32_16x16x32_bf16 v[108:111], v[172:175], v[176:179], v[108:111]
	ds_read_b128 v[176:179], v212 offset:34816
	s_add_u32 m0, s1, 0
	s_nop 0
	global_load_lds_dwordx4 v151, s[86:87]
	s_waitcnt lgkmcnt(5)
	v_mfma_f32_16x16x32_bf16 v[16:19], v[96:99], v[180:183], v[16:19]
	v_mfma_f32_16x16x32_bf16 v[48:51], v[164:167], v[180:183], v[48:51]
	v_mfma_f32_16x16x32_bf16 v[232:235], v[168:171], v[180:183], v[232:235]
	v_mfma_f32_16x16x32_bf16 v[112:115], v[172:175], v[180:183], v[112:115]
	ds_read_b128 v[180:183], v212 offset:36864
	s_add_u32 m0, s1, 4096
	s_nop 0
	global_load_lds_dwordx4 v156, s[86:87]
	s_waitcnt lgkmcnt(5)
	v_mfma_f32_16x16x32_bf16 v[20:23], v[96:99], v[188:191], v[20:23]
	v_mfma_f32_16x16x32_bf16 v[52:55], v[164:167], v[188:191], v[52:55]
	v_mfma_f32_16x16x32_bf16 v[236:239], v[168:171], v[188:191], v[236:239]
	v_mfma_f32_16x16x32_bf16 v[116:119], v[172:175], v[188:191], v[116:119]
	ds_read_b128 v[188:191], v212 offset:38912
	s_add_u32 m0, s1, 8192
	s_nop 0
	global_load_lds_dwordx4 v158, s[86:87]
	s_waitcnt lgkmcnt(5)
	v_mfma_f32_16x16x32_bf16 v[24:27], v[96:99], v[192:195], v[24:27]
	v_mfma_f32_16x16x32_bf16 v[56:59], v[164:167], v[192:195], v[56:59]
	v_mfma_f32_16x16x32_bf16 v[240:243], v[168:171], v[192:195], v[240:243]
	v_mfma_f32_16x16x32_bf16 v[120:123], v[172:175], v[192:195], v[120:123]
	ds_read_b128 v[192:195], v212 offset:40960
	s_add_u32 m0, s1, 12288
	s_nop 0
	global_load_lds_dwordx4 v159, s[86:87]
	s_add_u32 s86, s86, 128
	s_addc_u32 s87, s87, 0
	s_waitcnt lgkmcnt(5)
	v_mfma_f32_16x16x32_bf16 v[28:31], v[96:99], v[196:199], v[28:31]
	v_mfma_f32_16x16x32_bf16 v[60:63], v[164:167], v[196:199], v[60:63]
	v_mfma_f32_16x16x32_bf16 v[248:251], v[168:171], v[196:199], v[248:251]
	v_mfma_f32_16x16x32_bf16 v[124:127], v[172:175], v[196:199], v[124:127]
	s_waitcnt vmcnt(8)
	ds_read_b128 v[196:199], v212 offset:43008
	global_load_dwordx4 v[96:99], v142, s[84:85] offset:0
	s_waitcnt lgkmcnt(5)
	v_mfma_f32_16x16x32_bf16 v[0:3], v[64:67], v[160:163], v[0:3]
	v_mfma_f32_16x16x32_bf16 v[32:35], v[68:71], v[160:163], v[32:35]
	v_mfma_f32_16x16x32_bf16 v[144:147], v[72:75], v[160:163], v[144:147]
	v_mfma_f32_16x16x32_bf16 v[252:255], v[76:79], v[160:163], v[252:255]
	ds_read_b128 v[160:163], v212 offset:45056
	global_load_dwordx4 v[164:167], v150, s[84:85] offset:0
	s_waitcnt lgkmcnt(5)
	v_mfma_f32_16x16x32_bf16 v[4:7], v[64:67], v[176:179], v[4:7]
	v_mfma_f32_16x16x32_bf16 v[36:39], v[68:71], v[176:179], v[36:39]
	v_mfma_f32_16x16x32_bf16 v[184:187], v[72:75], v[176:179], v[184:187]
	v_mfma_f32_16x16x32_bf16 v[100:103], v[76:79], v[176:179], v[100:103]
	ds_read_b128 v[176:179], v212 offset:47104
	global_load_dwordx4 v[168:171], v142, s[92:93] offset:0
	s_waitcnt lgkmcnt(5)
	v_mfma_f32_16x16x32_bf16 v[8:11], v[64:67], v[180:183], v[8:11]
	v_mfma_f32_16x16x32_bf16 v[40:43], v[68:71], v[180:183], v[40:43]
	v_mfma_f32_16x16x32_bf16 v[204:207], v[72:75], v[180:183], v[204:207]
	v_mfma_f32_16x16x32_bf16 v[104:107], v[76:79], v[180:183], v[104:107]
	ds_read_b128 v[180:183], v213 offset:32768
	global_load_dwordx4 v[172:175], v150, s[92:93] offset:0
	s_waitcnt lgkmcnt(5)
	v_mfma_f32_16x16x32_bf16 v[12:15], v[64:67], v[188:191], v[12:15]
	v_mfma_f32_16x16x32_bf16 v[44:47], v[68:71], v[188:191], v[44:47]
	v_mfma_f32_16x16x32_bf16 v[208:211], v[72:75], v[188:191], v[208:211]
	v_mfma_f32_16x16x32_bf16 v[108:111], v[76:79], v[188:191], v[108:111]
	ds_read_b128 v[188:191], v213 offset:34816
	s_waitcnt lgkmcnt(5)
	v_mfma_f32_16x16x32_bf16 v[16:19], v[64:67], v[192:195], v[16:19]
	v_mfma_f32_16x16x32_bf16 v[48:51], v[68:71], v[192:195], v[48:51]
	v_mfma_f32_16x16x32_bf16 v[232:235], v[72:75], v[192:195], v[232:235]
	v_mfma_f32_16x16x32_bf16 v[112:115], v[76:79], v[192:195], v[112:115]
	ds_read_b128 v[192:195], v213 offset:36864
	s_waitcnt lgkmcnt(5)
	v_mfma_f32_16x16x32_bf16 v[20:23], v[64:67], v[196:199], v[20:23]
	v_mfma_f32_16x16x32_bf16 v[52:55], v[68:71], v[196:199], v[52:55]
	v_mfma_f32_16x16x32_bf16 v[236:239], v[72:75], v[196:199], v[236:239]
	v_mfma_f32_16x16x32_bf16 v[116:119], v[76:79], v[196:199], v[116:119]
	ds_read_b128 v[196:199], v213 offset:38912
	s_waitcnt lgkmcnt(5)
	v_mfma_f32_16x16x32_bf16 v[24:27], v[64:67], v[160:163], v[24:27]
	v_mfma_f32_16x16x32_bf16 v[56:59], v[68:71], v[160:163], v[56:59]
	v_mfma_f32_16x16x32_bf16 v[240:243], v[72:75], v[160:163], v[240:243]
	v_mfma_f32_16x16x32_bf16 v[120:123], v[76:79], v[160:163], v[120:123]
	ds_read_b128 v[160:163], v213 offset:40960
	s_waitcnt lgkmcnt(5)
	v_mfma_f32_16x16x32_bf16 v[28:31], v[64:67], v[176:179], v[28:31]
	v_mfma_f32_16x16x32_bf16 v[60:63], v[68:71], v[176:179], v[60:63]
	v_mfma_f32_16x16x32_bf16 v[248:251], v[72:75], v[176:179], v[248:251]
	v_mfma_f32_16x16x32_bf16 v[124:127], v[76:79], v[176:179], v[124:127]
	s_waitcnt vmcnt(16)
	s_barrier
	s_waitcnt vmcnt(8)
	ds_read_b128 v[176:179], v213 offset:43008
	global_load_dwordx4 v[64:67], v142, s[84:85] offset:1024
	s_waitcnt lgkmcnt(5)
	v_mfma_f32_16x16x32_bf16 v[0:3], v[80:83], v[180:183], v[0:3]
	v_mfma_f32_16x16x32_bf16 v[32:35], v[84:87], v[180:183], v[32:35]
	v_mfma_f32_16x16x32_bf16 v[144:147], v[88:91], v[180:183], v[144:147]
	v_mfma_f32_16x16x32_bf16 v[252:255], v[92:95], v[180:183], v[252:255]
	ds_read_b128 v[180:183], v213 offset:45056
	global_load_dwordx4 v[68:71], v150, s[84:85] offset:1024
	s_waitcnt lgkmcnt(5)
	v_mfma_f32_16x16x32_bf16 v[4:7], v[80:83], v[188:191], v[4:7]
	v_mfma_f32_16x16x32_bf16 v[36:39], v[84:87], v[188:191], v[36:39]
	v_mfma_f32_16x16x32_bf16 v[184:187], v[88:91], v[188:191], v[184:187]
	v_mfma_f32_16x16x32_bf16 v[100:103], v[92:95], v[188:191], v[100:103]
	ds_read_b128 v[188:191], v213 offset:47104
	global_load_dwordx4 v[72:75], v142, s[92:93] offset:1024
	s_waitcnt lgkmcnt(5)
	v_mfma_f32_16x16x32_bf16 v[8:11], v[80:83], v[192:195], v[8:11]
	v_mfma_f32_16x16x32_bf16 v[40:43], v[84:87], v[192:195], v[40:43]
	v_mfma_f32_16x16x32_bf16 v[204:207], v[88:91], v[192:195], v[204:207]
	v_mfma_f32_16x16x32_bf16 v[104:107], v[92:95], v[192:195], v[104:107]
	ds_read_b128 v[192:195], v212 offset:49152
	global_load_dwordx4 v[76:79], v150, s[92:93] offset:1024
	s_add_u32 s84, s84, 0x800
	s_addc_u32 s85, s85, 0
	s_add_u32 s92, s92, 0x800
	s_addc_u32 s93, s93, 0
	s_waitcnt lgkmcnt(5)
	v_mfma_f32_16x16x32_bf16 v[12:15], v[80:83], v[196:199], v[12:15]
	v_mfma_f32_16x16x32_bf16 v[44:47], v[84:87], v[196:199], v[44:47]
	v_mfma_f32_16x16x32_bf16 v[208:211], v[88:91], v[196:199], v[208:211]
	v_mfma_f32_16x16x32_bf16 v[108:111], v[92:95], v[196:199], v[108:111]
	ds_read_b128 v[196:199], v212 offset:51200
	s_add_u32 m0, s1, 16384
	s_nop 0
	global_load_lds_dwordx4 v151, s[86:87]
	s_waitcnt lgkmcnt(5)
	v_mfma_f32_16x16x32_bf16 v[16:19], v[80:83], v[160:163], v[16:19]
	v_mfma_f32_16x16x32_bf16 v[48:51], v[84:87], v[160:163], v[48:51]
	v_mfma_f32_16x16x32_bf16 v[232:235], v[88:91], v[160:163], v[232:235]
	v_mfma_f32_16x16x32_bf16 v[112:115], v[92:95], v[160:163], v[112:115]
	ds_read_b128 v[160:163], v212 offset:53248
	s_add_u32 m0, s1, 20480
	s_nop 0
	global_load_lds_dwordx4 v156, s[86:87]
	s_waitcnt lgkmcnt(5)
	v_mfma_f32_16x16x32_bf16 v[20:23], v[80:83], v[176:179], v[20:23]
	v_mfma_f32_16x16x32_bf16 v[52:55], v[84:87], v[176:179], v[52:55]
	v_mfma_f32_16x16x32_bf16 v[236:239], v[88:91], v[176:179], v[236:239]
	v_mfma_f32_16x16x32_bf16 v[116:119], v[92:95], v[176:179], v[116:119]
	ds_read_b128 v[176:179], v212 offset:55296
	s_add_u32 m0, s1, 24576
	s_nop 0
	global_load_lds_dwordx4 v158, s[86:87]
	s_waitcnt lgkmcnt(5)
	v_mfma_f32_16x16x32_bf16 v[24:27], v[80:83], v[180:183], v[24:27]
	v_mfma_f32_16x16x32_bf16 v[56:59], v[84:87], v[180:183], v[56:59]
	v_mfma_f32_16x16x32_bf16 v[240:243], v[88:91], v[180:183], v[240:243]
	v_mfma_f32_16x16x32_bf16 v[120:123], v[92:95], v[180:183], v[120:123]
	ds_read_b128 v[180:183], v212 offset:57344
	s_add_u32 m0, s1, 28672
	s_nop 0
	global_load_lds_dwordx4 v159, s[86:87]
	s_add_u32 s86, s86, 128
	s_addc_u32 s87, s87, 0
	s_waitcnt lgkmcnt(5)
	v_mfma_f32_16x16x32_bf16 v[28:31], v[80:83], v[188:191], v[28:31]
	v_mfma_f32_16x16x32_bf16 v[60:63], v[84:87], v[188:191], v[60:63]
	v_mfma_f32_16x16x32_bf16 v[248:251], v[88:91], v[188:191], v[248:251]
	v_mfma_f32_16x16x32_bf16 v[124:127], v[92:95], v[188:191], v[124:127]
	s_waitcnt vmcnt(8)
	ds_read_b128 v[188:191], v212 offset:59392
	global_load_dwordx4 v[80:83], v142, s[84:85] offset:0
	s_waitcnt lgkmcnt(5)
	v_mfma_f32_16x16x32_bf16 v[0:3], v[96:99], v[192:195], v[0:3]
	v_mfma_f32_16x16x32_bf16 v[32:35], v[164:167], v[192:195], v[32:35]
	v_mfma_f32_16x16x32_bf16 v[144:147], v[168:171], v[192:195], v[144:147]
	v_mfma_f32_16x16x32_bf16 v[252:255], v[172:175], v[192:195], v[252:255]
	ds_read_b128 v[192:195], v212 offset:61440
	global_load_dwordx4 v[84:87], v150, s[84:85] offset:0
	s_waitcnt lgkmcnt(5)
	v_mfma_f32_16x16x32_bf16 v[4:7], v[96:99], v[196:199], v[4:7]
	v_mfma_f32_16x16x32_bf16 v[36:39], v[164:167], v[196:199], v[36:39]
	v_mfma_f32_16x16x32_bf16 v[184:187], v[168:171], v[196:199], v[184:187]
	v_mfma_f32_16x16x32_bf16 v[100:103], v[172:175], v[196:199], v[100:103]
	ds_read_b128 v[196:199], v212 offset:63488
	global_load_dwordx4 v[88:91], v142, s[92:93] offset:0
	s_waitcnt lgkmcnt(5)
	v_mfma_f32_16x16x32_bf16 v[8:11], v[96:99], v[160:163], v[8:11]
	v_mfma_f32_16x16x32_bf16 v[40:43], v[164:167], v[160:163], v[40:43]
	v_mfma_f32_16x16x32_bf16 v[204:207], v[168:171], v[160:163], v[204:207]
	v_mfma_f32_16x16x32_bf16 v[104:107], v[172:175], v[160:163], v[104:107]
	ds_read_b128 v[160:163], v213 offset:49152
	global_load_dwordx4 v[92:95], v150, s[92:93] offset:0
	s_waitcnt lgkmcnt(5)
	v_mfma_f32_16x16x32_bf16 v[12:15], v[96:99], v[176:179], v[12:15]
	v_mfma_f32_16x16x32_bf16 v[44:47], v[164:167], v[176:179], v[44:47]
	v_mfma_f32_16x16x32_bf16 v[208:211], v[168:171], v[176:179], v[208:211]
	v_mfma_f32_16x16x32_bf16 v[108:111], v[172:175], v[176:179], v[108:111]
	ds_read_b128 v[176:179], v213 offset:51200
	s_waitcnt lgkmcnt(5)
	v_mfma_f32_16x16x32_bf16 v[16:19], v[96:99], v[180:183], v[16:19]
	v_mfma_f32_16x16x32_bf16 v[48:51], v[164:167], v[180:183], v[48:51]
	v_mfma_f32_16x16x32_bf16 v[232:235], v[168:171], v[180:183], v[232:235]
	v_mfma_f32_16x16x32_bf16 v[112:115], v[172:175], v[180:183], v[112:115]
	ds_read_b128 v[180:183], v213 offset:53248
	s_waitcnt lgkmcnt(5)
	v_mfma_f32_16x16x32_bf16 v[20:23], v[96:99], v[188:191], v[20:23]
	v_mfma_f32_16x16x32_bf16 v[52:55], v[164:167], v[188:191], v[52:55]
	v_mfma_f32_16x16x32_bf16 v[236:239], v[168:171], v[188:191], v[236:239]
	v_mfma_f32_16x16x32_bf16 v[116:119], v[172:175], v[188:191], v[116:119]
	ds_read_b128 v[188:191], v213 offset:55296
	s_waitcnt lgkmcnt(5)
	v_mfma_f32_16x16x32_bf16 v[24:27], v[96:99], v[192:195], v[24:27]
	v_mfma_f32_16x16x32_bf16 v[56:59], v[164:167], v[192:195], v[56:59]
	v_mfma_f32_16x16x32_bf16 v[240:243], v[168:171], v[192:195], v[240:243]
	v_mfma_f32_16x16x32_bf16 v[120:123], v[172:175], v[192:195], v[120:123]
	ds_read_b128 v[192:195], v213 offset:57344
	s_waitcnt lgkmcnt(5)
	v_mfma_f32_16x16x32_bf16 v[28:31], v[96:99], v[196:199], v[28:31]
	v_mfma_f32_16x16x32_bf16 v[60:63], v[164:167], v[196:199], v[60:63]
	v_mfma_f32_16x16x32_bf16 v[248:251], v[168:171], v[196:199], v[248:251]
	v_mfma_f32_16x16x32_bf16 v[124:127], v[172:175], v[196:199], v[124:127]
	s_waitcnt vmcnt(16)
	s_barrier
	s_waitcnt vmcnt(8)
	ds_read_b128 v[196:199], v213 offset:59392
	global_load_dwordx4 v[96:99], v142, s[84:85] offset:1024
	s_waitcnt lgkmcnt(5)
	v_mfma_f32_16x16x32_bf16 v[0:3], v[64:67], v[160:163], v[0:3]
	v_mfma_f32_16x16x32_bf16 v[32:35], v[68:71], v[160:163], v[32:35]
	v_mfma_f32_16x16x32_bf16 v[144:147], v[72:75], v[160:163], v[144:147]
	v_mfma_f32_16x16x32_bf16 v[252:255], v[76:79], v[160:163], v[252:255]
	ds_read_b128 v[160:163], v213 offset:61440
	global_load_dwordx4 v[164:167], v150, s[84:85] offset:1024
	s_waitcnt lgkmcnt(5)
	v_mfma_f32_16x16x32_bf16 v[4:7], v[64:67], v[176:179], v[4:7]
	v_mfma_f32_16x16x32_bf16 v[36:39], v[68:71], v[176:179], v[36:39]
	v_mfma_f32_16x16x32_bf16 v[184:187], v[72:75], v[176:179], v[184:187]
	v_mfma_f32_16x16x32_bf16 v[100:103], v[76:79], v[176:179], v[100:103]
	ds_read_b128 v[176:179], v213 offset:63488
	global_load_dwordx4 v[168:171], v142, s[92:93] offset:1024
	s_waitcnt lgkmcnt(5)
	v_mfma_f32_16x16x32_bf16 v[8:11], v[64:67], v[180:183], v[8:11]
	v_mfma_f32_16x16x32_bf16 v[40:43], v[68:71], v[180:183], v[40:43]
	v_mfma_f32_16x16x32_bf16 v[204:207], v[72:75], v[180:183], v[204:207]
	v_mfma_f32_16x16x32_bf16 v[104:107], v[76:79], v[180:183], v[104:107]
	ds_read_b128 v[180:183], v212 offset:0
	global_load_dwordx4 v[172:175], v150, s[92:93] offset:1024
	s_add_u32 s84, s84, 0x800
	s_addc_u32 s85, s85, 0
	s_add_u32 s92, s92, 0x800
	s_addc_u32 s93, s93, 0
	s_waitcnt lgkmcnt(5)
	v_mfma_f32_16x16x32_bf16 v[12:15], v[64:67], v[188:191], v[12:15]
	v_mfma_f32_16x16x32_bf16 v[44:47], v[68:71], v[188:191], v[44:47]
	v_mfma_f32_16x16x32_bf16 v[208:211], v[72:75], v[188:191], v[208:211]
	v_mfma_f32_16x16x32_bf16 v[108:111], v[76:79], v[188:191], v[108:111]
	ds_read_b128 v[188:191], v212 offset:2048
	s_add_u32 m0, s1, 32768
	s_nop 0
	global_load_lds_dwordx4 v151, s[86:87]
	s_waitcnt lgkmcnt(5)
	v_mfma_f32_16x16x32_bf16 v[16:19], v[64:67], v[192:195], v[16:19]
	v_mfma_f32_16x16x32_bf16 v[48:51], v[68:71], v[192:195], v[48:51]
	v_mfma_f32_16x16x32_bf16 v[232:235], v[72:75], v[192:195], v[232:235]
	v_mfma_f32_16x16x32_bf16 v[112:115], v[76:79], v[192:195], v[112:115]
	ds_read_b128 v[192:195], v212 offset:4096
	s_add_u32 m0, s1, 36864
	s_nop 0
	global_load_lds_dwordx4 v156, s[86:87]
	s_waitcnt lgkmcnt(5)
	v_mfma_f32_16x16x32_bf16 v[20:23], v[64:67], v[196:199], v[20:23]
	v_mfma_f32_16x16x32_bf16 v[52:55], v[68:71], v[196:199], v[52:55]
	v_mfma_f32_16x16x32_bf16 v[236:239], v[72:75], v[196:199], v[236:239]
	v_mfma_f32_16x16x32_bf16 v[116:119], v[76:79], v[196:199], v[116:119]
	ds_read_b128 v[196:199], v212 offset:6144
	s_add_u32 m0, s1, 40960
	s_nop 0
	global_load_lds_dwordx4 v158, s[86:87]
	s_waitcnt lgkmcnt(5)
	v_mfma_f32_16x16x32_bf16 v[24:27], v[64:67], v[160:163], v[24:27]
	v_mfma_f32_16x16x32_bf16 v[56:59], v[68:71], v[160:163], v[56:59]
	v_mfma_f32_16x16x32_bf16 v[240:243], v[72:75], v[160:163], v[240:243]
	v_mfma_f32_16x16x32_bf16 v[120:123], v[76:79], v[160:163], v[120:123]
	ds_read_b128 v[160:163], v212 offset:8192
	s_add_u32 m0, s1, 45056
	s_nop 0
	global_load_lds_dwordx4 v159, s[86:87]
	s_add_u32 s86, s86, 128
	s_addc_u32 s87, s87, 0
	s_waitcnt lgkmcnt(5)
	v_mfma_f32_16x16x32_bf16 v[28:31], v[64:67], v[176:179], v[28:31]
	v_mfma_f32_16x16x32_bf16 v[60:63], v[68:71], v[176:179], v[60:63]
	v_mfma_f32_16x16x32_bf16 v[248:251], v[72:75], v[176:179], v[248:251]
	v_mfma_f32_16x16x32_bf16 v[124:127], v[76:79], v[176:179], v[124:127]
	s_waitcnt vmcnt(8)
	ds_read_b128 v[176:179], v212 offset:10240
	global_load_dwordx4 v[64:67], v142, s[84:85] offset:0
	s_waitcnt lgkmcnt(5)
	v_mfma_f32_16x16x32_bf16 v[0:3], v[80:83], v[180:183], v[0:3]
	v_mfma_f32_16x16x32_bf16 v[32:35], v[84:87], v[180:183], v[32:35]
	v_mfma_f32_16x16x32_bf16 v[144:147], v[88:91], v[180:183], v[144:147]
	v_mfma_f32_16x16x32_bf16 v[252:255], v[92:95], v[180:183], v[252:255]
	ds_read_b128 v[180:183], v212 offset:12288
	global_load_dwordx4 v[68:71], v150, s[84:85] offset:0
	s_waitcnt lgkmcnt(5)
	v_mfma_f32_16x16x32_bf16 v[4:7], v[80:83], v[188:191], v[4:7]
	v_mfma_f32_16x16x32_bf16 v[36:39], v[84:87], v[188:191], v[36:39]
	v_mfma_f32_16x16x32_bf16 v[184:187], v[88:91], v[188:191], v[184:187]
	v_mfma_f32_16x16x32_bf16 v[100:103], v[92:95], v[188:191], v[100:103]
	ds_read_b128 v[188:191], v212 offset:14336
	global_load_dwordx4 v[72:75], v142, s[92:93] offset:0
	s_waitcnt lgkmcnt(5)
	v_mfma_f32_16x16x32_bf16 v[8:11], v[80:83], v[192:195], v[8:11]
	v_mfma_f32_16x16x32_bf16 v[40:43], v[84:87], v[192:195], v[40:43]
	v_mfma_f32_16x16x32_bf16 v[204:207], v[88:91], v[192:195], v[204:207]
	v_mfma_f32_16x16x32_bf16 v[104:107], v[92:95], v[192:195], v[104:107]
	ds_read_b128 v[192:195], v213 offset:0
	global_load_dwordx4 v[76:79], v150, s[92:93] offset:0
	s_waitcnt lgkmcnt(5)
	v_mfma_f32_16x16x32_bf16 v[12:15], v[80:83], v[196:199], v[12:15]
	v_mfma_f32_16x16x32_bf16 v[44:47], v[84:87], v[196:199], v[44:47]
	v_mfma_f32_16x16x32_bf16 v[208:211], v[88:91], v[196:199], v[208:211]
	v_mfma_f32_16x16x32_bf16 v[108:111], v[92:95], v[196:199], v[108:111]
	ds_read_b128 v[196:199], v213 offset:2048
	s_waitcnt lgkmcnt(5)
	v_mfma_f32_16x16x32_bf16 v[16:19], v[80:83], v[160:163], v[16:19]
	v_mfma_f32_16x16x32_bf16 v[48:51], v[84:87], v[160:163], v[48:51]
	v_mfma_f32_16x16x32_bf16 v[232:235], v[88:91], v[160:163], v[232:235]
	v_mfma_f32_16x16x32_bf16 v[112:115], v[92:95], v[160:163], v[112:115]
	ds_read_b128 v[160:163], v213 offset:4096
	s_waitcnt lgkmcnt(5)
	v_mfma_f32_16x16x32_bf16 v[20:23], v[80:83], v[176:179], v[20:23]
	v_mfma_f32_16x16x32_bf16 v[52:55], v[84:87], v[176:179], v[52:55]
	v_mfma_f32_16x16x32_bf16 v[236:239], v[88:91], v[176:179], v[236:239]
	v_mfma_f32_16x16x32_bf16 v[116:119], v[92:95], v[176:179], v[116:119]
	ds_read_b128 v[176:179], v213 offset:6144
	s_waitcnt lgkmcnt(5)
	v_mfma_f32_16x16x32_bf16 v[24:27], v[80:83], v[180:183], v[24:27]
	v_mfma_f32_16x16x32_bf16 v[56:59], v[84:87], v[180:183], v[56:59]
	v_mfma_f32_16x16x32_bf16 v[240:243], v[88:91], v[180:183], v[240:243]
	v_mfma_f32_16x16x32_bf16 v[120:123], v[92:95], v[180:183], v[120:123]
	ds_read_b128 v[180:183], v213 offset:8192
	s_waitcnt lgkmcnt(5)
	v_mfma_f32_16x16x32_bf16 v[28:31], v[80:83], v[188:191], v[28:31]
	v_mfma_f32_16x16x32_bf16 v[60:63], v[84:87], v[188:191], v[60:63]
	v_mfma_f32_16x16x32_bf16 v[248:251], v[88:91], v[188:191], v[248:251]
	v_mfma_f32_16x16x32_bf16 v[124:127], v[92:95], v[188:191], v[124:127]
	s_waitcnt vmcnt(16)
	s_barrier
	s_waitcnt vmcnt(8)
	ds_read_b128 v[188:191], v213 offset:10240
	global_load_dwordx4 v[80:83], v142, s[84:85] offset:1024
	s_waitcnt lgkmcnt(5)
	v_mfma_f32_16x16x32_bf16 v[0:3], v[96:99], v[192:195], v[0:3]
	v_mfma_f32_16x16x32_bf16 v[32:35], v[164:167], v[192:195], v[32:35]
	v_mfma_f32_16x16x32_bf16 v[144:147], v[168:171], v[192:195], v[144:147]
	v_mfma_f32_16x16x32_bf16 v[252:255], v[172:175], v[192:195], v[252:255]
	ds_read_b128 v[192:195], v213 offset:12288
	global_load_dwordx4 v[84:87], v150, s[84:85] offset:1024
	s_waitcnt lgkmcnt(5)
	v_mfma_f32_16x16x32_bf16 v[4:7], v[96:99], v[196:199], v[4:7]
	v_mfma_f32_16x16x32_bf16 v[36:39], v[164:167], v[196:199], v[36:39]
	v_mfma_f32_16x16x32_bf16 v[184:187], v[168:171], v[196:199], v[184:187]
	v_mfma_f32_16x16x32_bf16 v[100:103], v[172:175], v[196:199], v[100:103]
	ds_read_b128 v[196:199], v213 offset:14336
	global_load_dwordx4 v[88:91], v142, s[92:93] offset:1024
	s_waitcnt lgkmcnt(5)
	v_mfma_f32_16x16x32_bf16 v[8:11], v[96:99], v[160:163], v[8:11]
	v_mfma_f32_16x16x32_bf16 v[40:43], v[164:167], v[160:163], v[40:43]
	v_mfma_f32_16x16x32_bf16 v[204:207], v[168:171], v[160:163], v[204:207]
	v_mfma_f32_16x16x32_bf16 v[104:107], v[172:175], v[160:163], v[104:107]
	ds_read_b128 v[160:163], v212 offset:16384
	global_load_dwordx4 v[92:95], v150, s[92:93] offset:1024
	s_add_u32 s84, s84, 0x800
	s_addc_u32 s85, s85, 0
	s_add_u32 s92, s92, 0x800
	s_addc_u32 s93, s93, 0
	s_waitcnt lgkmcnt(5)
	v_mfma_f32_16x16x32_bf16 v[12:15], v[96:99], v[176:179], v[12:15]
	v_mfma_f32_16x16x32_bf16 v[44:47], v[164:167], v[176:179], v[44:47]
	v_mfma_f32_16x16x32_bf16 v[208:211], v[168:171], v[176:179], v[208:211]
	v_mfma_f32_16x16x32_bf16 v[108:111], v[172:175], v[176:179], v[108:111]
	ds_read_b128 v[176:179], v212 offset:18432
	s_add_u32 m0, s1, 49152
	s_nop 0
	global_load_lds_dwordx4 v151, s[86:87]
	s_waitcnt lgkmcnt(5)
	v_mfma_f32_16x16x32_bf16 v[16:19], v[96:99], v[180:183], v[16:19]
	v_mfma_f32_16x16x32_bf16 v[48:51], v[164:167], v[180:183], v[48:51]
	v_mfma_f32_16x16x32_bf16 v[232:235], v[168:171], v[180:183], v[232:235]
	v_mfma_f32_16x16x32_bf16 v[112:115], v[172:175], v[180:183], v[112:115]
	ds_read_b128 v[180:183], v212 offset:20480
	s_add_u32 m0, s1, 53248
	s_nop 0
	global_load_lds_dwordx4 v156, s[86:87]
	s_waitcnt lgkmcnt(5)
	v_mfma_f32_16x16x32_bf16 v[20:23], v[96:99], v[188:191], v[20:23]
	v_mfma_f32_16x16x32_bf16 v[52:55], v[164:167], v[188:191], v[52:55]
	v_mfma_f32_16x16x32_bf16 v[236:239], v[168:171], v[188:191], v[236:239]
	v_mfma_f32_16x16x32_bf16 v[116:119], v[172:175], v[188:191], v[116:119]
	ds_read_b128 v[188:191], v212 offset:22528
	s_add_u32 m0, s1, 57344
	s_nop 0
	global_load_lds_dwordx4 v158, s[86:87]
	s_waitcnt lgkmcnt(5)
	v_mfma_f32_16x16x32_bf16 v[24:27], v[96:99], v[192:195], v[24:27]
	v_mfma_f32_16x16x32_bf16 v[56:59], v[164:167], v[192:195], v[56:59]
	v_mfma_f32_16x16x32_bf16 v[240:243], v[168:171], v[192:195], v[240:243]
	v_mfma_f32_16x16x32_bf16 v[120:123], v[172:175], v[192:195], v[120:123]
	ds_read_b128 v[192:195], v212 offset:24576
	s_add_u32 m0, s1, 61440
	s_nop 0
	global_load_lds_dwordx4 v159, s[86:87]
	s_add_u32 s86, s86, 128
	s_addc_u32 s87, s87, 0
	s_waitcnt lgkmcnt(5)
	v_mfma_f32_16x16x32_bf16 v[28:31], v[96:99], v[196:199], v[28:31]
	v_mfma_f32_16x16x32_bf16 v[60:63], v[164:167], v[196:199], v[60:63]
	v_mfma_f32_16x16x32_bf16 v[248:251], v[168:171], v[196:199], v[248:251]
	v_mfma_f32_16x16x32_bf16 v[124:127], v[172:175], v[196:199], v[124:127]
	s_waitcnt vmcnt(8)
	ds_read_b128 v[196:199], v212 offset:26624
	global_load_dwordx4 v[96:99], v142, s[84:85] offset:0
	s_waitcnt lgkmcnt(5)
	v_mfma_f32_16x16x32_bf16 v[0:3], v[64:67], v[160:163], v[0:3]
	v_mfma_f32_16x16x32_bf16 v[32:35], v[68:71], v[160:163], v[32:35]
	v_mfma_f32_16x16x32_bf16 v[144:147], v[72:75], v[160:163], v[144:147]
	v_mfma_f32_16x16x32_bf16 v[252:255], v[76:79], v[160:163], v[252:255]
	ds_read_b128 v[160:163], v212 offset:28672
	global_load_dwordx4 v[164:167], v150, s[84:85] offset:0
	s_waitcnt lgkmcnt(5)
	v_mfma_f32_16x16x32_bf16 v[4:7], v[64:67], v[176:179], v[4:7]
	v_mfma_f32_16x16x32_bf16 v[36:39], v[68:71], v[176:179], v[36:39]
	v_mfma_f32_16x16x32_bf16 v[184:187], v[72:75], v[176:179], v[184:187]
	v_mfma_f32_16x16x32_bf16 v[100:103], v[76:79], v[176:179], v[100:103]
	ds_read_b128 v[176:179], v212 offset:30720
	global_load_dwordx4 v[168:171], v142, s[92:93] offset:0
	s_waitcnt lgkmcnt(5)
	v_mfma_f32_16x16x32_bf16 v[8:11], v[64:67], v[180:183], v[8:11]
	v_mfma_f32_16x16x32_bf16 v[40:43], v[68:71], v[180:183], v[40:43]
	v_mfma_f32_16x16x32_bf16 v[204:207], v[72:75], v[180:183], v[204:207]
	v_mfma_f32_16x16x32_bf16 v[104:107], v[76:79], v[180:183], v[104:107]
	ds_read_b128 v[180:183], v213 offset:16384
	global_load_dwordx4 v[172:175], v150, s[92:93] offset:0
	s_waitcnt lgkmcnt(5)
	v_mfma_f32_16x16x32_bf16 v[12:15], v[64:67], v[188:191], v[12:15]
	v_mfma_f32_16x16x32_bf16 v[44:47], v[68:71], v[188:191], v[44:47]
	v_mfma_f32_16x16x32_bf16 v[208:211], v[72:75], v[188:191], v[208:211]
	v_mfma_f32_16x16x32_bf16 v[108:111], v[76:79], v[188:191], v[108:111]
	ds_read_b128 v[188:191], v213 offset:18432
	s_waitcnt lgkmcnt(5)
	v_mfma_f32_16x16x32_bf16 v[16:19], v[64:67], v[192:195], v[16:19]
	v_mfma_f32_16x16x32_bf16 v[48:51], v[68:71], v[192:195], v[48:51]
	v_mfma_f32_16x16x32_bf16 v[232:235], v[72:75], v[192:195], v[232:235]
	v_mfma_f32_16x16x32_bf16 v[112:115], v[76:79], v[192:195], v[112:115]
	ds_read_b128 v[192:195], v213 offset:20480
	s_waitcnt lgkmcnt(5)
	v_mfma_f32_16x16x32_bf16 v[20:23], v[64:67], v[196:199], v[20:23]
	v_mfma_f32_16x16x32_bf16 v[52:55], v[68:71], v[196:199], v[52:55]
	v_mfma_f32_16x16x32_bf16 v[236:239], v[72:75], v[196:199], v[236:239]
	v_mfma_f32_16x16x32_bf16 v[116:119], v[76:79], v[196:199], v[116:119]
	ds_read_b128 v[196:199], v213 offset:22528
	s_waitcnt lgkmcnt(5)
	v_mfma_f32_16x16x32_bf16 v[24:27], v[64:67], v[160:163], v[24:27]
	v_mfma_f32_16x16x32_bf16 v[56:59], v[68:71], v[160:163], v[56:59]
	v_mfma_f32_16x16x32_bf16 v[240:243], v[72:75], v[160:163], v[240:243]
	v_mfma_f32_16x16x32_bf16 v[120:123], v[76:79], v[160:163], v[120:123]
	ds_read_b128 v[160:163], v213 offset:24576
	s_waitcnt lgkmcnt(5)
	v_mfma_f32_16x16x32_bf16 v[28:31], v[64:67], v[176:179], v[28:31]
	v_mfma_f32_16x16x32_bf16 v[60:63], v[68:71], v[176:179], v[60:63]
	v_mfma_f32_16x16x32_bf16 v[248:251], v[72:75], v[176:179], v[248:251]
	v_mfma_f32_16x16x32_bf16 v[124:127], v[76:79], v[176:179], v[124:127]
	s_waitcnt vmcnt(16)
	s_barrier
	s_waitcnt vmcnt(8)
	ds_read_b128 v[176:179], v213 offset:26624
	global_load_dwordx4 v[64:67], v142, s[84:85] offset:1024
	s_waitcnt lgkmcnt(5)
	v_mfma_f32_16x16x32_bf16 v[0:3], v[80:83], v[180:183], v[0:3]
	v_mfma_f32_16x16x32_bf16 v[32:35], v[84:87], v[180:183], v[32:35]
	v_mfma_f32_16x16x32_bf16 v[144:147], v[88:91], v[180:183], v[144:147]
	v_mfma_f32_16x16x32_bf16 v[252:255], v[92:95], v[180:183], v[252:255]
	ds_read_b128 v[180:183], v213 offset:28672
	global_load_dwordx4 v[68:71], v150, s[84:85] offset:1024
	s_waitcnt lgkmcnt(5)
	v_mfma_f32_16x16x32_bf16 v[4:7], v[80:83], v[188:191], v[4:7]
	v_mfma_f32_16x16x32_bf16 v[36:39], v[84:87], v[188:191], v[36:39]
	v_mfma_f32_16x16x32_bf16 v[184:187], v[88:91], v[188:191], v[184:187]
	v_mfma_f32_16x16x32_bf16 v[100:103], v[92:95], v[188:191], v[100:103]
	ds_read_b128 v[188:191], v213 offset:30720
	global_load_dwordx4 v[72:75], v142, s[92:93] offset:1024
	s_waitcnt lgkmcnt(5)
	v_mfma_f32_16x16x32_bf16 v[8:11], v[80:83], v[192:195], v[8:11]
	v_mfma_f32_16x16x32_bf16 v[40:43], v[84:87], v[192:195], v[40:43]
	v_mfma_f32_16x16x32_bf16 v[204:207], v[88:91], v[192:195], v[204:207]
	v_mfma_f32_16x16x32_bf16 v[104:107], v[92:95], v[192:195], v[104:107]
	ds_read_b128 v[192:195], v212 offset:32768
	global_load_dwordx4 v[76:79], v150, s[92:93] offset:1024
	s_add_u32 s84, s84, 0x800
	s_addc_u32 s85, s85, 0
	s_add_u32 s92, s92, 0x800
	s_addc_u32 s93, s93, 0
	s_waitcnt lgkmcnt(5)
	v_mfma_f32_16x16x32_bf16 v[12:15], v[80:83], v[196:199], v[12:15]
	v_mfma_f32_16x16x32_bf16 v[44:47], v[84:87], v[196:199], v[44:47]
	v_mfma_f32_16x16x32_bf16 v[208:211], v[88:91], v[196:199], v[208:211]
	v_mfma_f32_16x16x32_bf16 v[108:111], v[92:95], v[196:199], v[108:111]
	ds_read_b128 v[196:199], v212 offset:34816
	s_add_u32 m0, s1, 0
	s_nop 0
	global_load_lds_dwordx4 v151, s[86:87]
	s_waitcnt lgkmcnt(5)
	v_mfma_f32_16x16x32_bf16 v[16:19], v[80:83], v[160:163], v[16:19]
	v_mfma_f32_16x16x32_bf16 v[48:51], v[84:87], v[160:163], v[48:51]
	v_mfma_f32_16x16x32_bf16 v[232:235], v[88:91], v[160:163], v[232:235]
	v_mfma_f32_16x16x32_bf16 v[112:115], v[92:95], v[160:163], v[112:115]
	ds_read_b128 v[160:163], v212 offset:36864
	s_add_u32 m0, s1, 4096
	s_nop 0
	global_load_lds_dwordx4 v156, s[86:87]
	s_waitcnt lgkmcnt(5)
	v_mfma_f32_16x16x32_bf16 v[20:23], v[80:83], v[176:179], v[20:23]
	v_mfma_f32_16x16x32_bf16 v[52:55], v[84:87], v[176:179], v[52:55]
	v_mfma_f32_16x16x32_bf16 v[236:239], v[88:91], v[176:179], v[236:239]
	v_mfma_f32_16x16x32_bf16 v[116:119], v[92:95], v[176:179], v[116:119]
	ds_read_b128 v[176:179], v212 offset:38912
	s_add_u32 m0, s1, 8192
	s_nop 0
	global_load_lds_dwordx4 v158, s[86:87]
	s_waitcnt lgkmcnt(5)
	v_mfma_f32_16x16x32_bf16 v[24:27], v[80:83], v[180:183], v[24:27]
	v_mfma_f32_16x16x32_bf16 v[56:59], v[84:87], v[180:183], v[56:59]
	v_mfma_f32_16x16x32_bf16 v[240:243], v[88:91], v[180:183], v[240:243]
	v_mfma_f32_16x16x32_bf16 v[120:123], v[92:95], v[180:183], v[120:123]
	ds_read_b128 v[180:183], v212 offset:40960
	s_add_u32 m0, s1, 12288
	s_nop 0
	global_load_lds_dwordx4 v159, s[86:87]
	s_add_u32 s86, s86, 128
	s_addc_u32 s87, s87, 0
	s_waitcnt lgkmcnt(5)
	v_mfma_f32_16x16x32_bf16 v[28:31], v[80:83], v[188:191], v[28:31]
	v_mfma_f32_16x16x32_bf16 v[60:63], v[84:87], v[188:191], v[60:63]
	v_mfma_f32_16x16x32_bf16 v[248:251], v[88:91], v[188:191], v[248:251]
	v_mfma_f32_16x16x32_bf16 v[124:127], v[92:95], v[188:191], v[124:127]
	s_waitcnt vmcnt(8)
	ds_read_b128 v[188:191], v212 offset:43008
	global_load_dwordx4 v[80:83], v142, s[84:85] offset:0
	s_waitcnt lgkmcnt(5)
	v_mfma_f32_16x16x32_bf16 v[0:3], v[96:99], v[192:195], v[0:3]
	v_mfma_f32_16x16x32_bf16 v[32:35], v[164:167], v[192:195], v[32:35]
	v_mfma_f32_16x16x32_bf16 v[144:147], v[168:171], v[192:195], v[144:147]
	v_mfma_f32_16x16x32_bf16 v[252:255], v[172:175], v[192:195], v[252:255]
	ds_read_b128 v[192:195], v212 offset:45056
	global_load_dwordx4 v[84:87], v150, s[84:85] offset:0
	s_waitcnt lgkmcnt(5)
	v_mfma_f32_16x16x32_bf16 v[4:7], v[96:99], v[196:199], v[4:7]
	v_mfma_f32_16x16x32_bf16 v[36:39], v[164:167], v[196:199], v[36:39]
	v_mfma_f32_16x16x32_bf16 v[184:187], v[168:171], v[196:199], v[184:187]
	v_mfma_f32_16x16x32_bf16 v[100:103], v[172:175], v[196:199], v[100:103]
	ds_read_b128 v[196:199], v212 offset:47104
	global_load_dwordx4 v[88:91], v142, s[92:93] offset:0
	s_waitcnt lgkmcnt(5)
	v_mfma_f32_16x16x32_bf16 v[8:11], v[96:99], v[160:163], v[8:11]
	v_mfma_f32_16x16x32_bf16 v[40:43], v[164:167], v[160:163], v[40:43]
	v_mfma_f32_16x16x32_bf16 v[204:207], v[168:171], v[160:163], v[204:207]
	v_mfma_f32_16x16x32_bf16 v[104:107], v[172:175], v[160:163], v[104:107]
	ds_read_b128 v[160:163], v213 offset:32768
	global_load_dwordx4 v[92:95], v150, s[92:93] offset:0
	s_waitcnt lgkmcnt(5)
	v_mfma_f32_16x16x32_bf16 v[12:15], v[96:99], v[176:179], v[12:15]
	v_mfma_f32_16x16x32_bf16 v[44:47], v[164:167], v[176:179], v[44:47]
	v_mfma_f32_16x16x32_bf16 v[208:211], v[168:171], v[176:179], v[208:211]
	v_mfma_f32_16x16x32_bf16 v[108:111], v[172:175], v[176:179], v[108:111]
	ds_read_b128 v[176:179], v213 offset:34816
	s_waitcnt lgkmcnt(5)
	v_mfma_f32_16x16x32_bf16 v[16:19], v[96:99], v[180:183], v[16:19]
	v_mfma_f32_16x16x32_bf16 v[48:51], v[164:167], v[180:183], v[48:51]
	v_mfma_f32_16x16x32_bf16 v[232:235], v[168:171], v[180:183], v[232:235]
	v_mfma_f32_16x16x32_bf16 v[112:115], v[172:175], v[180:183], v[112:115]
	ds_read_b128 v[180:183], v213 offset:36864
	s_waitcnt lgkmcnt(5)
	v_mfma_f32_16x16x32_bf16 v[20:23], v[96:99], v[188:191], v[20:23]
	v_mfma_f32_16x16x32_bf16 v[52:55], v[164:167], v[188:191], v[52:55]
	v_mfma_f32_16x16x32_bf16 v[236:239], v[168:171], v[188:191], v[236:239]
	v_mfma_f32_16x16x32_bf16 v[116:119], v[172:175], v[188:191], v[116:119]
	ds_read_b128 v[188:191], v213 offset:38912
	s_waitcnt lgkmcnt(5)
	v_mfma_f32_16x16x32_bf16 v[24:27], v[96:99], v[192:195], v[24:27]
	v_mfma_f32_16x16x32_bf16 v[56:59], v[164:167], v[192:195], v[56:59]
	v_mfma_f32_16x16x32_bf16 v[240:243], v[168:171], v[192:195], v[240:243]
	v_mfma_f32_16x16x32_bf16 v[120:123], v[172:175], v[192:195], v[120:123]
	ds_read_b128 v[192:195], v213 offset:40960
	s_waitcnt lgkmcnt(5)
	v_mfma_f32_16x16x32_bf16 v[28:31], v[96:99], v[196:199], v[28:31]
	v_mfma_f32_16x16x32_bf16 v[60:63], v[164:167], v[196:199], v[60:63]
	v_mfma_f32_16x16x32_bf16 v[248:251], v[168:171], v[196:199], v[248:251]
	v_mfma_f32_16x16x32_bf16 v[124:127], v[172:175], v[196:199], v[124:127]
	s_waitcnt vmcnt(16)
	s_barrier
	s_waitcnt vmcnt(8)
	ds_read_b128 v[196:199], v213 offset:43008
	global_load_dwordx4 v[96:99], v142, s[84:85] offset:1024
	s_waitcnt lgkmcnt(5)
	v_mfma_f32_16x16x32_bf16 v[0:3], v[64:67], v[160:163], v[0:3]
	v_mfma_f32_16x16x32_bf16 v[32:35], v[68:71], v[160:163], v[32:35]
	v_mfma_f32_16x16x32_bf16 v[144:147], v[72:75], v[160:163], v[144:147]
	v_mfma_f32_16x16x32_bf16 v[252:255], v[76:79], v[160:163], v[252:255]
	ds_read_b128 v[160:163], v213 offset:45056
	global_load_dwordx4 v[164:167], v150, s[84:85] offset:1024
	s_waitcnt lgkmcnt(5)
	v_mfma_f32_16x16x32_bf16 v[4:7], v[64:67], v[176:179], v[4:7]
	v_mfma_f32_16x16x32_bf16 v[36:39], v[68:71], v[176:179], v[36:39]
	v_mfma_f32_16x16x32_bf16 v[184:187], v[72:75], v[176:179], v[184:187]
	v_mfma_f32_16x16x32_bf16 v[100:103], v[76:79], v[176:179], v[100:103]
	ds_read_b128 v[176:179], v213 offset:47104
	global_load_dwordx4 v[168:171], v142, s[92:93] offset:1024
	s_waitcnt lgkmcnt(5)
	v_mfma_f32_16x16x32_bf16 v[8:11], v[64:67], v[180:183], v[8:11]
	v_mfma_f32_16x16x32_bf16 v[40:43], v[68:71], v[180:183], v[40:43]
	v_mfma_f32_16x16x32_bf16 v[204:207], v[72:75], v[180:183], v[204:207]
	v_mfma_f32_16x16x32_bf16 v[104:107], v[76:79], v[180:183], v[104:107]
	ds_read_b128 v[180:183], v212 offset:49152
	global_load_dwordx4 v[172:175], v150, s[92:93] offset:1024
	s_add_u32 s84, s84, 0x800
	s_addc_u32 s85, s85, 0
	s_add_u32 s92, s92, 0x800
	s_addc_u32 s93, s93, 0
	s_waitcnt lgkmcnt(5)
	v_mfma_f32_16x16x32_bf16 v[12:15], v[64:67], v[188:191], v[12:15]
	v_mfma_f32_16x16x32_bf16 v[44:47], v[68:71], v[188:191], v[44:47]
	v_mfma_f32_16x16x32_bf16 v[208:211], v[72:75], v[188:191], v[208:211]
	v_mfma_f32_16x16x32_bf16 v[108:111], v[76:79], v[188:191], v[108:111]
	ds_read_b128 v[188:191], v212 offset:51200
	s_add_u32 m0, s1, 16384
	s_nop 0
	global_load_lds_dwordx4 v151, s[86:87]
	s_waitcnt lgkmcnt(5)
	v_mfma_f32_16x16x32_bf16 v[16:19], v[64:67], v[192:195], v[16:19]
	v_mfma_f32_16x16x32_bf16 v[48:51], v[68:71], v[192:195], v[48:51]
	v_mfma_f32_16x16x32_bf16 v[232:235], v[72:75], v[192:195], v[232:235]
	v_mfma_f32_16x16x32_bf16 v[112:115], v[76:79], v[192:195], v[112:115]
	ds_read_b128 v[192:195], v212 offset:53248
	s_add_u32 m0, s1, 20480
	s_nop 0
	global_load_lds_dwordx4 v156, s[86:87]
	s_waitcnt lgkmcnt(5)
	v_mfma_f32_16x16x32_bf16 v[20:23], v[64:67], v[196:199], v[20:23]
	v_mfma_f32_16x16x32_bf16 v[52:55], v[68:71], v[196:199], v[52:55]
	v_mfma_f32_16x16x32_bf16 v[236:239], v[72:75], v[196:199], v[236:239]
	v_mfma_f32_16x16x32_bf16 v[116:119], v[76:79], v[196:199], v[116:119]
	ds_read_b128 v[196:199], v212 offset:55296
	s_add_u32 m0, s1, 24576
	s_nop 0
	global_load_lds_dwordx4 v158, s[86:87]
	s_waitcnt lgkmcnt(5)
	v_mfma_f32_16x16x32_bf16 v[24:27], v[64:67], v[160:163], v[24:27]
	v_mfma_f32_16x16x32_bf16 v[56:59], v[68:71], v[160:163], v[56:59]
	v_mfma_f32_16x16x32_bf16 v[240:243], v[72:75], v[160:163], v[240:243]
	v_mfma_f32_16x16x32_bf16 v[120:123], v[76:79], v[160:163], v[120:123]
	ds_read_b128 v[160:163], v212 offset:57344
	s_add_u32 m0, s1, 28672
	s_nop 0
	global_load_lds_dwordx4 v159, s[86:87]
	s_add_u32 s86, s86, 128
	s_addc_u32 s87, s87, 0
	s_waitcnt lgkmcnt(5)
	v_mfma_f32_16x16x32_bf16 v[28:31], v[64:67], v[176:179], v[28:31]
	v_mfma_f32_16x16x32_bf16 v[60:63], v[68:71], v[176:179], v[60:63]
	v_mfma_f32_16x16x32_bf16 v[248:251], v[72:75], v[176:179], v[248:251]
	v_mfma_f32_16x16x32_bf16 v[124:127], v[76:79], v[176:179], v[124:127]
	s_waitcnt vmcnt(8)
	ds_read_b128 v[176:179], v212 offset:59392
	global_load_dwordx4 v[64:67], v142, s[84:85] offset:0
	s_waitcnt lgkmcnt(5)
	v_mfma_f32_16x16x32_bf16 v[0:3], v[80:83], v[180:183], v[0:3]
	v_mfma_f32_16x16x32_bf16 v[32:35], v[84:87], v[180:183], v[32:35]
	v_mfma_f32_16x16x32_bf16 v[144:147], v[88:91], v[180:183], v[144:147]
	v_mfma_f32_16x16x32_bf16 v[252:255], v[92:95], v[180:183], v[252:255]
	ds_read_b128 v[180:183], v212 offset:61440
	global_load_dwordx4 v[68:71], v150, s[84:85] offset:0
	s_waitcnt lgkmcnt(5)
	v_mfma_f32_16x16x32_bf16 v[4:7], v[80:83], v[188:191], v[4:7]
	v_mfma_f32_16x16x32_bf16 v[36:39], v[84:87], v[188:191], v[36:39]
	v_mfma_f32_16x16x32_bf16 v[184:187], v[88:91], v[188:191], v[184:187]
	v_mfma_f32_16x16x32_bf16 v[100:103], v[92:95], v[188:191], v[100:103]
	ds_read_b128 v[188:191], v212 offset:63488
	global_load_dwordx4 v[72:75], v142, s[92:93] offset:0
	s_waitcnt lgkmcnt(5)
	v_mfma_f32_16x16x32_bf16 v[8:11], v[80:83], v[192:195], v[8:11]
	v_mfma_f32_16x16x32_bf16 v[40:43], v[84:87], v[192:195], v[40:43]
	v_mfma_f32_16x16x32_bf16 v[204:207], v[88:91], v[192:195], v[204:207]
	v_mfma_f32_16x16x32_bf16 v[104:107], v[92:95], v[192:195], v[104:107]
	ds_read_b128 v[192:195], v213 offset:49152
	global_load_dwordx4 v[76:79], v150, s[92:93] offset:0
	s_waitcnt lgkmcnt(5)
	v_mfma_f32_16x16x32_bf16 v[12:15], v[80:83], v[196:199], v[12:15]
	v_mfma_f32_16x16x32_bf16 v[44:47], v[84:87], v[196:199], v[44:47]
	v_mfma_f32_16x16x32_bf16 v[208:211], v[88:91], v[196:199], v[208:211]
	v_mfma_f32_16x16x32_bf16 v[108:111], v[92:95], v[196:199], v[108:111]
	ds_read_b128 v[196:199], v213 offset:51200
	s_waitcnt lgkmcnt(5)
	v_mfma_f32_16x16x32_bf16 v[16:19], v[80:83], v[160:163], v[16:19]
	v_mfma_f32_16x16x32_bf16 v[48:51], v[84:87], v[160:163], v[48:51]
	v_mfma_f32_16x16x32_bf16 v[232:235], v[88:91], v[160:163], v[232:235]
	v_mfma_f32_16x16x32_bf16 v[112:115], v[92:95], v[160:163], v[112:115]
	ds_read_b128 v[160:163], v213 offset:53248
	s_waitcnt lgkmcnt(5)
	v_mfma_f32_16x16x32_bf16 v[20:23], v[80:83], v[176:179], v[20:23]
	v_mfma_f32_16x16x32_bf16 v[52:55], v[84:87], v[176:179], v[52:55]
	v_mfma_f32_16x16x32_bf16 v[236:239], v[88:91], v[176:179], v[236:239]
	v_mfma_f32_16x16x32_bf16 v[116:119], v[92:95], v[176:179], v[116:119]
	ds_read_b128 v[176:179], v213 offset:55296
	s_waitcnt lgkmcnt(5)
	v_mfma_f32_16x16x32_bf16 v[24:27], v[80:83], v[180:183], v[24:27]
	v_mfma_f32_16x16x32_bf16 v[56:59], v[84:87], v[180:183], v[56:59]
	v_mfma_f32_16x16x32_bf16 v[240:243], v[88:91], v[180:183], v[240:243]
	v_mfma_f32_16x16x32_bf16 v[120:123], v[92:95], v[180:183], v[120:123]
	ds_read_b128 v[180:183], v213 offset:57344
	s_waitcnt lgkmcnt(5)
	v_mfma_f32_16x16x32_bf16 v[28:31], v[80:83], v[188:191], v[28:31]
	v_mfma_f32_16x16x32_bf16 v[60:63], v[84:87], v[188:191], v[60:63]
	v_mfma_f32_16x16x32_bf16 v[248:251], v[88:91], v[188:191], v[248:251]
	v_mfma_f32_16x16x32_bf16 v[124:127], v[92:95], v[188:191], v[124:127]
	s_waitcnt vmcnt(16)
	s_barrier
	s_waitcnt vmcnt(8)
	ds_read_b128 v[188:191], v213 offset:59392
	global_load_dwordx4 v[80:83], v142, s[84:85] offset:1024
	s_waitcnt lgkmcnt(5)
	v_mfma_f32_16x16x32_bf16 v[0:3], v[96:99], v[192:195], v[0:3]
	v_mfma_f32_16x16x32_bf16 v[32:35], v[164:167], v[192:195], v[32:35]
	v_mfma_f32_16x16x32_bf16 v[144:147], v[168:171], v[192:195], v[144:147]
	v_mfma_f32_16x16x32_bf16 v[252:255], v[172:175], v[192:195], v[252:255]
	ds_read_b128 v[192:195], v213 offset:61440
	global_load_dwordx4 v[84:87], v150, s[84:85] offset:1024
	s_waitcnt lgkmcnt(5)
	v_mfma_f32_16x16x32_bf16 v[4:7], v[96:99], v[196:199], v[4:7]
	v_mfma_f32_16x16x32_bf16 v[36:39], v[164:167], v[196:199], v[36:39]
	v_mfma_f32_16x16x32_bf16 v[184:187], v[168:171], v[196:199], v[184:187]
	v_mfma_f32_16x16x32_bf16 v[100:103], v[172:175], v[196:199], v[100:103]
	ds_read_b128 v[196:199], v213 offset:63488
	global_load_dwordx4 v[88:91], v142, s[92:93] offset:1024
	s_waitcnt lgkmcnt(5)
	v_mfma_f32_16x16x32_bf16 v[8:11], v[96:99], v[160:163], v[8:11]
	v_mfma_f32_16x16x32_bf16 v[40:43], v[164:167], v[160:163], v[40:43]
	v_mfma_f32_16x16x32_bf16 v[204:207], v[168:171], v[160:163], v[204:207]
	v_mfma_f32_16x16x32_bf16 v[104:107], v[172:175], v[160:163], v[104:107]
	ds_read_b128 v[160:163], v212 offset:0
	global_load_dwordx4 v[92:95], v150, s[92:93] offset:1024
	s_add_u32 s84, s84, 0x800
	s_addc_u32 s85, s85, 0
	s_add_u32 s92, s92, 0x800
	s_addc_u32 s93, s93, 0
	s_waitcnt lgkmcnt(5)
	v_mfma_f32_16x16x32_bf16 v[12:15], v[96:99], v[176:179], v[12:15]
	v_mfma_f32_16x16x32_bf16 v[44:47], v[164:167], v[176:179], v[44:47]
	v_mfma_f32_16x16x32_bf16 v[208:211], v[168:171], v[176:179], v[208:211]
	v_mfma_f32_16x16x32_bf16 v[108:111], v[172:175], v[176:179], v[108:111]
	ds_read_b128 v[176:179], v212 offset:2048
	s_add_u32 m0, s1, 32768
	s_nop 0
	global_load_lds_dwordx4 v151, s[86:87]
	s_waitcnt lgkmcnt(5)
	v_mfma_f32_16x16x32_bf16 v[16:19], v[96:99], v[180:183], v[16:19]
	v_mfma_f32_16x16x32_bf16 v[48:51], v[164:167], v[180:183], v[48:51]
	v_mfma_f32_16x16x32_bf16 v[232:235], v[168:171], v[180:183], v[232:235]
	v_mfma_f32_16x16x32_bf16 v[112:115], v[172:175], v[180:183], v[112:115]
	ds_read_b128 v[180:183], v212 offset:4096
	s_add_u32 m0, s1, 36864
	s_nop 0
	global_load_lds_dwordx4 v156, s[86:87]
	s_waitcnt lgkmcnt(5)
	v_mfma_f32_16x16x32_bf16 v[20:23], v[96:99], v[188:191], v[20:23]
	v_mfma_f32_16x16x32_bf16 v[52:55], v[164:167], v[188:191], v[52:55]
	v_mfma_f32_16x16x32_bf16 v[236:239], v[168:171], v[188:191], v[236:239]
	v_mfma_f32_16x16x32_bf16 v[116:119], v[172:175], v[188:191], v[116:119]
	ds_read_b128 v[188:191], v212 offset:6144
	s_add_u32 m0, s1, 40960
	s_nop 0
	global_load_lds_dwordx4 v158, s[86:87]
	s_waitcnt lgkmcnt(5)
	v_mfma_f32_16x16x32_bf16 v[24:27], v[96:99], v[192:195], v[24:27]
	v_mfma_f32_16x16x32_bf16 v[56:59], v[164:167], v[192:195], v[56:59]
	v_mfma_f32_16x16x32_bf16 v[240:243], v[168:171], v[192:195], v[240:243]
	v_mfma_f32_16x16x32_bf16 v[120:123], v[172:175], v[192:195], v[120:123]
	ds_read_b128 v[192:195], v212 offset:8192
	s_add_u32 m0, s1, 45056
	s_nop 0
	global_load_lds_dwordx4 v159, s[86:87]
	s_add_u32 s86, s86, 128
	s_addc_u32 s87, s87, 0
	s_waitcnt lgkmcnt(5)
	v_mfma_f32_16x16x32_bf16 v[28:31], v[96:99], v[196:199], v[28:31]
	v_mfma_f32_16x16x32_bf16 v[60:63], v[164:167], v[196:199], v[60:63]
	v_mfma_f32_16x16x32_bf16 v[248:251], v[168:171], v[196:199], v[248:251]
	v_mfma_f32_16x16x32_bf16 v[124:127], v[172:175], v[196:199], v[124:127]
	s_waitcnt vmcnt(8)
	ds_read_b128 v[196:199], v212 offset:10240
	global_load_dwordx4 v[96:99], v142, s[84:85] offset:0
	s_waitcnt lgkmcnt(5)
	v_mfma_f32_16x16x32_bf16 v[0:3], v[64:67], v[160:163], v[0:3]
	v_mfma_f32_16x16x32_bf16 v[32:35], v[68:71], v[160:163], v[32:35]
	v_mfma_f32_16x16x32_bf16 v[144:147], v[72:75], v[160:163], v[144:147]
	v_mfma_f32_16x16x32_bf16 v[252:255], v[76:79], v[160:163], v[252:255]
	ds_read_b128 v[160:163], v212 offset:12288
	global_load_dwordx4 v[164:167], v150, s[84:85] offset:0
	s_waitcnt lgkmcnt(5)
	v_mfma_f32_16x16x32_bf16 v[4:7], v[64:67], v[176:179], v[4:7]
	v_mfma_f32_16x16x32_bf16 v[36:39], v[68:71], v[176:179], v[36:39]
	v_mfma_f32_16x16x32_bf16 v[184:187], v[72:75], v[176:179], v[184:187]
	v_mfma_f32_16x16x32_bf16 v[100:103], v[76:79], v[176:179], v[100:103]
	ds_read_b128 v[176:179], v212 offset:14336
	global_load_dwordx4 v[168:171], v142, s[92:93] offset:0
	s_waitcnt lgkmcnt(5)
	v_mfma_f32_16x16x32_bf16 v[8:11], v[64:67], v[180:183], v[8:11]
	v_mfma_f32_16x16x32_bf16 v[40:43], v[68:71], v[180:183], v[40:43]
	v_mfma_f32_16x16x32_bf16 v[204:207], v[72:75], v[180:183], v[204:207]
	v_mfma_f32_16x16x32_bf16 v[104:107], v[76:79], v[180:183], v[104:107]
	ds_read_b128 v[180:183], v213 offset:0
	global_load_dwordx4 v[172:175], v150, s[92:93] offset:0
	s_waitcnt lgkmcnt(5)
	v_mfma_f32_16x16x32_bf16 v[12:15], v[64:67], v[188:191], v[12:15]
	v_mfma_f32_16x16x32_bf16 v[44:47], v[68:71], v[188:191], v[44:47]
	v_mfma_f32_16x16x32_bf16 v[208:211], v[72:75], v[188:191], v[208:211]
	v_mfma_f32_16x16x32_bf16 v[108:111], v[76:79], v[188:191], v[108:111]
	ds_read_b128 v[188:191], v213 offset:2048
	s_waitcnt lgkmcnt(5)
	v_mfma_f32_16x16x32_bf16 v[16:19], v[64:67], v[192:195], v[16:19]
	v_mfma_f32_16x16x32_bf16 v[48:51], v[68:71], v[192:195], v[48:51]
	v_mfma_f32_16x16x32_bf16 v[232:235], v[72:75], v[192:195], v[232:235]
	v_mfma_f32_16x16x32_bf16 v[112:115], v[76:79], v[192:195], v[112:115]
	ds_read_b128 v[192:195], v213 offset:4096
	s_waitcnt lgkmcnt(5)
	v_mfma_f32_16x16x32_bf16 v[20:23], v[64:67], v[196:199], v[20:23]
	v_mfma_f32_16x16x32_bf16 v[52:55], v[68:71], v[196:199], v[52:55]
	v_mfma_f32_16x16x32_bf16 v[236:239], v[72:75], v[196:199], v[236:239]
	v_mfma_f32_16x16x32_bf16 v[116:119], v[76:79], v[196:199], v[116:119]
	ds_read_b128 v[196:199], v213 offset:6144
	s_waitcnt lgkmcnt(5)
	v_mfma_f32_16x16x32_bf16 v[24:27], v[64:67], v[160:163], v[24:27]
	v_mfma_f32_16x16x32_bf16 v[56:59], v[68:71], v[160:163], v[56:59]
	v_mfma_f32_16x16x32_bf16 v[240:243], v[72:75], v[160:163], v[240:243]
	v_mfma_f32_16x16x32_bf16 v[120:123], v[76:79], v[160:163], v[120:123]
	ds_read_b128 v[160:163], v213 offset:8192
	s_waitcnt lgkmcnt(5)
	v_mfma_f32_16x16x32_bf16 v[28:31], v[64:67], v[176:179], v[28:31]
	v_mfma_f32_16x16x32_bf16 v[60:63], v[68:71], v[176:179], v[60:63]
	v_mfma_f32_16x16x32_bf16 v[248:251], v[72:75], v[176:179], v[248:251]
	v_mfma_f32_16x16x32_bf16 v[124:127], v[76:79], v[176:179], v[124:127]
	s_waitcnt vmcnt(16)
	s_barrier
	s_waitcnt vmcnt(8)
	ds_read_b128 v[176:179], v213 offset:10240
	global_load_dwordx4 v[64:67], v142, s[84:85] offset:1024
	s_waitcnt lgkmcnt(5)
	v_mfma_f32_16x16x32_bf16 v[0:3], v[80:83], v[180:183], v[0:3]
	v_mfma_f32_16x16x32_bf16 v[32:35], v[84:87], v[180:183], v[32:35]
	v_mfma_f32_16x16x32_bf16 v[144:147], v[88:91], v[180:183], v[144:147]
	v_mfma_f32_16x16x32_bf16 v[252:255], v[92:95], v[180:183], v[252:255]
	ds_read_b128 v[180:183], v213 offset:12288
	global_load_dwordx4 v[68:71], v150, s[84:85] offset:1024
	s_waitcnt lgkmcnt(5)
	v_mfma_f32_16x16x32_bf16 v[4:7], v[80:83], v[188:191], v[4:7]
	v_mfma_f32_16x16x32_bf16 v[36:39], v[84:87], v[188:191], v[36:39]
	v_mfma_f32_16x16x32_bf16 v[184:187], v[88:91], v[188:191], v[184:187]
	v_mfma_f32_16x16x32_bf16 v[100:103], v[92:95], v[188:191], v[100:103]
	ds_read_b128 v[188:191], v213 offset:14336
	global_load_dwordx4 v[72:75], v142, s[92:93] offset:1024
	s_waitcnt lgkmcnt(5)
	v_mfma_f32_16x16x32_bf16 v[8:11], v[80:83], v[192:195], v[8:11]
	v_mfma_f32_16x16x32_bf16 v[40:43], v[84:87], v[192:195], v[40:43]
	v_mfma_f32_16x16x32_bf16 v[204:207], v[88:91], v[192:195], v[204:207]
	v_mfma_f32_16x16x32_bf16 v[104:107], v[92:95], v[192:195], v[104:107]
	ds_read_b128 v[192:195], v212 offset:16384
	global_load_dwordx4 v[76:79], v150, s[92:93] offset:1024
	s_add_u32 s84, s84, 0x800
	s_addc_u32 s85, s85, 0
	s_add_u32 s92, s92, 0x800
	s_addc_u32 s93, s93, 0
	s_waitcnt lgkmcnt(5)
	v_mfma_f32_16x16x32_bf16 v[12:15], v[80:83], v[196:199], v[12:15]
	v_mfma_f32_16x16x32_bf16 v[44:47], v[84:87], v[196:199], v[44:47]
	v_mfma_f32_16x16x32_bf16 v[208:211], v[88:91], v[196:199], v[208:211]
	v_mfma_f32_16x16x32_bf16 v[108:111], v[92:95], v[196:199], v[108:111]
	ds_read_b128 v[196:199], v212 offset:18432
	s_add_u32 m0, s1, 49152
	s_nop 0
	global_load_lds_dwordx4 v151, s[86:87]
	s_waitcnt lgkmcnt(5)
	v_mfma_f32_16x16x32_bf16 v[16:19], v[80:83], v[160:163], v[16:19]
	v_mfma_f32_16x16x32_bf16 v[48:51], v[84:87], v[160:163], v[48:51]
	v_mfma_f32_16x16x32_bf16 v[232:235], v[88:91], v[160:163], v[232:235]
	v_mfma_f32_16x16x32_bf16 v[112:115], v[92:95], v[160:163], v[112:115]
	ds_read_b128 v[160:163], v212 offset:20480
	s_add_u32 m0, s1, 53248
	s_nop 0
	global_load_lds_dwordx4 v156, s[86:87]
	s_waitcnt lgkmcnt(5)
	v_mfma_f32_16x16x32_bf16 v[20:23], v[80:83], v[176:179], v[20:23]
	v_mfma_f32_16x16x32_bf16 v[52:55], v[84:87], v[176:179], v[52:55]
	v_mfma_f32_16x16x32_bf16 v[236:239], v[88:91], v[176:179], v[236:239]
	v_mfma_f32_16x16x32_bf16 v[116:119], v[92:95], v[176:179], v[116:119]
	ds_read_b128 v[176:179], v212 offset:22528
	s_add_u32 m0, s1, 57344
	s_nop 0
	global_load_lds_dwordx4 v158, s[86:87]
	s_waitcnt lgkmcnt(5)
	v_mfma_f32_16x16x32_bf16 v[24:27], v[80:83], v[180:183], v[24:27]
	v_mfma_f32_16x16x32_bf16 v[56:59], v[84:87], v[180:183], v[56:59]
	v_mfma_f32_16x16x32_bf16 v[240:243], v[88:91], v[180:183], v[240:243]
	v_mfma_f32_16x16x32_bf16 v[120:123], v[92:95], v[180:183], v[120:123]
	ds_read_b128 v[180:183], v212 offset:24576
	s_add_u32 m0, s1, 61440
	s_nop 0
	global_load_lds_dwordx4 v159, s[86:87]
	s_add_u32 s86, s86, 128
	s_addc_u32 s87, s87, 0
	s_waitcnt lgkmcnt(5)
	v_mfma_f32_16x16x32_bf16 v[28:31], v[80:83], v[188:191], v[28:31]
	v_mfma_f32_16x16x32_bf16 v[60:63], v[84:87], v[188:191], v[60:63]
	v_mfma_f32_16x16x32_bf16 v[248:251], v[88:91], v[188:191], v[248:251]
	v_mfma_f32_16x16x32_bf16 v[124:127], v[92:95], v[188:191], v[124:127]
	s_waitcnt vmcnt(8)
	ds_read_b128 v[188:191], v212 offset:26624
	global_load_dwordx4 v[80:83], v142, s[84:85] offset:0
	s_waitcnt lgkmcnt(5)
	v_mfma_f32_16x16x32_bf16 v[0:3], v[96:99], v[192:195], v[0:3]
	v_mfma_f32_16x16x32_bf16 v[32:35], v[164:167], v[192:195], v[32:35]
	v_mfma_f32_16x16x32_bf16 v[144:147], v[168:171], v[192:195], v[144:147]
	v_mfma_f32_16x16x32_bf16 v[252:255], v[172:175], v[192:195], v[252:255]
	ds_read_b128 v[192:195], v212 offset:28672
	global_load_dwordx4 v[84:87], v150, s[84:85] offset:0
	s_waitcnt lgkmcnt(5)
	v_mfma_f32_16x16x32_bf16 v[4:7], v[96:99], v[196:199], v[4:7]
	v_mfma_f32_16x16x32_bf16 v[36:39], v[164:167], v[196:199], v[36:39]
	v_mfma_f32_16x16x32_bf16 v[184:187], v[168:171], v[196:199], v[184:187]
	v_mfma_f32_16x16x32_bf16 v[100:103], v[172:175], v[196:199], v[100:103]
	ds_read_b128 v[196:199], v212 offset:30720
	global_load_dwordx4 v[88:91], v142, s[92:93] offset:0
	s_waitcnt lgkmcnt(5)
	v_mfma_f32_16x16x32_bf16 v[8:11], v[96:99], v[160:163], v[8:11]
	v_mfma_f32_16x16x32_bf16 v[40:43], v[164:167], v[160:163], v[40:43]
	v_mfma_f32_16x16x32_bf16 v[204:207], v[168:171], v[160:163], v[204:207]
	v_mfma_f32_16x16x32_bf16 v[104:107], v[172:175], v[160:163], v[104:107]
	ds_read_b128 v[160:163], v213 offset:16384
	global_load_dwordx4 v[92:95], v150, s[92:93] offset:0
	s_waitcnt lgkmcnt(5)
	v_mfma_f32_16x16x32_bf16 v[12:15], v[96:99], v[176:179], v[12:15]
	v_mfma_f32_16x16x32_bf16 v[44:47], v[164:167], v[176:179], v[44:47]
	v_mfma_f32_16x16x32_bf16 v[208:211], v[168:171], v[176:179], v[208:211]
	v_mfma_f32_16x16x32_bf16 v[108:111], v[172:175], v[176:179], v[108:111]
	ds_read_b128 v[176:179], v213 offset:18432
	s_waitcnt lgkmcnt(5)
	v_mfma_f32_16x16x32_bf16 v[16:19], v[96:99], v[180:183], v[16:19]
	v_mfma_f32_16x16x32_bf16 v[48:51], v[164:167], v[180:183], v[48:51]
	v_mfma_f32_16x16x32_bf16 v[232:235], v[168:171], v[180:183], v[232:235]
	v_mfma_f32_16x16x32_bf16 v[112:115], v[172:175], v[180:183], v[112:115]
	ds_read_b128 v[180:183], v213 offset:20480
	s_waitcnt lgkmcnt(5)
	v_mfma_f32_16x16x32_bf16 v[20:23], v[96:99], v[188:191], v[20:23]
	v_mfma_f32_16x16x32_bf16 v[52:55], v[164:167], v[188:191], v[52:55]
	v_mfma_f32_16x16x32_bf16 v[236:239], v[168:171], v[188:191], v[236:239]
	v_mfma_f32_16x16x32_bf16 v[116:119], v[172:175], v[188:191], v[116:119]
	ds_read_b128 v[188:191], v213 offset:22528
	s_waitcnt lgkmcnt(5)
	v_mfma_f32_16x16x32_bf16 v[24:27], v[96:99], v[192:195], v[24:27]
	v_mfma_f32_16x16x32_bf16 v[56:59], v[164:167], v[192:195], v[56:59]
	v_mfma_f32_16x16x32_bf16 v[240:243], v[168:171], v[192:195], v[240:243]
	v_mfma_f32_16x16x32_bf16 v[120:123], v[172:175], v[192:195], v[120:123]
	ds_read_b128 v[192:195], v213 offset:24576
	s_waitcnt lgkmcnt(5)
	v_mfma_f32_16x16x32_bf16 v[28:31], v[96:99], v[196:199], v[28:31]
	v_mfma_f32_16x16x32_bf16 v[60:63], v[164:167], v[196:199], v[60:63]
	v_mfma_f32_16x16x32_bf16 v[248:251], v[168:171], v[196:199], v[248:251]
	v_mfma_f32_16x16x32_bf16 v[124:127], v[172:175], v[196:199], v[124:127]
	s_waitcnt vmcnt(16)
	s_barrier
	s_waitcnt vmcnt(8)
	ds_read_b128 v[196:199], v213 offset:26624
	global_load_dwordx4 v[96:99], v142, s[84:85] offset:1024
	s_waitcnt lgkmcnt(5)
	v_mfma_f32_16x16x32_bf16 v[0:3], v[64:67], v[160:163], v[0:3]
	v_mfma_f32_16x16x32_bf16 v[32:35], v[68:71], v[160:163], v[32:35]
	v_mfma_f32_16x16x32_bf16 v[144:147], v[72:75], v[160:163], v[144:147]
	v_mfma_f32_16x16x32_bf16 v[252:255], v[76:79], v[160:163], v[252:255]
	ds_read_b128 v[160:163], v213 offset:28672
	global_load_dwordx4 v[164:167], v150, s[84:85] offset:1024
	s_waitcnt lgkmcnt(5)
	v_mfma_f32_16x16x32_bf16 v[4:7], v[64:67], v[176:179], v[4:7]
	v_mfma_f32_16x16x32_bf16 v[36:39], v[68:71], v[176:179], v[36:39]
	v_mfma_f32_16x16x32_bf16 v[184:187], v[72:75], v[176:179], v[184:187]
	v_mfma_f32_16x16x32_bf16 v[100:103], v[76:79], v[176:179], v[100:103]
	ds_read_b128 v[176:179], v213 offset:30720
	global_load_dwordx4 v[168:171], v142, s[92:93] offset:1024
	s_waitcnt lgkmcnt(5)
	v_mfma_f32_16x16x32_bf16 v[8:11], v[64:67], v[180:183], v[8:11]
	v_mfma_f32_16x16x32_bf16 v[40:43], v[68:71], v[180:183], v[40:43]
	v_mfma_f32_16x16x32_bf16 v[204:207], v[72:75], v[180:183], v[204:207]
	v_mfma_f32_16x16x32_bf16 v[104:107], v[76:79], v[180:183], v[104:107]
	ds_read_b128 v[180:183], v212 offset:32768
	global_load_dwordx4 v[172:175], v150, s[92:93] offset:1024
	s_add_u32 s84, s84, 0x800
	s_addc_u32 s85, s85, 0
	s_add_u32 s92, s92, 0x800
	s_addc_u32 s93, s93, 0
	s_waitcnt lgkmcnt(5)
	v_mfma_f32_16x16x32_bf16 v[12:15], v[64:67], v[188:191], v[12:15]
	v_mfma_f32_16x16x32_bf16 v[44:47], v[68:71], v[188:191], v[44:47]
	v_mfma_f32_16x16x32_bf16 v[208:211], v[72:75], v[188:191], v[208:211]
	v_mfma_f32_16x16x32_bf16 v[108:111], v[76:79], v[188:191], v[108:111]
	ds_read_b128 v[188:191], v212 offset:34816
	s_waitcnt lgkmcnt(5)
	v_mfma_f32_16x16x32_bf16 v[16:19], v[64:67], v[192:195], v[16:19]
	v_mfma_f32_16x16x32_bf16 v[48:51], v[68:71], v[192:195], v[48:51]
	v_mfma_f32_16x16x32_bf16 v[232:235], v[72:75], v[192:195], v[232:235]
	v_mfma_f32_16x16x32_bf16 v[112:115], v[76:79], v[192:195], v[112:115]
	ds_read_b128 v[192:195], v212 offset:36864
	s_waitcnt lgkmcnt(5)
	v_mfma_f32_16x16x32_bf16 v[20:23], v[64:67], v[196:199], v[20:23]
	v_mfma_f32_16x16x32_bf16 v[52:55], v[68:71], v[196:199], v[52:55]
	v_mfma_f32_16x16x32_bf16 v[236:239], v[72:75], v[196:199], v[236:239]
	v_mfma_f32_16x16x32_bf16 v[116:119], v[76:79], v[196:199], v[116:119]
	ds_read_b128 v[196:199], v212 offset:38912
	s_waitcnt lgkmcnt(5)
	v_mfma_f32_16x16x32_bf16 v[24:27], v[64:67], v[160:163], v[24:27]
	v_mfma_f32_16x16x32_bf16 v[56:59], v[68:71], v[160:163], v[56:59]
	v_mfma_f32_16x16x32_bf16 v[240:243], v[72:75], v[160:163], v[240:243]
	v_mfma_f32_16x16x32_bf16 v[120:123], v[76:79], v[160:163], v[120:123]
	ds_read_b128 v[160:163], v212 offset:40960
	s_waitcnt lgkmcnt(5)
	v_mfma_f32_16x16x32_bf16 v[28:31], v[64:67], v[176:179], v[28:31]
	v_mfma_f32_16x16x32_bf16 v[60:63], v[68:71], v[176:179], v[60:63]
	v_mfma_f32_16x16x32_bf16 v[248:251], v[72:75], v[176:179], v[248:251]
	v_mfma_f32_16x16x32_bf16 v[124:127], v[76:79], v[176:179], v[124:127]
	s_waitcnt vmcnt(4)
	ds_read_b128 v[176:179], v212 offset:43008
	global_load_dwordx4 v[64:67], v142, s[84:85] offset:0
	s_waitcnt lgkmcnt(5)
	v_mfma_f32_16x16x32_bf16 v[0:3], v[80:83], v[180:183], v[0:3]
	v_mfma_f32_16x16x32_bf16 v[32:35], v[84:87], v[180:183], v[32:35]
	v_mfma_f32_16x16x32_bf16 v[144:147], v[88:91], v[180:183], v[144:147]
	v_mfma_f32_16x16x32_bf16 v[252:255], v[92:95], v[180:183], v[252:255]
	ds_read_b128 v[180:183], v212 offset:45056
	global_load_dwordx4 v[68:71], v150, s[84:85] offset:0
	s_waitcnt lgkmcnt(5)
	v_mfma_f32_16x16x32_bf16 v[4:7], v[80:83], v[188:191], v[4:7]
	v_mfma_f32_16x16x32_bf16 v[36:39], v[84:87], v[188:191], v[36:39]
	v_mfma_f32_16x16x32_bf16 v[184:187], v[88:91], v[188:191], v[184:187]
	v_mfma_f32_16x16x32_bf16 v[100:103], v[92:95], v[188:191], v[100:103]
	ds_read_b128 v[188:191], v212 offset:47104
	global_load_dwordx4 v[72:75], v142, s[92:93] offset:0
	s_waitcnt lgkmcnt(5)
	v_mfma_f32_16x16x32_bf16 v[8:11], v[80:83], v[192:195], v[8:11]
	v_mfma_f32_16x16x32_bf16 v[40:43], v[84:87], v[192:195], v[40:43]
	v_mfma_f32_16x16x32_bf16 v[204:207], v[88:91], v[192:195], v[204:207]
	v_mfma_f32_16x16x32_bf16 v[104:107], v[92:95], v[192:195], v[104:107]
	ds_read_b128 v[192:195], v213 offset:32768
	global_load_dwordx4 v[76:79], v150, s[92:93] offset:0
	s_waitcnt lgkmcnt(5)
	v_mfma_f32_16x16x32_bf16 v[12:15], v[80:83], v[196:199], v[12:15]
	v_mfma_f32_16x16x32_bf16 v[44:47], v[84:87], v[196:199], v[44:47]
	v_mfma_f32_16x16x32_bf16 v[208:211], v[88:91], v[196:199], v[208:211]
	v_mfma_f32_16x16x32_bf16 v[108:111], v[92:95], v[196:199], v[108:111]
	ds_read_b128 v[196:199], v213 offset:34816
	s_waitcnt lgkmcnt(5)
	v_mfma_f32_16x16x32_bf16 v[16:19], v[80:83], v[160:163], v[16:19]
	v_mfma_f32_16x16x32_bf16 v[48:51], v[84:87], v[160:163], v[48:51]
	v_mfma_f32_16x16x32_bf16 v[232:235], v[88:91], v[160:163], v[232:235]
	v_mfma_f32_16x16x32_bf16 v[112:115], v[92:95], v[160:163], v[112:115]
	ds_read_b128 v[160:163], v213 offset:36864
	s_waitcnt lgkmcnt(5)
	v_mfma_f32_16x16x32_bf16 v[20:23], v[80:83], v[176:179], v[20:23]
	v_mfma_f32_16x16x32_bf16 v[52:55], v[84:87], v[176:179], v[52:55]
	v_mfma_f32_16x16x32_bf16 v[236:239], v[88:91], v[176:179], v[236:239]
	v_mfma_f32_16x16x32_bf16 v[116:119], v[92:95], v[176:179], v[116:119]
	ds_read_b128 v[176:179], v213 offset:38912
	s_waitcnt lgkmcnt(5)
	v_mfma_f32_16x16x32_bf16 v[24:27], v[80:83], v[180:183], v[24:27]
	v_mfma_f32_16x16x32_bf16 v[56:59], v[84:87], v[180:183], v[56:59]
	v_mfma_f32_16x16x32_bf16 v[240:243], v[88:91], v[180:183], v[240:243]
	v_mfma_f32_16x16x32_bf16 v[120:123], v[92:95], v[180:183], v[120:123]
	ds_read_b128 v[180:183], v213 offset:40960
	s_waitcnt lgkmcnt(5)
	v_mfma_f32_16x16x32_bf16 v[28:31], v[80:83], v[188:191], v[28:31]
	v_mfma_f32_16x16x32_bf16 v[60:63], v[84:87], v[188:191], v[60:63]
	v_mfma_f32_16x16x32_bf16 v[248:251], v[88:91], v[188:191], v[248:251]
	v_mfma_f32_16x16x32_bf16 v[124:127], v[92:95], v[188:191], v[124:127]
	s_waitcnt vmcnt(12)
	s_barrier
	s_waitcnt vmcnt(4)
	ds_read_b128 v[188:191], v213 offset:43008
	global_load_dwordx4 v[80:83], v142, s[84:85] offset:1024
	s_waitcnt lgkmcnt(5)
	v_mfma_f32_16x16x32_bf16 v[0:3], v[96:99], v[192:195], v[0:3]
	v_mfma_f32_16x16x32_bf16 v[32:35], v[164:167], v[192:195], v[32:35]
	v_mfma_f32_16x16x32_bf16 v[144:147], v[168:171], v[192:195], v[144:147]
	v_mfma_f32_16x16x32_bf16 v[252:255], v[172:175], v[192:195], v[252:255]
	ds_read_b128 v[192:195], v213 offset:45056
	global_load_dwordx4 v[84:87], v150, s[84:85] offset:1024
	s_waitcnt lgkmcnt(5)
	v_mfma_f32_16x16x32_bf16 v[4:7], v[96:99], v[196:199], v[4:7]
	v_mfma_f32_16x16x32_bf16 v[36:39], v[164:167], v[196:199], v[36:39]
	v_mfma_f32_16x16x32_bf16 v[184:187], v[168:171], v[196:199], v[184:187]
	v_mfma_f32_16x16x32_bf16 v[100:103], v[172:175], v[196:199], v[100:103]
	ds_read_b128 v[196:199], v213 offset:47104
	global_load_dwordx4 v[88:91], v142, s[92:93] offset:1024
	s_waitcnt lgkmcnt(5)
	v_mfma_f32_16x16x32_bf16 v[8:11], v[96:99], v[160:163], v[8:11]
	v_mfma_f32_16x16x32_bf16 v[40:43], v[164:167], v[160:163], v[40:43]
	v_mfma_f32_16x16x32_bf16 v[204:207], v[168:171], v[160:163], v[204:207]
	v_mfma_f32_16x16x32_bf16 v[104:107], v[172:175], v[160:163], v[104:107]
	ds_read_b128 v[160:163], v212 offset:49152
	global_load_dwordx4 v[92:95], v150, s[92:93] offset:1024
	s_add_u32 s84, s84, 0x800
	s_addc_u32 s85, s85, 0
	s_add_u32 s92, s92, 0x800
	s_addc_u32 s93, s93, 0
	s_waitcnt lgkmcnt(5)
	v_mfma_f32_16x16x32_bf16 v[12:15], v[96:99], v[176:179], v[12:15]
	v_mfma_f32_16x16x32_bf16 v[44:47], v[164:167], v[176:179], v[44:47]
	v_mfma_f32_16x16x32_bf16 v[208:211], v[168:171], v[176:179], v[208:211]
	v_mfma_f32_16x16x32_bf16 v[108:111], v[172:175], v[176:179], v[108:111]
	ds_read_b128 v[176:179], v212 offset:51200
	s_waitcnt lgkmcnt(5)
	v_mfma_f32_16x16x32_bf16 v[16:19], v[96:99], v[180:183], v[16:19]
	v_mfma_f32_16x16x32_bf16 v[48:51], v[164:167], v[180:183], v[48:51]
	v_mfma_f32_16x16x32_bf16 v[232:235], v[168:171], v[180:183], v[232:235]
	v_mfma_f32_16x16x32_bf16 v[112:115], v[172:175], v[180:183], v[112:115]
	ds_read_b128 v[180:183], v212 offset:53248
	s_waitcnt lgkmcnt(5)
	v_mfma_f32_16x16x32_bf16 v[20:23], v[96:99], v[188:191], v[20:23]
	v_mfma_f32_16x16x32_bf16 v[52:55], v[164:167], v[188:191], v[52:55]
	v_mfma_f32_16x16x32_bf16 v[236:239], v[168:171], v[188:191], v[236:239]
	v_mfma_f32_16x16x32_bf16 v[116:119], v[172:175], v[188:191], v[116:119]
	ds_read_b128 v[188:191], v212 offset:55296
	s_waitcnt lgkmcnt(5)
	v_mfma_f32_16x16x32_bf16 v[24:27], v[96:99], v[192:195], v[24:27]
	v_mfma_f32_16x16x32_bf16 v[56:59], v[164:167], v[192:195], v[56:59]
	v_mfma_f32_16x16x32_bf16 v[240:243], v[168:171], v[192:195], v[240:243]
	v_mfma_f32_16x16x32_bf16 v[120:123], v[172:175], v[192:195], v[120:123]
	ds_read_b128 v[192:195], v212 offset:57344
	s_waitcnt lgkmcnt(5)
	v_mfma_f32_16x16x32_bf16 v[28:31], v[96:99], v[196:199], v[28:31]
	v_mfma_f32_16x16x32_bf16 v[60:63], v[164:167], v[196:199], v[60:63]
	v_mfma_f32_16x16x32_bf16 v[248:251], v[168:171], v[196:199], v[248:251]
	v_mfma_f32_16x16x32_bf16 v[124:127], v[172:175], v[196:199], v[124:127]
	s_waitcnt vmcnt(4)
	ds_read_b128 v[196:199], v212 offset:59392
	s_waitcnt lgkmcnt(5)
	v_mfma_f32_16x16x32_bf16 v[0:3], v[64:67], v[160:163], v[0:3]
	v_mfma_f32_16x16x32_bf16 v[32:35], v[68:71], v[160:163], v[32:35]
	v_mfma_f32_16x16x32_bf16 v[144:147], v[72:75], v[160:163], v[144:147]
	v_mfma_f32_16x16x32_bf16 v[252:255], v[76:79], v[160:163], v[252:255]
	ds_read_b128 v[160:163], v212 offset:61440
	s_waitcnt lgkmcnt(5)
	v_mfma_f32_16x16x32_bf16 v[4:7], v[64:67], v[176:179], v[4:7]
	v_mfma_f32_16x16x32_bf16 v[36:39], v[68:71], v[176:179], v[36:39]
	v_mfma_f32_16x16x32_bf16 v[184:187], v[72:75], v[176:179], v[184:187]
	v_mfma_f32_16x16x32_bf16 v[100:103], v[76:79], v[176:179], v[100:103]
	ds_read_b128 v[176:179], v212 offset:63488
	s_waitcnt lgkmcnt(5)
	v_mfma_f32_16x16x32_bf16 v[8:11], v[64:67], v[180:183], v[8:11]
	v_mfma_f32_16x16x32_bf16 v[40:43], v[68:71], v[180:183], v[40:43]
	v_mfma_f32_16x16x32_bf16 v[204:207], v[72:75], v[180:183], v[204:207]
	v_mfma_f32_16x16x32_bf16 v[104:107], v[76:79], v[180:183], v[104:107]
	ds_read_b128 v[180:183], v213 offset:49152
	s_waitcnt lgkmcnt(5)
	v_mfma_f32_16x16x32_bf16 v[12:15], v[64:67], v[188:191], v[12:15]
	v_mfma_f32_16x16x32_bf16 v[44:47], v[68:71], v[188:191], v[44:47]
	v_mfma_f32_16x16x32_bf16 v[208:211], v[72:75], v[188:191], v[208:211]
	v_mfma_f32_16x16x32_bf16 v[108:111], v[76:79], v[188:191], v[108:111]
	ds_read_b128 v[188:191], v213 offset:51200
	s_waitcnt lgkmcnt(5)
	v_mfma_f32_16x16x32_bf16 v[16:19], v[64:67], v[192:195], v[16:19]
	v_mfma_f32_16x16x32_bf16 v[48:51], v[68:71], v[192:195], v[48:51]
	v_mfma_f32_16x16x32_bf16 v[232:235], v[72:75], v[192:195], v[232:235]
	v_mfma_f32_16x16x32_bf16 v[112:115], v[76:79], v[192:195], v[112:115]
	ds_read_b128 v[192:195], v213 offset:53248
	s_waitcnt lgkmcnt(5)
	v_mfma_f32_16x16x32_bf16 v[20:23], v[64:67], v[196:199], v[20:23]
	v_mfma_f32_16x16x32_bf16 v[52:55], v[68:71], v[196:199], v[52:55]
	v_mfma_f32_16x16x32_bf16 v[236:239], v[72:75], v[196:199], v[236:239]
	v_mfma_f32_16x16x32_bf16 v[116:119], v[76:79], v[196:199], v[116:119]
	ds_read_b128 v[196:199], v213 offset:55296
	s_waitcnt lgkmcnt(5)
	v_mfma_f32_16x16x32_bf16 v[24:27], v[64:67], v[160:163], v[24:27]
	v_mfma_f32_16x16x32_bf16 v[56:59], v[68:71], v[160:163], v[56:59]
	v_mfma_f32_16x16x32_bf16 v[240:243], v[72:75], v[160:163], v[240:243]
	v_mfma_f32_16x16x32_bf16 v[120:123], v[76:79], v[160:163], v[120:123]
	ds_read_b128 v[160:163], v213 offset:57344
	s_waitcnt lgkmcnt(5)
	v_mfma_f32_16x16x32_bf16 v[28:31], v[64:67], v[176:179], v[28:31]
	v_mfma_f32_16x16x32_bf16 v[60:63], v[68:71], v[176:179], v[60:63]
	v_mfma_f32_16x16x32_bf16 v[248:251], v[72:75], v[176:179], v[248:251]
	v_mfma_f32_16x16x32_bf16 v[124:127], v[76:79], v[176:179], v[124:127]
	s_waitcnt vmcnt(0)
	ds_read_b128 v[176:179], v213 offset:59392
	s_waitcnt lgkmcnt(5)
	v_mfma_f32_16x16x32_bf16 v[0:3], v[80:83], v[180:183], v[0:3]
	v_mfma_f32_16x16x32_bf16 v[32:35], v[84:87], v[180:183], v[32:35]
	v_mfma_f32_16x16x32_bf16 v[144:147], v[88:91], v[180:183], v[144:147]
	v_mfma_f32_16x16x32_bf16 v[252:255], v[92:95], v[180:183], v[252:255]
	ds_read_b128 v[180:183], v213 offset:61440
	s_waitcnt lgkmcnt(5)
	v_mfma_f32_16x16x32_bf16 v[4:7], v[80:83], v[188:191], v[4:7]
	v_mfma_f32_16x16x32_bf16 v[36:39], v[84:87], v[188:191], v[36:39]
	v_mfma_f32_16x16x32_bf16 v[184:187], v[88:91], v[188:191], v[184:187]
	v_mfma_f32_16x16x32_bf16 v[100:103], v[92:95], v[188:191], v[100:103]
	ds_read_b128 v[188:191], v213 offset:63488
	s_waitcnt lgkmcnt(5)
	v_mfma_f32_16x16x32_bf16 v[8:11], v[80:83], v[192:195], v[8:11]
	v_mfma_f32_16x16x32_bf16 v[40:43], v[84:87], v[192:195], v[40:43]
	v_mfma_f32_16x16x32_bf16 v[204:207], v[88:91], v[192:195], v[204:207]
	v_mfma_f32_16x16x32_bf16 v[104:107], v[92:95], v[192:195], v[104:107]
	s_waitcnt lgkmcnt(4)
	v_mfma_f32_16x16x32_bf16 v[12:15], v[80:83], v[196:199], v[12:15]
	v_mfma_f32_16x16x32_bf16 v[44:47], v[84:87], v[196:199], v[44:47]
	v_mfma_f32_16x16x32_bf16 v[208:211], v[88:91], v[196:199], v[208:211]
	v_mfma_f32_16x16x32_bf16 v[108:111], v[92:95], v[196:199], v[108:111]
	s_waitcnt lgkmcnt(3)
	v_mfma_f32_16x16x32_bf16 v[16:19], v[80:83], v[160:163], v[16:19]
	v_mfma_f32_16x16x32_bf16 v[48:51], v[84:87], v[160:163], v[48:51]
	v_mfma_f32_16x16x32_bf16 v[232:235], v[88:91], v[160:163], v[232:235]
	v_mfma_f32_16x16x32_bf16 v[112:115], v[92:95], v[160:163], v[112:115]
	s_waitcnt lgkmcnt(2)
	v_mfma_f32_16x16x32_bf16 v[20:23], v[80:83], v[176:179], v[20:23]
	v_mfma_f32_16x16x32_bf16 v[52:55], v[84:87], v[176:179], v[52:55]
	v_mfma_f32_16x16x32_bf16 v[236:239], v[88:91], v[176:179], v[236:239]
	v_mfma_f32_16x16x32_bf16 v[116:119], v[92:95], v[176:179], v[116:119]
	s_waitcnt lgkmcnt(1)
	v_mfma_f32_16x16x32_bf16 v[24:27], v[80:83], v[180:183], v[24:27]
	v_mfma_f32_16x16x32_bf16 v[56:59], v[84:87], v[180:183], v[56:59]
	v_mfma_f32_16x16x32_bf16 v[240:243], v[88:91], v[180:183], v[240:243]
	v_mfma_f32_16x16x32_bf16 v[120:123], v[92:95], v[180:183], v[120:123]
	s_waitcnt lgkmcnt(0)
	v_mfma_f32_16x16x32_bf16 v[28:31], v[80:83], v[188:191], v[28:31]
	v_mfma_f32_16x16x32_bf16 v[60:63], v[84:87], v[188:191], v[60:63]
	v_mfma_f32_16x16x32_bf16 v[248:251], v[88:91], v[188:191], v[248:251]
	v_mfma_f32_16x16x32_bf16 v[124:127], v[92:95], v[188:191], v[124:127]
	s_nop 7
	s_nop 7
	s_waitcnt vmcnt(0) lgkmcnt(0)
	s_setprio 0
	s_barrier
	v_mov_b32_e32 v150, v100
	v_mov_b32_e32 v151, v101
	v_mov_b32_e32 v156, v102
	v_mov_b32_e32 v158, v103
	v_mov_b32_e32 v159, v104
	v_mov_b32_e32 v160, v105
	v_mov_b32_e32 v183, v106
	v_mov_b32_e32 v188, v107
	v_mov_b32_e32 v189, v108
	v_mov_b32_e32 v212, v109
	v_mov_b32_e32 v213, v110
	v_mov_b32_e32 v214, v111
	v_mov_b32_e32 v216, v112
	v_mov_b32_e32 v218, v113
	v_mov_b32_e32 v220, v114
	v_mov_b32_e32 v222, v115
	v_mov_b32_e32 v224, v116
	v_mov_b32_e32 v226, v117
	v_mov_b32_e32 v228, v118
	v_mov_b32_e32 v230, v119
	v_mov_b32_e32 v231, v120
	v_mov_b32_e32 v244, v121
	v_mov_b32_e32 v245, v122
	ds_write_b32 v140, v123 offset:40960
	ds_write_b32 v140, v124 offset:41984
	ds_write_b32 v140, v125 offset:43008
	ds_write_b32 v140, v126 offset:44032
	ds_write_b32 v140, v127 offset:45056
	v_lshlrev_b32_e32 v64, 13, v135
	v_lshl_add_u32 v65, v134, 3, v138
	v_lshl_or_b32 v66, v134, 11, v64
	v_lshlrev_b32_e32 v68, 5, v138
	v_or3_b32 v161, v64, v137, v68
	v_lshl_or_b32 v162, v65, 2, v66
	v_add_u32_e32 v68, 0x60, v65
	v_add_u32_e32 v65, 0x70, v65
	v_and_b32_e32 v68, 0x7f, v68
	v_and_b32_e32 v65, 0x7f, v65
	v_lshl_or_b32 v163, v68, 2, v66
	v_lshl_or_b32 v164, v65, 2, v66
	v_add_u32_e32 v66, 8, v133
	v_and_b32_e32 v66, 0x78, v66
	v_lshlrev_b32_e32 v65, 9, v136
	v_lshlrev_b32_e32 v66, 2, v66
	v_or3_b32 v166, v64, v65, v66
	v_add_u32_e32 v66, 16, v133
	v_and_b32_e32 v66, 0x78, v66
	v_lshlrev_b32_e32 v65, 9, v132
	v_lshlrev_b32_e32 v66, 2, v66
	v_or3_b32 v168, v64, v65, v66
	v_add_u32_e32 v66, 24, v133
	v_and_b32_e32 v66, 0x78, v66
	v_lshlrev_b32_e32 v67, 5, v135
	v_lshlrev_b32_e32 v65, 9, v130
	v_lshlrev_b32_e32 v66, 2, v66
	v_or3_b32 v170, v64, v65, v66
	v_or_b32_e32 v64, 16, v67
	v_add_u32_e32 v68, 0x100, v131
	v_add_u32_e32 v69, 0x200, v131
	v_add_u32_e32 v70, 0x300, v131
	v_add_u32_e32 v71, 0x500, v131
	v_add_u32_e32 v72, 0x600, v131
	v_add_u32_e32 v73, 0x700, v131
	v_or_b32_e32 v172, v64, v134
	v_or_b32_e32 v173, v136, v64
	v_or_b32_e32 v174, v132, v64
	v_or_b32_e32 v175, v130, v64
	v_and_b32_e32 v64, 24, v153
	s_movk_i32 s90, 0x3c0
	v_lshrrev_b32_e32 v176, 4, v68
	v_lshrrev_b32_e32 v177, 4, v69
	v_lshrrev_b32_e32 v178, 4, v70
	v_lshrrev_b32_e32 v180, 4, v71
	v_lshrrev_b32_e32 v181, 4, v72
	v_lshrrev_b32_e32 v182, 4, v73
	v_or_b32_e32 v165, v134, v67
	v_or_b32_e32 v167, v136, v67
	v_or_b32_e32 v169, v132, v67
	v_or_b32_e32 v171, v130, v67
	v_and_or_b32 v64, v131, s90, v64
	v_mul_u32_u24_e32 v65, 0x110, v138
	v_lshlrev_b32_e32 v66, 4, v138
	v_mul_u32_u24_e32 v67, 0x110, v128
	v_mul_u32_u24_e32 v68, 0x110, v176
	v_mul_u32_u24_e32 v69, 0x110, v177
	v_mul_u32_u24_e32 v70, 0x110, v178
	v_mul_u32_u24_e32 v71, 0x110, v180
	v_mul_u32_u24_e32 v72, 0x110, v181
	v_mul_u32_u24_e32 v73, 0x110, v182
	v_or_b32_e32 v179, 64, v128
	v_lshlrev_b32_e32 v190, 2, v138
	v_add_u32_e32 v191, v64, v65
	v_add_u32_e32 v192, v66, v67
	v_add_u32_e32 v193, v66, v68
	v_add_u32_e32 v194, v66, v69
	v_add_u32_e32 v195, v66, v70
	v_add_u32_e32 v196, v66, v71
	v_add_u32_e32 v197, v66, v72
	v_add_u32_e32 v198, v66, v73
	v_mbcnt_hi_u32_b32 v199, -1, v155
	s_waitcnt lgkmcnt(0)
	s_mov_b64 s[6:7], -1
	s_cmp_lt_i32 s77, 5
	s_branch .Lmy_ip0_epi

.LBB0_430:
	s_lshr_b32 s90, s64, 3
	s_lshl_b32 s90, s90, 4
	s_and_b32 s91, s64, 7
	s_or_b32 s90, s90, s91
	s_lshl_b32 s91, s89, 3
	s_add_i32 s90, s90, s91
	s_ashr_i32 s1, s90, 31
	s_lshr_b32 s1, s1, 23
	s_add_i32 s1, s90, s1
	s_ashr_i32 s1, s1, 9
	s_and_b32 s0, s90, 7
	s_lshl_b32 s1, s1, 3
	s_or_b32 s38, s1, s0
	s_mul_hi_i32 s66, s38, 0x2aaaaaab
	s_lshr_b32 s0, s66, 31
	s_add_i32 s66, s66, s0
	s_lshl_b32 s0, s66, 3
	s_bfe_u32 s1, s90, 0x30003
	s_or_b32 s0, s0, s1
	s_mul_i32 s1, s66, 6
	s_sub_i32 s65, s38, s1
	s_lshl_b32 s1, s65, 3
	s_bfe_u32 s33, s90, 0x30006
	s_or_b32 s4, s1, s33
	s_ashr_i32 s1, s0, 31
	s_ashr_i32 s5, s4, 31
	s_lshl_b64 s[54:55], s[4:5], 18
	s_lshl_b64 s[56:57], s[0:1], 18
	s_cmp_lg_u32 s89, 0
	s_cbranch_scc1 .Lmy_ip1_pass2
	s_barrier
	s_setprio 2
	s_add_u32 s84, s50, 0x3a00000
	s_addc_u32 s85, s51, 0
	s_add_u32 s84, s84, s56
	s_addc_u32 s85, s85, s57
	s_add_u32 s92, s84, 0x40000
	s_addc_u32 s93, s85, 0
	s_add_u32 s86, s50, s54
	s_addc_u32 s87, s51, s55
	s_lshl_b64 s[54:55], s[0:1], 17
	v_readfirstlane_b32 s88, v129
	v_and_b32_e32 v200, 15, v131
	v_bfe_u32 v201, v131, 4, 2
	v_and_b32_e32 v202, 63, v131
	v_lshlrev_b32_e32 v202, 4, v202
	v_lshrrev_b32_e32 v203, 6, v131
	v_lshl_add_u32 v66, v203, 16, v202
	v_add_u32_e32 v67, 0x8000, v66
	v_bfe_u32 v202, v131, 1, 3
	v_xor_b32_e32 v202, v201, v202
	v_lshlrev_b32_e32 v202, 4, v202
	v_lshl_or_b32 v75, v200, 7, v202
	v_xor_b32_e32 v212, 64, v75
	v_bfe_u32 v200, v131, 4, 3
	v_and_b32_e32 v201, 7, v131
	v_xor_b32_e32 v200, v200, v201
	v_lshlrev_b32_e32 v200, 4, v200
	v_lshrrev_b32_e32 v201, 3, v131
	v_lshl_or_b32 v68, v201, 11, v200
	v_add_u32_e32 v69, 65536, v68
	v_add_u32_e32 v71, 131072, v68
	v_add_u32_e32 v74, 196608, v68
	s_add_u32 m0, s88, 0
	v_mov_b32_e32 v32, 0
	v_mov_b32_e32 v33, 0
	global_load_lds_dwordx4 v68, s[86:87]
	v_mov_b32_e32 v34, 0
	v_mov_b32_e32 v35, 0
	v_mov_b32_e32 v36, 0
	s_add_u32 m0, s88, 4096
	v_mov_b32_e32 v37, 0
	v_mov_b32_e32 v38, 0
	global_load_lds_dwordx4 v69, s[86:87]
	v_mov_b32_e32 v39, 0
	v_mov_b32_e32 v40, 0
	v_mov_b32_e32 v41, 0
	s_add_u32 m0, s88, 8192
	v_mov_b32_e32 v42, 0
	v_mov_b32_e32 v43, 0
	global_load_lds_dwordx4 v71, s[86:87]
	v_mov_b32_e32 v44, 0
	v_mov_b32_e32 v45, 0
	v_mov_b32_e32 v46, 0
	s_add_u32 m0, s88, 12288
	v_mov_b32_e32 v47, 0
	v_mov_b32_e32 v48, 0
	global_load_lds_dwordx4 v74, s[86:87]
	s_add_u32 s86, s86, 128
	s_addc_u32 s87, s87, 0
	v_mov_b32_e32 v49, 0
	v_mov_b32_e32 v50, 0
	v_mov_b32_e32 v51, 0
	global_load_dwordx4 v[76:79], v66, s[84:85] offset:0
	v_mov_b32_e32 v52, 0
	v_mov_b32_e32 v53, 0
	v_mov_b32_e32 v54, 0
	global_load_dwordx4 v[80:83], v67, s[84:85] offset:0
	v_mov_b32_e32 v55, 0
	v_mov_b32_e32 v56, 0
	v_mov_b32_e32 v57, 0
	global_load_dwordx4 v[84:87], v66, s[92:93] offset:0
	v_mov_b32_e32 v58, 0
	v_mov_b32_e32 v59, 0
	v_mov_b32_e32 v60, 0
	global_load_dwordx4 v[88:91], v67, s[92:93] offset:0
	v_mov_b32_e32 v61, 0
	v_mov_b32_e32 v62, 0
	v_mov_b32_e32 v63, 0
	global_load_dwordx4 v[140:143], v66, s[84:85] offset:1024
	v_mov_b32_e32 v4, 0
	v_mov_b32_e32 v5, 0
	v_mov_b32_e32 v6, 0
	global_load_dwordx4 v[144:147], v67, s[84:85] offset:1024
	v_mov_b32_e32 v7, 0
	v_mov_b32_e32 v12, 0
	v_mov_b32_e32 v13, 0
	global_load_dwordx4 v[148:151], v66, s[92:93] offset:1024
	v_mov_b32_e32 v14, 0
	v_mov_b32_e32 v15, 0
	v_mov_b32_e32 v16, 0
	global_load_dwordx4 v[204:207], v67, s[92:93] offset:1024
	s_add_u32 s84, s84, 0x800
	s_addc_u32 s85, s85, 0
	s_add_u32 s92, s92, 0x800
	s_addc_u32 s93, s93, 0
	v_mov_b32_e32 v17, 0
	v_mov_b32_e32 v18, 0
	v_mov_b32_e32 v19, 0
	s_add_u32 m0, s88, 16384
	v_mov_b32_e32 v20, 0
	v_mov_b32_e32 v21, 0
	global_load_lds_dwordx4 v68, s[86:87]
	v_mov_b32_e32 v22, 0
	v_mov_b32_e32 v23, 0
	v_mov_b32_e32 v0, 0
	s_add_u32 m0, s88, 20480
	v_mov_b32_e32 v1, 0
	v_mov_b32_e32 v2, 0
	global_load_lds_dwordx4 v69, s[86:87]
	v_mov_b32_e32 v3, 0
	v_mov_b32_e32 v8, 0
	v_mov_b32_e32 v9, 0
	s_add_u32 m0, s88, 24576
	v_mov_b32_e32 v10, 0
	v_mov_b32_e32 v11, 0
	global_load_lds_dwordx4 v71, s[86:87]
	v_mov_b32_e32 v24, 0
	v_mov_b32_e32 v25, 0
	v_mov_b32_e32 v26, 0
	s_add_u32 m0, s88, 28672
	v_mov_b32_e32 v27, 0
	v_mov_b32_e32 v28, 0
	global_load_lds_dwordx4 v74, s[86:87]
	s_add_u32 s86, s86, 128
	s_addc_u32 s87, s87, 0
	v_mov_b32_e32 v29, 0
	v_mov_b32_e32 v30, 0
	v_mov_b32_e32 v31, 0
	s_add_u32 m0, s88, 32768
	v_mov_b32_e32 v188, 0
	v_mov_b32_e32 v189, 0
	global_load_lds_dwordx4 v68, s[86:87]
	v_mov_b32_e32 v190, 0
	v_mov_b32_e32 v191, 0
	v_mov_b32_e32 v208, 0
	s_add_u32 m0, s88, 36864
	v_mov_b32_e32 v209, 0
	v_mov_b32_e32 v210, 0
	global_load_lds_dwordx4 v69, s[86:87]
	v_mov_b32_e32 v211, 0
	v_mov_b32_e32 v232, 0
	v_mov_b32_e32 v233, 0
	s_add_u32 m0, s88, 40960
	v_mov_b32_e32 v234, 0
	v_mov_b32_e32 v235, 0
	global_load_lds_dwordx4 v71, s[86:87]
	v_mov_b32_e32 v236, 0
	v_mov_b32_e32 v237, 0
	v_mov_b32_e32 v238, 0
	s_add_u32 m0, s88, 45056
	v_mov_b32_e32 v239, 0
	v_mov_b32_e32 v240, 0
	global_load_lds_dwordx4 v74, s[86:87]
	s_add_u32 s86, s86, 128
	s_addc_u32 s87, s87, 0
	v_mov_b32_e32 v241, 0
	v_mov_b32_e32 v242, 0
	v_mov_b32_e32 v243, 0
	v_mov_b32_e32 v248, 0
	v_mov_b32_e32 v249, 0
	v_mov_b32_e32 v250, 0
	v_mov_b32_e32 v251, 0
	v_mov_b32_e32 v252, 0
	v_mov_b32_e32 v253, 0
	v_mov_b32_e32 v254, 0
	v_mov_b32_e32 v255, 0
	v_mov_b32_e32 v92, 0
	v_mov_b32_e32 v93, 0
	v_mov_b32_e32 v94, 0
	v_mov_b32_e32 v95, 0
	v_mov_b32_e32 v96, 0
	v_mov_b32_e32 v97, 0
	v_mov_b32_e32 v98, 0
	v_mov_b32_e32 v99, 0
	v_mov_b32_e32 v100, 0
	v_mov_b32_e32 v101, 0
	v_mov_b32_e32 v102, 0
	v_mov_b32_e32 v103, 0
	v_mov_b32_e32 v104, 0
	v_mov_b32_e32 v105, 0
	v_mov_b32_e32 v106, 0
	v_mov_b32_e32 v107, 0
	v_mov_b32_e32 v108, 0
	v_mov_b32_e32 v109, 0
	v_mov_b32_e32 v110, 0
	v_mov_b32_e32 v111, 0
	v_mov_b32_e32 v112, 0
	v_mov_b32_e32 v113, 0
	v_mov_b32_e32 v114, 0
	v_mov_b32_e32 v115, 0
	v_mov_b32_e32 v116, 0
	v_mov_b32_e32 v117, 0
	v_mov_b32_e32 v118, 0
	v_mov_b32_e32 v119, 0
	v_mov_b32_e32 v120, 0
	v_mov_b32_e32 v121, 0
	v_mov_b32_e32 v122, 0
	v_mov_b32_e32 v123, 0
	v_mov_b32_e32 v124, 0
	v_mov_b32_e32 v125, 0
	v_mov_b32_e32 v126, 0
	v_mov_b32_e32 v127, 0
	s_waitcnt vmcnt(12)
	s_barrier
	ds_read_b128 v[176:179], v75 offset:0
	ds_read_b128 v[180:183], v75 offset:2048
	ds_read_b128 v[184:187], v75 offset:4096
	ds_read_b128 v[192:195], v75 offset:6144
	ds_read_b128 v[196:199], v75 offset:8192
	ds_read_b128 v[200:203], v75 offset:10240
	global_load_dwordx4 v[160:163], v66, s[84:85] offset:0
	s_waitcnt lgkmcnt(5)
	v_mfma_f32_16x16x32_bf16 v[32:35], v[76:79], v[176:179], v[32:35]
	v_mfma_f32_16x16x32_bf16 v[4:7], v[80:83], v[176:179], v[4:7]
	v_mfma_f32_16x16x32_bf16 v[188:191], v[84:87], v[176:179], v[188:191]
	v_mfma_f32_16x16x32_bf16 v[96:99], v[88:91], v[176:179], v[96:99]
	ds_read_b128 v[176:179], v75 offset:12288
	global_load_dwordx4 v[164:167], v67, s[84:85] offset:0
	s_waitcnt lgkmcnt(5)
	v_mfma_f32_16x16x32_bf16 v[36:39], v[76:79], v[180:183], v[36:39]
	v_mfma_f32_16x16x32_bf16 v[12:15], v[80:83], v[180:183], v[12:15]
	v_mfma_f32_16x16x32_bf16 v[208:211], v[84:87], v[180:183], v[208:211]
	v_mfma_f32_16x16x32_bf16 v[100:103], v[88:91], v[180:183], v[100:103]
	ds_read_b128 v[180:183], v75 offset:14336
	global_load_dwordx4 v[168:171], v66, s[92:93] offset:0
	s_waitcnt lgkmcnt(5)
	v_mfma_f32_16x16x32_bf16 v[40:43], v[76:79], v[184:187], v[40:43]
	v_mfma_f32_16x16x32_bf16 v[16:19], v[80:83], v[184:187], v[16:19]
	v_mfma_f32_16x16x32_bf16 v[232:235], v[84:87], v[184:187], v[232:235]
	v_mfma_f32_16x16x32_bf16 v[104:107], v[88:91], v[184:187], v[104:107]
	ds_read_b128 v[184:187], v212 offset:0
	global_load_dwordx4 v[172:175], v67, s[92:93] offset:0
	s_waitcnt lgkmcnt(5)
	v_mfma_f32_16x16x32_bf16 v[44:47], v[76:79], v[192:195], v[44:47]
	v_mfma_f32_16x16x32_bf16 v[20:23], v[80:83], v[192:195], v[20:23]
	v_mfma_f32_16x16x32_bf16 v[236:239], v[84:87], v[192:195], v[236:239]
	v_mfma_f32_16x16x32_bf16 v[108:111], v[88:91], v[192:195], v[108:111]
	ds_read_b128 v[192:195], v212 offset:2048
	s_waitcnt lgkmcnt(5)
	v_mfma_f32_16x16x32_bf16 v[48:51], v[76:79], v[196:199], v[48:51]
	v_mfma_f32_16x16x32_bf16 v[0:3], v[80:83], v[196:199], v[0:3]
	v_mfma_f32_16x16x32_bf16 v[240:243], v[84:87], v[196:199], v[240:243]
	v_mfma_f32_16x16x32_bf16 v[112:115], v[88:91], v[196:199], v[112:115]
	ds_read_b128 v[196:199], v212 offset:4096
	s_waitcnt lgkmcnt(5)
	v_mfma_f32_16x16x32_bf16 v[52:55], v[76:79], v[200:203], v[52:55]
	v_mfma_f32_16x16x32_bf16 v[8:11], v[80:83], v[200:203], v[8:11]
	v_mfma_f32_16x16x32_bf16 v[248:251], v[84:87], v[200:203], v[248:251]
	v_mfma_f32_16x16x32_bf16 v[116:119], v[88:91], v[200:203], v[116:119]
	ds_read_b128 v[200:203], v212 offset:6144
	s_waitcnt lgkmcnt(5)
	v_mfma_f32_16x16x32_bf16 v[56:59], v[76:79], v[176:179], v[56:59]
	v_mfma_f32_16x16x32_bf16 v[24:27], v[80:83], v[176:179], v[24:27]
	v_mfma_f32_16x16x32_bf16 v[252:255], v[84:87], v[176:179], v[252:255]
	v_mfma_f32_16x16x32_bf16 v[120:123], v[88:91], v[176:179], v[120:123]
	ds_read_b128 v[176:179], v212 offset:8192
	s_waitcnt lgkmcnt(5)
	v_mfma_f32_16x16x32_bf16 v[60:63], v[76:79], v[180:183], v[60:63]
	v_mfma_f32_16x16x32_bf16 v[28:31], v[80:83], v[180:183], v[28:31]
	v_mfma_f32_16x16x32_bf16 v[92:95], v[84:87], v[180:183], v[92:95]
	v_mfma_f32_16x16x32_bf16 v[124:127], v[88:91], v[180:183], v[124:127]
	s_waitcnt vmcnt(8)
	s_barrier
	s_waitcnt vmcnt(12)
	ds_read_b128 v[180:183], v212 offset:10240
	global_load_dwordx4 v[76:79], v66, s[84:85] offset:1024
	s_waitcnt lgkmcnt(5)
	v_mfma_f32_16x16x32_bf16 v[32:35], v[140:143], v[184:187], v[32:35]
	v_mfma_f32_16x16x32_bf16 v[4:7], v[144:147], v[184:187], v[4:7]
	v_mfma_f32_16x16x32_bf16 v[188:191], v[148:151], v[184:187], v[188:191]
	v_mfma_f32_16x16x32_bf16 v[96:99], v[204:207], v[184:187], v[96:99]
	ds_read_b128 v[184:187], v212 offset:12288
	global_load_dwordx4 v[80:83], v67, s[84:85] offset:1024
	s_waitcnt lgkmcnt(5)
	v_mfma_f32_16x16x32_bf16 v[36:39], v[140:143], v[192:195], v[36:39]
	v_mfma_f32_16x16x32_bf16 v[12:15], v[144:147], v[192:195], v[12:15]
	v_mfma_f32_16x16x32_bf16 v[208:211], v[148:151], v[192:195], v[208:211]
	v_mfma_f32_16x16x32_bf16 v[100:103], v[204:207], v[192:195], v[100:103]
	ds_read_b128 v[192:195], v212 offset:14336
	global_load_dwordx4 v[84:87], v66, s[92:93] offset:1024
	s_waitcnt lgkmcnt(5)
	v_mfma_f32_16x16x32_bf16 v[40:43], v[140:143], v[196:199], v[40:43]
	v_mfma_f32_16x16x32_bf16 v[16:19], v[144:147], v[196:199], v[16:19]
	v_mfma_f32_16x16x32_bf16 v[232:235], v[148:151], v[196:199], v[232:235]
	v_mfma_f32_16x16x32_bf16 v[104:107], v[204:207], v[196:199], v[104:107]
	ds_read_b128 v[196:199], v75 offset:16384
	global_load_dwordx4 v[88:91], v67, s[92:93] offset:1024
	s_add_u32 s84, s84, 0x800
	s_addc_u32 s85, s85, 0
	s_add_u32 s92, s92, 0x800
	s_addc_u32 s93, s93, 0
	s_waitcnt lgkmcnt(5)
	v_mfma_f32_16x16x32_bf16 v[44:47], v[140:143], v[200:203], v[44:47]
	v_mfma_f32_16x16x32_bf16 v[20:23], v[144:147], v[200:203], v[20:23]
	v_mfma_f32_16x16x32_bf16 v[236:239], v[148:151], v[200:203], v[236:239]
	v_mfma_f32_16x16x32_bf16 v[108:111], v[204:207], v[200:203], v[108:111]
	ds_read_b128 v[200:203], v75 offset:18432
	s_add_u32 m0, s88, 49152
	s_nop 0
	global_load_lds_dwordx4 v68, s[86:87]
	s_waitcnt lgkmcnt(5)
	v_mfma_f32_16x16x32_bf16 v[48:51], v[140:143], v[176:179], v[48:51]
	v_mfma_f32_16x16x32_bf16 v[0:3], v[144:147], v[176:179], v[0:3]
	v_mfma_f32_16x16x32_bf16 v[240:243], v[148:151], v[176:179], v[240:243]
	v_mfma_f32_16x16x32_bf16 v[112:115], v[204:207], v[176:179], v[112:115]
	ds_read_b128 v[176:179], v75 offset:20480
	s_add_u32 m0, s88, 53248
	s_nop 0
	global_load_lds_dwordx4 v69, s[86:87]
	s_waitcnt lgkmcnt(5)
	v_mfma_f32_16x16x32_bf16 v[52:55], v[140:143], v[180:183], v[52:55]
	v_mfma_f32_16x16x32_bf16 v[8:11], v[144:147], v[180:183], v[8:11]
	v_mfma_f32_16x16x32_bf16 v[248:251], v[148:151], v[180:183], v[248:251]
	v_mfma_f32_16x16x32_bf16 v[116:119], v[204:207], v[180:183], v[116:119]
	ds_read_b128 v[180:183], v75 offset:22528
	s_add_u32 m0, s88, 57344
	s_nop 0
	global_load_lds_dwordx4 v71, s[86:87]
	s_waitcnt lgkmcnt(5)
	v_mfma_f32_16x16x32_bf16 v[56:59], v[140:143], v[184:187], v[56:59]
	v_mfma_f32_16x16x32_bf16 v[24:27], v[144:147], v[184:187], v[24:27]
	v_mfma_f32_16x16x32_bf16 v[252:255], v[148:151], v[184:187], v[252:255]
	v_mfma_f32_16x16x32_bf16 v[120:123], v[204:207], v[184:187], v[120:123]
	ds_read_b128 v[184:187], v75 offset:24576
	s_add_u32 m0, s88, 61440
	s_nop 0
	global_load_lds_dwordx4 v74, s[86:87]
	s_add_u32 s86, s86, 128
	s_addc_u32 s87, s87, 0
	s_waitcnt lgkmcnt(5)
	v_mfma_f32_16x16x32_bf16 v[60:63], v[140:143], v[192:195], v[60:63]
	v_mfma_f32_16x16x32_bf16 v[28:31], v[144:147], v[192:195], v[28:31]
	v_mfma_f32_16x16x32_bf16 v[92:95], v[148:151], v[192:195], v[92:95]
	v_mfma_f32_16x16x32_bf16 v[124:127], v[204:207], v[192:195], v[124:127]
	s_waitcnt vmcnt(8)
	ds_read_b128 v[192:195], v75 offset:26624
	global_load_dwordx4 v[140:143], v66, s[84:85] offset:0
	s_waitcnt lgkmcnt(5)
	v_mfma_f32_16x16x32_bf16 v[32:35], v[160:163], v[196:199], v[32:35]
	v_mfma_f32_16x16x32_bf16 v[4:7], v[164:167], v[196:199], v[4:7]
	v_mfma_f32_16x16x32_bf16 v[188:191], v[168:171], v[196:199], v[188:191]
	v_mfma_f32_16x16x32_bf16 v[96:99], v[172:175], v[196:199], v[96:99]
	ds_read_b128 v[196:199], v75 offset:28672
	global_load_dwordx4 v[144:147], v67, s[84:85] offset:0
	s_waitcnt lgkmcnt(5)
	v_mfma_f32_16x16x32_bf16 v[36:39], v[160:163], v[200:203], v[36:39]
	v_mfma_f32_16x16x32_bf16 v[12:15], v[164:167], v[200:203], v[12:15]
	v_mfma_f32_16x16x32_bf16 v[208:211], v[168:171], v[200:203], v[208:211]
	v_mfma_f32_16x16x32_bf16 v[100:103], v[172:175], v[200:203], v[100:103]
	ds_read_b128 v[200:203], v75 offset:30720
	global_load_dwordx4 v[148:151], v66, s[92:93] offset:0
	s_waitcnt lgkmcnt(5)
	v_mfma_f32_16x16x32_bf16 v[40:43], v[160:163], v[176:179], v[40:43]
	v_mfma_f32_16x16x32_bf16 v[16:19], v[164:167], v[176:179], v[16:19]
	v_mfma_f32_16x16x32_bf16 v[232:235], v[168:171], v[176:179], v[232:235]
	v_mfma_f32_16x16x32_bf16 v[104:107], v[172:175], v[176:179], v[104:107]
	ds_read_b128 v[176:179], v212 offset:16384
	global_load_dwordx4 v[204:207], v67, s[92:93] offset:0
	s_waitcnt lgkmcnt(5)
	v_mfma_f32_16x16x32_bf16 v[44:47], v[160:163], v[180:183], v[44:47]
	v_mfma_f32_16x16x32_bf16 v[20:23], v[164:167], v[180:183], v[20:23]
	v_mfma_f32_16x16x32_bf16 v[236:239], v[168:171], v[180:183], v[236:239]
	v_mfma_f32_16x16x32_bf16 v[108:111], v[172:175], v[180:183], v[108:111]
	ds_read_b128 v[180:183], v212 offset:18432
	s_waitcnt lgkmcnt(5)
	v_mfma_f32_16x16x32_bf16 v[48:51], v[160:163], v[184:187], v[48:51]
	v_mfma_f32_16x16x32_bf16 v[0:3], v[164:167], v[184:187], v[0:3]
	v_mfma_f32_16x16x32_bf16 v[240:243], v[168:171], v[184:187], v[240:243]
	v_mfma_f32_16x16x32_bf16 v[112:115], v[172:175], v[184:187], v[112:115]
	ds_read_b128 v[184:187], v212 offset:20480
	s_waitcnt lgkmcnt(5)
	v_mfma_f32_16x16x32_bf16 v[52:55], v[160:163], v[192:195], v[52:55]
	v_mfma_f32_16x16x32_bf16 v[8:11], v[164:167], v[192:195], v[8:11]
	v_mfma_f32_16x16x32_bf16 v[248:251], v[168:171], v[192:195], v[248:251]
	v_mfma_f32_16x16x32_bf16 v[116:119], v[172:175], v[192:195], v[116:119]
	ds_read_b128 v[192:195], v212 offset:22528
	s_waitcnt lgkmcnt(5)
	v_mfma_f32_16x16x32_bf16 v[56:59], v[160:163], v[196:199], v[56:59]
	v_mfma_f32_16x16x32_bf16 v[24:27], v[164:167], v[196:199], v[24:27]
	v_mfma_f32_16x16x32_bf16 v[252:255], v[168:171], v[196:199], v[252:255]
	v_mfma_f32_16x16x32_bf16 v[120:123], v[172:175], v[196:199], v[120:123]
	ds_read_b128 v[196:199], v212 offset:24576
	s_waitcnt lgkmcnt(5)
	v_mfma_f32_16x16x32_bf16 v[60:63], v[160:163], v[200:203], v[60:63]
	v_mfma_f32_16x16x32_bf16 v[28:31], v[164:167], v[200:203], v[28:31]
	v_mfma_f32_16x16x32_bf16 v[92:95], v[168:171], v[200:203], v[92:95]
	v_mfma_f32_16x16x32_bf16 v[124:127], v[172:175], v[200:203], v[124:127]
	s_waitcnt vmcnt(16)
	s_barrier
	s_waitcnt vmcnt(8)
	ds_read_b128 v[200:203], v212 offset:26624
	global_load_dwordx4 v[160:163], v66, s[84:85] offset:1024
	s_waitcnt lgkmcnt(5)
	v_mfma_f32_16x16x32_bf16 v[32:35], v[76:79], v[176:179], v[32:35]
	v_mfma_f32_16x16x32_bf16 v[4:7], v[80:83], v[176:179], v[4:7]
	v_mfma_f32_16x16x32_bf16 v[188:191], v[84:87], v[176:179], v[188:191]
	v_mfma_f32_16x16x32_bf16 v[96:99], v[88:91], v[176:179], v[96:99]
	ds_read_b128 v[176:179], v212 offset:28672
	global_load_dwordx4 v[164:167], v67, s[84:85] offset:1024
	s_waitcnt lgkmcnt(5)
	v_mfma_f32_16x16x32_bf16 v[36:39], v[76:79], v[180:183], v[36:39]
	v_mfma_f32_16x16x32_bf16 v[12:15], v[80:83], v[180:183], v[12:15]
	v_mfma_f32_16x16x32_bf16 v[208:211], v[84:87], v[180:183], v[208:211]
	v_mfma_f32_16x16x32_bf16 v[100:103], v[88:91], v[180:183], v[100:103]
	ds_read_b128 v[180:183], v212 offset:30720
	global_load_dwordx4 v[168:171], v66, s[92:93] offset:1024
	s_waitcnt lgkmcnt(5)
	v_mfma_f32_16x16x32_bf16 v[40:43], v[76:79], v[184:187], v[40:43]
	v_mfma_f32_16x16x32_bf16 v[16:19], v[80:83], v[184:187], v[16:19]
	v_mfma_f32_16x16x32_bf16 v[232:235], v[84:87], v[184:187], v[232:235]
	v_mfma_f32_16x16x32_bf16 v[104:107], v[88:91], v[184:187], v[104:107]
	ds_read_b128 v[184:187], v75 offset:32768
	global_load_dwordx4 v[172:175], v67, s[92:93] offset:1024
	s_add_u32 s84, s84, 0x800
	s_addc_u32 s85, s85, 0
	s_add_u32 s92, s92, 0x800
	s_addc_u32 s93, s93, 0
	s_waitcnt lgkmcnt(5)
	v_mfma_f32_16x16x32_bf16 v[44:47], v[76:79], v[192:195], v[44:47]
	v_mfma_f32_16x16x32_bf16 v[20:23], v[80:83], v[192:195], v[20:23]
	v_mfma_f32_16x16x32_bf16 v[236:239], v[84:87], v[192:195], v[236:239]
	v_mfma_f32_16x16x32_bf16 v[108:111], v[88:91], v[192:195], v[108:111]
	ds_read_b128 v[192:195], v75 offset:34816
	s_add_u32 m0, s88, 0
	s_nop 0
	global_load_lds_dwordx4 v68, s[86:87]
	s_waitcnt lgkmcnt(5)
	v_mfma_f32_16x16x32_bf16 v[48:51], v[76:79], v[196:199], v[48:51]
	v_mfma_f32_16x16x32_bf16 v[0:3], v[80:83], v[196:199], v[0:3]
	v_mfma_f32_16x16x32_bf16 v[240:243], v[84:87], v[196:199], v[240:243]
	v_mfma_f32_16x16x32_bf16 v[112:115], v[88:91], v[196:199], v[112:115]
	ds_read_b128 v[196:199], v75 offset:36864
	s_add_u32 m0, s88, 4096
	s_nop 0
	global_load_lds_dwordx4 v69, s[86:87]
	s_waitcnt lgkmcnt(5)
	v_mfma_f32_16x16x32_bf16 v[52:55], v[76:79], v[200:203], v[52:55]
	v_mfma_f32_16x16x32_bf16 v[8:11], v[80:83], v[200:203], v[8:11]
	v_mfma_f32_16x16x32_bf16 v[248:251], v[84:87], v[200:203], v[248:251]
	v_mfma_f32_16x16x32_bf16 v[116:119], v[88:91], v[200:203], v[116:119]
	ds_read_b128 v[200:203], v75 offset:38912
	s_add_u32 m0, s88, 8192
	s_nop 0
	global_load_lds_dwordx4 v71, s[86:87]
	s_waitcnt lgkmcnt(5)
	v_mfma_f32_16x16x32_bf16 v[56:59], v[76:79], v[176:179], v[56:59]
	v_mfma_f32_16x16x32_bf16 v[24:27], v[80:83], v[176:179], v[24:27]
	v_mfma_f32_16x16x32_bf16 v[252:255], v[84:87], v[176:179], v[252:255]
	v_mfma_f32_16x16x32_bf16 v[120:123], v[88:91], v[176:179], v[120:123]
	ds_read_b128 v[176:179], v75 offset:40960
	s_add_u32 m0, s88, 12288
	s_nop 0
	global_load_lds_dwordx4 v74, s[86:87]
	s_add_u32 s86, s86, 128
	s_addc_u32 s87, s87, 0
	s_waitcnt lgkmcnt(5)
	v_mfma_f32_16x16x32_bf16 v[60:63], v[76:79], v[180:183], v[60:63]
	v_mfma_f32_16x16x32_bf16 v[28:31], v[80:83], v[180:183], v[28:31]
	v_mfma_f32_16x16x32_bf16 v[92:95], v[84:87], v[180:183], v[92:95]
	v_mfma_f32_16x16x32_bf16 v[124:127], v[88:91], v[180:183], v[124:127]
	s_waitcnt vmcnt(8)
	ds_read_b128 v[180:183], v75 offset:43008
	global_load_dwordx4 v[76:79], v66, s[84:85] offset:0
	s_waitcnt lgkmcnt(5)
	v_mfma_f32_16x16x32_bf16 v[32:35], v[140:143], v[184:187], v[32:35]
	v_mfma_f32_16x16x32_bf16 v[4:7], v[144:147], v[184:187], v[4:7]
	v_mfma_f32_16x16x32_bf16 v[188:191], v[148:151], v[184:187], v[188:191]
	v_mfma_f32_16x16x32_bf16 v[96:99], v[204:207], v[184:187], v[96:99]
	ds_read_b128 v[184:187], v75 offset:45056
	global_load_dwordx4 v[80:83], v67, s[84:85] offset:0
	s_waitcnt lgkmcnt(5)
	v_mfma_f32_16x16x32_bf16 v[36:39], v[140:143], v[192:195], v[36:39]
	v_mfma_f32_16x16x32_bf16 v[12:15], v[144:147], v[192:195], v[12:15]
	v_mfma_f32_16x16x32_bf16 v[208:211], v[148:151], v[192:195], v[208:211]
	v_mfma_f32_16x16x32_bf16 v[100:103], v[204:207], v[192:195], v[100:103]
	ds_read_b128 v[192:195], v75 offset:47104
	global_load_dwordx4 v[84:87], v66, s[92:93] offset:0
	s_waitcnt lgkmcnt(5)
	v_mfma_f32_16x16x32_bf16 v[40:43], v[140:143], v[196:199], v[40:43]
	v_mfma_f32_16x16x32_bf16 v[16:19], v[144:147], v[196:199], v[16:19]
	v_mfma_f32_16x16x32_bf16 v[232:235], v[148:151], v[196:199], v[232:235]
	v_mfma_f32_16x16x32_bf16 v[104:107], v[204:207], v[196:199], v[104:107]
	ds_read_b128 v[196:199], v212 offset:32768
	global_load_dwordx4 v[88:91], v67, s[92:93] offset:0
	s_waitcnt lgkmcnt(5)
	v_mfma_f32_16x16x32_bf16 v[44:47], v[140:143], v[200:203], v[44:47]
	v_mfma_f32_16x16x32_bf16 v[20:23], v[144:147], v[200:203], v[20:23]
	v_mfma_f32_16x16x32_bf16 v[236:239], v[148:151], v[200:203], v[236:239]
	v_mfma_f32_16x16x32_bf16 v[108:111], v[204:207], v[200:203], v[108:111]
	ds_read_b128 v[200:203], v212 offset:34816
	s_waitcnt lgkmcnt(5)
	v_mfma_f32_16x16x32_bf16 v[48:51], v[140:143], v[176:179], v[48:51]
	v_mfma_f32_16x16x32_bf16 v[0:3], v[144:147], v[176:179], v[0:3]
	v_mfma_f32_16x16x32_bf16 v[240:243], v[148:151], v[176:179], v[240:243]
	v_mfma_f32_16x16x32_bf16 v[112:115], v[204:207], v[176:179], v[112:115]
	ds_read_b128 v[176:179], v212 offset:36864
	s_waitcnt lgkmcnt(5)
	v_mfma_f32_16x16x32_bf16 v[52:55], v[140:143], v[180:183], v[52:55]
	v_mfma_f32_16x16x32_bf16 v[8:11], v[144:147], v[180:183], v[8:11]
	v_mfma_f32_16x16x32_bf16 v[248:251], v[148:151], v[180:183], v[248:251]
	v_mfma_f32_16x16x32_bf16 v[116:119], v[204:207], v[180:183], v[116:119]
	ds_read_b128 v[180:183], v212 offset:38912
	s_waitcnt lgkmcnt(5)
	v_mfma_f32_16x16x32_bf16 v[56:59], v[140:143], v[184:187], v[56:59]
	v_mfma_f32_16x16x32_bf16 v[24:27], v[144:147], v[184:187], v[24:27]
	v_mfma_f32_16x16x32_bf16 v[252:255], v[148:151], v[184:187], v[252:255]
	v_mfma_f32_16x16x32_bf16 v[120:123], v[204:207], v[184:187], v[120:123]
	ds_read_b128 v[184:187], v212 offset:40960
	s_waitcnt lgkmcnt(5)
	v_mfma_f32_16x16x32_bf16 v[60:63], v[140:143], v[192:195], v[60:63]
	v_mfma_f32_16x16x32_bf16 v[28:31], v[144:147], v[192:195], v[28:31]
	v_mfma_f32_16x16x32_bf16 v[92:95], v[148:151], v[192:195], v[92:95]
	v_mfma_f32_16x16x32_bf16 v[124:127], v[204:207], v[192:195], v[124:127]
	s_waitcnt vmcnt(16)
	s_barrier
	s_waitcnt vmcnt(8)
	ds_read_b128 v[192:195], v212 offset:43008
	global_load_dwordx4 v[140:143], v66, s[84:85] offset:1024
	s_waitcnt lgkmcnt(5)
	v_mfma_f32_16x16x32_bf16 v[32:35], v[160:163], v[196:199], v[32:35]
	v_mfma_f32_16x16x32_bf16 v[4:7], v[164:167], v[196:199], v[4:7]
	v_mfma_f32_16x16x32_bf16 v[188:191], v[168:171], v[196:199], v[188:191]
	v_mfma_f32_16x16x32_bf16 v[96:99], v[172:175], v[196:199], v[96:99]
	ds_read_b128 v[196:199], v212 offset:45056
	global_load_dwordx4 v[144:147], v67, s[84:85] offset:1024
	s_waitcnt lgkmcnt(5)
	v_mfma_f32_16x16x32_bf16 v[36:39], v[160:163], v[200:203], v[36:39]
	v_mfma_f32_16x16x32_bf16 v[12:15], v[164:167], v[200:203], v[12:15]
	v_mfma_f32_16x16x32_bf16 v[208:211], v[168:171], v[200:203], v[208:211]
	v_mfma_f32_16x16x32_bf16 v[100:103], v[172:175], v[200:203], v[100:103]
	ds_read_b128 v[200:203], v212 offset:47104
	global_load_dwordx4 v[148:151], v66, s[92:93] offset:1024
	s_waitcnt lgkmcnt(5)
	v_mfma_f32_16x16x32_bf16 v[40:43], v[160:163], v[176:179], v[40:43]
	v_mfma_f32_16x16x32_bf16 v[16:19], v[164:167], v[176:179], v[16:19]
	v_mfma_f32_16x16x32_bf16 v[232:235], v[168:171], v[176:179], v[232:235]
	v_mfma_f32_16x16x32_bf16 v[104:107], v[172:175], v[176:179], v[104:107]
	ds_read_b128 v[176:179], v75 offset:49152
	global_load_dwordx4 v[204:207], v67, s[92:93] offset:1024
	s_add_u32 s84, s84, 0x800
	s_addc_u32 s85, s85, 0
	s_add_u32 s92, s92, 0x800
	s_addc_u32 s93, s93, 0
	s_waitcnt lgkmcnt(5)
	v_mfma_f32_16x16x32_bf16 v[44:47], v[160:163], v[180:183], v[44:47]
	v_mfma_f32_16x16x32_bf16 v[20:23], v[164:167], v[180:183], v[20:23]
	v_mfma_f32_16x16x32_bf16 v[236:239], v[168:171], v[180:183], v[236:239]
	v_mfma_f32_16x16x32_bf16 v[108:111], v[172:175], v[180:183], v[108:111]
	ds_read_b128 v[180:183], v75 offset:51200
	s_add_u32 m0, s88, 16384
	s_nop 0
	global_load_lds_dwordx4 v68, s[86:87]
	s_waitcnt lgkmcnt(5)
	v_mfma_f32_16x16x32_bf16 v[48:51], v[160:163], v[184:187], v[48:51]
	v_mfma_f32_16x16x32_bf16 v[0:3], v[164:167], v[184:187], v[0:3]
	v_mfma_f32_16x16x32_bf16 v[240:243], v[168:171], v[184:187], v[240:243]
	v_mfma_f32_16x16x32_bf16 v[112:115], v[172:175], v[184:187], v[112:115]
	ds_read_b128 v[184:187], v75 offset:53248
	s_add_u32 m0, s88, 20480
	s_nop 0
	global_load_lds_dwordx4 v69, s[86:87]
	s_waitcnt lgkmcnt(5)
	v_mfma_f32_16x16x32_bf16 v[52:55], v[160:163], v[192:195], v[52:55]
	v_mfma_f32_16x16x32_bf16 v[8:11], v[164:167], v[192:195], v[8:11]
	v_mfma_f32_16x16x32_bf16 v[248:251], v[168:171], v[192:195], v[248:251]
	v_mfma_f32_16x16x32_bf16 v[116:119], v[172:175], v[192:195], v[116:119]
	ds_read_b128 v[192:195], v75 offset:55296
	s_add_u32 m0, s88, 24576
	s_nop 0
	global_load_lds_dwordx4 v71, s[86:87]
	s_waitcnt lgkmcnt(5)
	v_mfma_f32_16x16x32_bf16 v[56:59], v[160:163], v[196:199], v[56:59]
	v_mfma_f32_16x16x32_bf16 v[24:27], v[164:167], v[196:199], v[24:27]
	v_mfma_f32_16x16x32_bf16 v[252:255], v[168:171], v[196:199], v[252:255]
	v_mfma_f32_16x16x32_bf16 v[120:123], v[172:175], v[196:199], v[120:123]
	ds_read_b128 v[196:199], v75 offset:57344
	s_add_u32 m0, s88, 28672
	s_nop 0
	global_load_lds_dwordx4 v74, s[86:87]
	s_add_u32 s86, s86, 128
	s_addc_u32 s87, s87, 0
	s_waitcnt lgkmcnt(5)
	v_mfma_f32_16x16x32_bf16 v[60:63], v[160:163], v[200:203], v[60:63]
	v_mfma_f32_16x16x32_bf16 v[28:31], v[164:167], v[200:203], v[28:31]
	v_mfma_f32_16x16x32_bf16 v[92:95], v[168:171], v[200:203], v[92:95]
	v_mfma_f32_16x16x32_bf16 v[124:127], v[172:175], v[200:203], v[124:127]
	s_waitcnt vmcnt(8)
	ds_read_b128 v[200:203], v75 offset:59392
	global_load_dwordx4 v[160:163], v66, s[84:85] offset:0
	s_waitcnt lgkmcnt(5)
	v_mfma_f32_16x16x32_bf16 v[32:35], v[76:79], v[176:179], v[32:35]
	v_mfma_f32_16x16x32_bf16 v[4:7], v[80:83], v[176:179], v[4:7]
	v_mfma_f32_16x16x32_bf16 v[188:191], v[84:87], v[176:179], v[188:191]
	v_mfma_f32_16x16x32_bf16 v[96:99], v[88:91], v[176:179], v[96:99]
	ds_read_b128 v[176:179], v75 offset:61440
	global_load_dwordx4 v[164:167], v67, s[84:85] offset:0
	s_waitcnt lgkmcnt(5)
	v_mfma_f32_16x16x32_bf16 v[36:39], v[76:79], v[180:183], v[36:39]
	v_mfma_f32_16x16x32_bf16 v[12:15], v[80:83], v[180:183], v[12:15]
	v_mfma_f32_16x16x32_bf16 v[208:211], v[84:87], v[180:183], v[208:211]
	v_mfma_f32_16x16x32_bf16 v[100:103], v[88:91], v[180:183], v[100:103]
	ds_read_b128 v[180:183], v75 offset:63488
	global_load_dwordx4 v[168:171], v66, s[92:93] offset:0
	s_waitcnt lgkmcnt(5)
	v_mfma_f32_16x16x32_bf16 v[40:43], v[76:79], v[184:187], v[40:43]
	v_mfma_f32_16x16x32_bf16 v[16:19], v[80:83], v[184:187], v[16:19]
	v_mfma_f32_16x16x32_bf16 v[232:235], v[84:87], v[184:187], v[232:235]
	v_mfma_f32_16x16x32_bf16 v[104:107], v[88:91], v[184:187], v[104:107]
	ds_read_b128 v[184:187], v212 offset:49152
	global_load_dwordx4 v[172:175], v67, s[92:93] offset:0
	s_waitcnt lgkmcnt(5)
	v_mfma_f32_16x16x32_bf16 v[44:47], v[76:79], v[192:195], v[44:47]
	v_mfma_f32_16x16x32_bf16 v[20:23], v[80:83], v[192:195], v[20:23]
	v_mfma_f32_16x16x32_bf16 v[236:239], v[84:87], v[192:195], v[236:239]
	v_mfma_f32_16x16x32_bf16 v[108:111], v[88:91], v[192:195], v[108:111]
	ds_read_b128 v[192:195], v212 offset:51200
	s_waitcnt lgkmcnt(5)
	v_mfma_f32_16x16x32_bf16 v[48:51], v[76:79], v[196:199], v[48:51]
	v_mfma_f32_16x16x32_bf16 v[0:3], v[80:83], v[196:199], v[0:3]
	v_mfma_f32_16x16x32_bf16 v[240:243], v[84:87], v[196:199], v[240:243]
	v_mfma_f32_16x16x32_bf16 v[112:115], v[88:91], v[196:199], v[112:115]
	ds_read_b128 v[196:199], v212 offset:53248
	s_waitcnt lgkmcnt(5)
	v_mfma_f32_16x16x32_bf16 v[52:55], v[76:79], v[200:203], v[52:55]
	v_mfma_f32_16x16x32_bf16 v[8:11], v[80:83], v[200:203], v[8:11]
	v_mfma_f32_16x16x32_bf16 v[248:251], v[84:87], v[200:203], v[248:251]
	v_mfma_f32_16x16x32_bf16 v[116:119], v[88:91], v[200:203], v[116:119]
	ds_read_b128 v[200:203], v212 offset:55296
	s_waitcnt lgkmcnt(5)
	v_mfma_f32_16x16x32_bf16 v[56:59], v[76:79], v[176:179], v[56:59]
	v_mfma_f32_16x16x32_bf16 v[24:27], v[80:83], v[176:179], v[24:27]
	v_mfma_f32_16x16x32_bf16 v[252:255], v[84:87], v[176:179], v[252:255]
	v_mfma_f32_16x16x32_bf16 v[120:123], v[88:91], v[176:179], v[120:123]
	ds_read_b128 v[176:179], v212 offset:57344
	s_waitcnt lgkmcnt(5)
	v_mfma_f32_16x16x32_bf16 v[60:63], v[76:79], v[180:183], v[60:63]
	v_mfma_f32_16x16x32_bf16 v[28:31], v[80:83], v[180:183], v[28:31]
	v_mfma_f32_16x16x32_bf16 v[92:95], v[84:87], v[180:183], v[92:95]
	v_mfma_f32_16x16x32_bf16 v[124:127], v[88:91], v[180:183], v[124:127]
	s_waitcnt vmcnt(16)
	s_barrier
	s_waitcnt vmcnt(8)
	ds_read_b128 v[180:183], v212 offset:59392
	global_load_dwordx4 v[76:79], v66, s[84:85] offset:1024
	s_waitcnt lgkmcnt(5)
	v_mfma_f32_16x16x32_bf16 v[32:35], v[140:143], v[184:187], v[32:35]
	v_mfma_f32_16x16x32_bf16 v[4:7], v[144:147], v[184:187], v[4:7]
	v_mfma_f32_16x16x32_bf16 v[188:191], v[148:151], v[184:187], v[188:191]
	v_mfma_f32_16x16x32_bf16 v[96:99], v[204:207], v[184:187], v[96:99]
	ds_read_b128 v[184:187], v212 offset:61440
	global_load_dwordx4 v[80:83], v67, s[84:85] offset:1024
	s_waitcnt lgkmcnt(5)
	v_mfma_f32_16x16x32_bf16 v[36:39], v[140:143], v[192:195], v[36:39]
	v_mfma_f32_16x16x32_bf16 v[12:15], v[144:147], v[192:195], v[12:15]
	v_mfma_f32_16x16x32_bf16 v[208:211], v[148:151], v[192:195], v[208:211]
	v_mfma_f32_16x16x32_bf16 v[100:103], v[204:207], v[192:195], v[100:103]
	ds_read_b128 v[192:195], v212 offset:63488
	global_load_dwordx4 v[84:87], v66, s[92:93] offset:1024
	s_waitcnt lgkmcnt(5)
	v_mfma_f32_16x16x32_bf16 v[40:43], v[140:143], v[196:199], v[40:43]
	v_mfma_f32_16x16x32_bf16 v[16:19], v[144:147], v[196:199], v[16:19]
	v_mfma_f32_16x16x32_bf16 v[232:235], v[148:151], v[196:199], v[232:235]
	v_mfma_f32_16x16x32_bf16 v[104:107], v[204:207], v[196:199], v[104:107]
	ds_read_b128 v[196:199], v75 offset:0
	global_load_dwordx4 v[88:91], v67, s[92:93] offset:1024
	s_add_u32 s84, s84, 0x800
	s_addc_u32 s85, s85, 0
	s_add_u32 s92, s92, 0x800
	s_addc_u32 s93, s93, 0
	s_waitcnt lgkmcnt(5)
	v_mfma_f32_16x16x32_bf16 v[44:47], v[140:143], v[200:203], v[44:47]
	v_mfma_f32_16x16x32_bf16 v[20:23], v[144:147], v[200:203], v[20:23]
	v_mfma_f32_16x16x32_bf16 v[236:239], v[148:151], v[200:203], v[236:239]
	v_mfma_f32_16x16x32_bf16 v[108:111], v[204:207], v[200:203], v[108:111]
	ds_read_b128 v[200:203], v75 offset:2048
	s_add_u32 m0, s88, 32768
	s_nop 0
	global_load_lds_dwordx4 v68, s[86:87]
	s_waitcnt lgkmcnt(5)
	v_mfma_f32_16x16x32_bf16 v[48:51], v[140:143], v[176:179], v[48:51]
	v_mfma_f32_16x16x32_bf16 v[0:3], v[144:147], v[176:179], v[0:3]
	v_mfma_f32_16x16x32_bf16 v[240:243], v[148:151], v[176:179], v[240:243]
	v_mfma_f32_16x16x32_bf16 v[112:115], v[204:207], v[176:179], v[112:115]
	ds_read_b128 v[176:179], v75 offset:4096
	s_add_u32 m0, s88, 36864
	s_nop 0
	global_load_lds_dwordx4 v69, s[86:87]
	s_waitcnt lgkmcnt(5)
	v_mfma_f32_16x16x32_bf16 v[52:55], v[140:143], v[180:183], v[52:55]
	v_mfma_f32_16x16x32_bf16 v[8:11], v[144:147], v[180:183], v[8:11]
	v_mfma_f32_16x16x32_bf16 v[248:251], v[148:151], v[180:183], v[248:251]
	v_mfma_f32_16x16x32_bf16 v[116:119], v[204:207], v[180:183], v[116:119]
	ds_read_b128 v[180:183], v75 offset:6144
	s_add_u32 m0, s88, 40960
	s_nop 0
	global_load_lds_dwordx4 v71, s[86:87]
	s_waitcnt lgkmcnt(5)
	v_mfma_f32_16x16x32_bf16 v[56:59], v[140:143], v[184:187], v[56:59]
	v_mfma_f32_16x16x32_bf16 v[24:27], v[144:147], v[184:187], v[24:27]
	v_mfma_f32_16x16x32_bf16 v[252:255], v[148:151], v[184:187], v[252:255]
	v_mfma_f32_16x16x32_bf16 v[120:123], v[204:207], v[184:187], v[120:123]
	ds_read_b128 v[184:187], v75 offset:8192
	s_add_u32 m0, s88, 45056
	s_nop 0
	global_load_lds_dwordx4 v74, s[86:87]
	s_add_u32 s86, s86, 128
	s_addc_u32 s87, s87, 0
	s_waitcnt lgkmcnt(5)
	v_mfma_f32_16x16x32_bf16 v[60:63], v[140:143], v[192:195], v[60:63]
	v_mfma_f32_16x16x32_bf16 v[28:31], v[144:147], v[192:195], v[28:31]
	v_mfma_f32_16x16x32_bf16 v[92:95], v[148:151], v[192:195], v[92:95]
	v_mfma_f32_16x16x32_bf16 v[124:127], v[204:207], v[192:195], v[124:127]
	s_waitcnt vmcnt(8)
	ds_read_b128 v[192:195], v75 offset:10240
	global_load_dwordx4 v[140:143], v66, s[84:85] offset:0
	s_waitcnt lgkmcnt(5)
	v_mfma_f32_16x16x32_bf16 v[32:35], v[160:163], v[196:199], v[32:35]
	v_mfma_f32_16x16x32_bf16 v[4:7], v[164:167], v[196:199], v[4:7]
	v_mfma_f32_16x16x32_bf16 v[188:191], v[168:171], v[196:199], v[188:191]
	v_mfma_f32_16x16x32_bf16 v[96:99], v[172:175], v[196:199], v[96:99]
	ds_read_b128 v[196:199], v75 offset:12288
	global_load_dwordx4 v[144:147], v67, s[84:85] offset:0
	s_waitcnt lgkmcnt(5)
	v_mfma_f32_16x16x32_bf16 v[36:39], v[160:163], v[200:203], v[36:39]
	v_mfma_f32_16x16x32_bf16 v[12:15], v[164:167], v[200:203], v[12:15]
	v_mfma_f32_16x16x32_bf16 v[208:211], v[168:171], v[200:203], v[208:211]
	v_mfma_f32_16x16x32_bf16 v[100:103], v[172:175], v[200:203], v[100:103]
	ds_read_b128 v[200:203], v75 offset:14336
	global_load_dwordx4 v[148:151], v66, s[92:93] offset:0
	s_waitcnt lgkmcnt(5)
	v_mfma_f32_16x16x32_bf16 v[40:43], v[160:163], v[176:179], v[40:43]
	v_mfma_f32_16x16x32_bf16 v[16:19], v[164:167], v[176:179], v[16:19]
	v_mfma_f32_16x16x32_bf16 v[232:235], v[168:171], v[176:179], v[232:235]
	v_mfma_f32_16x16x32_bf16 v[104:107], v[172:175], v[176:179], v[104:107]
	ds_read_b128 v[176:179], v212 offset:0
	global_load_dwordx4 v[204:207], v67, s[92:93] offset:0
	s_waitcnt lgkmcnt(5)
	v_mfma_f32_16x16x32_bf16 v[44:47], v[160:163], v[180:183], v[44:47]
	v_mfma_f32_16x16x32_bf16 v[20:23], v[164:167], v[180:183], v[20:23]
	v_mfma_f32_16x16x32_bf16 v[236:239], v[168:171], v[180:183], v[236:239]
	v_mfma_f32_16x16x32_bf16 v[108:111], v[172:175], v[180:183], v[108:111]
	ds_read_b128 v[180:183], v212 offset:2048
	s_waitcnt lgkmcnt(5)
	v_mfma_f32_16x16x32_bf16 v[48:51], v[160:163], v[184:187], v[48:51]
	v_mfma_f32_16x16x32_bf16 v[0:3], v[164:167], v[184:187], v[0:3]
	v_mfma_f32_16x16x32_bf16 v[240:243], v[168:171], v[184:187], v[240:243]
	v_mfma_f32_16x16x32_bf16 v[112:115], v[172:175], v[184:187], v[112:115]
	ds_read_b128 v[184:187], v212 offset:4096
	s_waitcnt lgkmcnt(5)
	v_mfma_f32_16x16x32_bf16 v[52:55], v[160:163], v[192:195], v[52:55]
	v_mfma_f32_16x16x32_bf16 v[8:11], v[164:167], v[192:195], v[8:11]
	v_mfma_f32_16x16x32_bf16 v[248:251], v[168:171], v[192:195], v[248:251]
	v_mfma_f32_16x16x32_bf16 v[116:119], v[172:175], v[192:195], v[116:119]
	ds_read_b128 v[192:195], v212 offset:6144
	s_waitcnt lgkmcnt(5)
	v_mfma_f32_16x16x32_bf16 v[56:59], v[160:163], v[196:199], v[56:59]
	v_mfma_f32_16x16x32_bf16 v[24:27], v[164:167], v[196:199], v[24:27]
	v_mfma_f32_16x16x32_bf16 v[252:255], v[168:171], v[196:199], v[252:255]
	v_mfma_f32_16x16x32_bf16 v[120:123], v[172:175], v[196:199], v[120:123]
	ds_read_b128 v[196:199], v212 offset:8192
	s_waitcnt lgkmcnt(5)
	v_mfma_f32_16x16x32_bf16 v[60:63], v[160:163], v[200:203], v[60:63]
	v_mfma_f32_16x16x32_bf16 v[28:31], v[164:167], v[200:203], v[28:31]
	v_mfma_f32_16x16x32_bf16 v[92:95], v[168:171], v[200:203], v[92:95]
	v_mfma_f32_16x16x32_bf16 v[124:127], v[172:175], v[200:203], v[124:127]
	s_waitcnt vmcnt(16)
	s_barrier
	s_waitcnt vmcnt(8)
	ds_read_b128 v[200:203], v212 offset:10240
	global_load_dwordx4 v[160:163], v66, s[84:85] offset:1024
	s_waitcnt lgkmcnt(5)
	v_mfma_f32_16x16x32_bf16 v[32:35], v[76:79], v[176:179], v[32:35]
	v_mfma_f32_16x16x32_bf16 v[4:7], v[80:83], v[176:179], v[4:7]
	v_mfma_f32_16x16x32_bf16 v[188:191], v[84:87], v[176:179], v[188:191]
	v_mfma_f32_16x16x32_bf16 v[96:99], v[88:91], v[176:179], v[96:99]
	ds_read_b128 v[176:179], v212 offset:12288
	global_load_dwordx4 v[164:167], v67, s[84:85] offset:1024
	s_waitcnt lgkmcnt(5)
	v_mfma_f32_16x16x32_bf16 v[36:39], v[76:79], v[180:183], v[36:39]
	v_mfma_f32_16x16x32_bf16 v[12:15], v[80:83], v[180:183], v[12:15]
	v_mfma_f32_16x16x32_bf16 v[208:211], v[84:87], v[180:183], v[208:211]
	v_mfma_f32_16x16x32_bf16 v[100:103], v[88:91], v[180:183], v[100:103]
	ds_read_b128 v[180:183], v212 offset:14336
	global_load_dwordx4 v[168:171], v66, s[92:93] offset:1024
	s_waitcnt lgkmcnt(5)
	v_mfma_f32_16x16x32_bf16 v[40:43], v[76:79], v[184:187], v[40:43]
	v_mfma_f32_16x16x32_bf16 v[16:19], v[80:83], v[184:187], v[16:19]
	v_mfma_f32_16x16x32_bf16 v[232:235], v[84:87], v[184:187], v[232:235]
	v_mfma_f32_16x16x32_bf16 v[104:107], v[88:91], v[184:187], v[104:107]
	ds_read_b128 v[184:187], v75 offset:16384
	global_load_dwordx4 v[172:175], v67, s[92:93] offset:1024
	s_add_u32 s84, s84, 0x800
	s_addc_u32 s85, s85, 0
	s_add_u32 s92, s92, 0x800
	s_addc_u32 s93, s93, 0
	s_waitcnt lgkmcnt(5)
	v_mfma_f32_16x16x32_bf16 v[44:47], v[76:79], v[192:195], v[44:47]
	v_mfma_f32_16x16x32_bf16 v[20:23], v[80:83], v[192:195], v[20:23]
	v_mfma_f32_16x16x32_bf16 v[236:239], v[84:87], v[192:195], v[236:239]
	v_mfma_f32_16x16x32_bf16 v[108:111], v[88:91], v[192:195], v[108:111]
	ds_read_b128 v[192:195], v75 offset:18432
	s_add_u32 m0, s88, 49152
	s_nop 0
	global_load_lds_dwordx4 v68, s[86:87]
	s_waitcnt lgkmcnt(5)
	v_mfma_f32_16x16x32_bf16 v[48:51], v[76:79], v[196:199], v[48:51]
	v_mfma_f32_16x16x32_bf16 v[0:3], v[80:83], v[196:199], v[0:3]
	v_mfma_f32_16x16x32_bf16 v[240:243], v[84:87], v[196:199], v[240:243]
	v_mfma_f32_16x16x32_bf16 v[112:115], v[88:91], v[196:199], v[112:115]
	ds_read_b128 v[196:199], v75 offset:20480
	s_add_u32 m0, s88, 53248
	s_nop 0
	global_load_lds_dwordx4 v69, s[86:87]
	s_waitcnt lgkmcnt(5)
	v_mfma_f32_16x16x32_bf16 v[52:55], v[76:79], v[200:203], v[52:55]
	v_mfma_f32_16x16x32_bf16 v[8:11], v[80:83], v[200:203], v[8:11]
	v_mfma_f32_16x16x32_bf16 v[248:251], v[84:87], v[200:203], v[248:251]
	v_mfma_f32_16x16x32_bf16 v[116:119], v[88:91], v[200:203], v[116:119]
	ds_read_b128 v[200:203], v75 offset:22528
	s_add_u32 m0, s88, 57344
	s_nop 0
	global_load_lds_dwordx4 v71, s[86:87]
	s_waitcnt lgkmcnt(5)
	v_mfma_f32_16x16x32_bf16 v[56:59], v[76:79], v[176:179], v[56:59]
	v_mfma_f32_16x16x32_bf16 v[24:27], v[80:83], v[176:179], v[24:27]
	v_mfma_f32_16x16x32_bf16 v[252:255], v[84:87], v[176:179], v[252:255]
	v_mfma_f32_16x16x32_bf16 v[120:123], v[88:91], v[176:179], v[120:123]
	ds_read_b128 v[176:179], v75 offset:24576
	s_add_u32 m0, s88, 61440
	s_nop 0
	global_load_lds_dwordx4 v74, s[86:87]
	s_add_u32 s86, s86, 128
	s_addc_u32 s87, s87, 0
	s_waitcnt lgkmcnt(5)
	v_mfma_f32_16x16x32_bf16 v[60:63], v[76:79], v[180:183], v[60:63]
	v_mfma_f32_16x16x32_bf16 v[28:31], v[80:83], v[180:183], v[28:31]
	v_mfma_f32_16x16x32_bf16 v[92:95], v[84:87], v[180:183], v[92:95]
	v_mfma_f32_16x16x32_bf16 v[124:127], v[88:91], v[180:183], v[124:127]
	s_waitcnt vmcnt(8)
	ds_read_b128 v[180:183], v75 offset:26624
	global_load_dwordx4 v[76:79], v66, s[84:85] offset:0
	s_waitcnt lgkmcnt(5)
	v_mfma_f32_16x16x32_bf16 v[32:35], v[140:143], v[184:187], v[32:35]
	v_mfma_f32_16x16x32_bf16 v[4:7], v[144:147], v[184:187], v[4:7]
	v_mfma_f32_16x16x32_bf16 v[188:191], v[148:151], v[184:187], v[188:191]
	v_mfma_f32_16x16x32_bf16 v[96:99], v[204:207], v[184:187], v[96:99]
	ds_read_b128 v[184:187], v75 offset:28672
	global_load_dwordx4 v[80:83], v67, s[84:85] offset:0
	s_waitcnt lgkmcnt(5)
	v_mfma_f32_16x16x32_bf16 v[36:39], v[140:143], v[192:195], v[36:39]
	v_mfma_f32_16x16x32_bf16 v[12:15], v[144:147], v[192:195], v[12:15]
	v_mfma_f32_16x16x32_bf16 v[208:211], v[148:151], v[192:195], v[208:211]
	v_mfma_f32_16x16x32_bf16 v[100:103], v[204:207], v[192:195], v[100:103]
	ds_read_b128 v[192:195], v75 offset:30720
	global_load_dwordx4 v[84:87], v66, s[92:93] offset:0
	s_waitcnt lgkmcnt(5)
	v_mfma_f32_16x16x32_bf16 v[40:43], v[140:143], v[196:199], v[40:43]
	v_mfma_f32_16x16x32_bf16 v[16:19], v[144:147], v[196:199], v[16:19]
	v_mfma_f32_16x16x32_bf16 v[232:235], v[148:151], v[196:199], v[232:235]
	v_mfma_f32_16x16x32_bf16 v[104:107], v[204:207], v[196:199], v[104:107]
	ds_read_b128 v[196:199], v212 offset:16384
	global_load_dwordx4 v[88:91], v67, s[92:93] offset:0
	s_waitcnt lgkmcnt(5)
	v_mfma_f32_16x16x32_bf16 v[44:47], v[140:143], v[200:203], v[44:47]
	v_mfma_f32_16x16x32_bf16 v[20:23], v[144:147], v[200:203], v[20:23]
	v_mfma_f32_16x16x32_bf16 v[236:239], v[148:151], v[200:203], v[236:239]
	v_mfma_f32_16x16x32_bf16 v[108:111], v[204:207], v[200:203], v[108:111]
	ds_read_b128 v[200:203], v212 offset:18432
	s_waitcnt lgkmcnt(5)
	v_mfma_f32_16x16x32_bf16 v[48:51], v[140:143], v[176:179], v[48:51]
	v_mfma_f32_16x16x32_bf16 v[0:3], v[144:147], v[176:179], v[0:3]
	v_mfma_f32_16x16x32_bf16 v[240:243], v[148:151], v[176:179], v[240:243]
	v_mfma_f32_16x16x32_bf16 v[112:115], v[204:207], v[176:179], v[112:115]
	ds_read_b128 v[176:179], v212 offset:20480
	s_waitcnt lgkmcnt(5)
	v_mfma_f32_16x16x32_bf16 v[52:55], v[140:143], v[180:183], v[52:55]
	v_mfma_f32_16x16x32_bf16 v[8:11], v[144:147], v[180:183], v[8:11]
	v_mfma_f32_16x16x32_bf16 v[248:251], v[148:151], v[180:183], v[248:251]
	v_mfma_f32_16x16x32_bf16 v[116:119], v[204:207], v[180:183], v[116:119]
	ds_read_b128 v[180:183], v212 offset:22528
	s_waitcnt lgkmcnt(5)
	v_mfma_f32_16x16x32_bf16 v[56:59], v[140:143], v[184:187], v[56:59]
	v_mfma_f32_16x16x32_bf16 v[24:27], v[144:147], v[184:187], v[24:27]
	v_mfma_f32_16x16x32_bf16 v[252:255], v[148:151], v[184:187], v[252:255]
	v_mfma_f32_16x16x32_bf16 v[120:123], v[204:207], v[184:187], v[120:123]
	ds_read_b128 v[184:187], v212 offset:24576
	s_waitcnt lgkmcnt(5)
	v_mfma_f32_16x16x32_bf16 v[60:63], v[140:143], v[192:195], v[60:63]
	v_mfma_f32_16x16x32_bf16 v[28:31], v[144:147], v[192:195], v[28:31]
	v_mfma_f32_16x16x32_bf16 v[92:95], v[148:151], v[192:195], v[92:95]
	v_mfma_f32_16x16x32_bf16 v[124:127], v[204:207], v[192:195], v[124:127]
	s_waitcnt vmcnt(16)
	s_barrier
	s_waitcnt vmcnt(8)
	ds_read_b128 v[192:195], v212 offset:26624
	global_load_dwordx4 v[140:143], v66, s[84:85] offset:1024
	s_waitcnt lgkmcnt(5)
	v_mfma_f32_16x16x32_bf16 v[32:35], v[160:163], v[196:199], v[32:35]
	v_mfma_f32_16x16x32_bf16 v[4:7], v[164:167], v[196:199], v[4:7]
	v_mfma_f32_16x16x32_bf16 v[188:191], v[168:171], v[196:199], v[188:191]
	v_mfma_f32_16x16x32_bf16 v[96:99], v[172:175], v[196:199], v[96:99]
	ds_read_b128 v[196:199], v212 offset:28672
	global_load_dwordx4 v[144:147], v67, s[84:85] offset:1024
	s_waitcnt lgkmcnt(5)
	v_mfma_f32_16x16x32_bf16 v[36:39], v[160:163], v[200:203], v[36:39]
	v_mfma_f32_16x16x32_bf16 v[12:15], v[164:167], v[200:203], v[12:15]
	v_mfma_f32_16x16x32_bf16 v[208:211], v[168:171], v[200:203], v[208:211]
	v_mfma_f32_16x16x32_bf16 v[100:103], v[172:175], v[200:203], v[100:103]
	ds_read_b128 v[200:203], v212 offset:30720
	global_load_dwordx4 v[148:151], v66, s[92:93] offset:1024
	s_waitcnt lgkmcnt(5)
	v_mfma_f32_16x16x32_bf16 v[40:43], v[160:163], v[176:179], v[40:43]
	v_mfma_f32_16x16x32_bf16 v[16:19], v[164:167], v[176:179], v[16:19]
	v_mfma_f32_16x16x32_bf16 v[232:235], v[168:171], v[176:179], v[232:235]
	v_mfma_f32_16x16x32_bf16 v[104:107], v[172:175], v[176:179], v[104:107]
	ds_read_b128 v[176:179], v75 offset:32768
	global_load_dwordx4 v[204:207], v67, s[92:93] offset:1024
	s_add_u32 s84, s84, 0x800
	s_addc_u32 s85, s85, 0
	s_add_u32 s92, s92, 0x800
	s_addc_u32 s93, s93, 0
	s_waitcnt lgkmcnt(5)
	v_mfma_f32_16x16x32_bf16 v[44:47], v[160:163], v[180:183], v[44:47]
	v_mfma_f32_16x16x32_bf16 v[20:23], v[164:167], v[180:183], v[20:23]
	v_mfma_f32_16x16x32_bf16 v[236:239], v[168:171], v[180:183], v[236:239]
	v_mfma_f32_16x16x32_bf16 v[108:111], v[172:175], v[180:183], v[108:111]
	ds_read_b128 v[180:183], v75 offset:34816
	s_add_u32 m0, s88, 0
	s_nop 0
	global_load_lds_dwordx4 v68, s[86:87]
	s_waitcnt lgkmcnt(5)
	v_mfma_f32_16x16x32_bf16 v[48:51], v[160:163], v[184:187], v[48:51]
	v_mfma_f32_16x16x32_bf16 v[0:3], v[164:167], v[184:187], v[0:3]
	v_mfma_f32_16x16x32_bf16 v[240:243], v[168:171], v[184:187], v[240:243]
	v_mfma_f32_16x16x32_bf16 v[112:115], v[172:175], v[184:187], v[112:115]
	ds_read_b128 v[184:187], v75 offset:36864
	s_add_u32 m0, s88, 4096
	s_nop 0
	global_load_lds_dwordx4 v69, s[86:87]
	s_waitcnt lgkmcnt(5)
	v_mfma_f32_16x16x32_bf16 v[52:55], v[160:163], v[192:195], v[52:55]
	v_mfma_f32_16x16x32_bf16 v[8:11], v[164:167], v[192:195], v[8:11]
	v_mfma_f32_16x16x32_bf16 v[248:251], v[168:171], v[192:195], v[248:251]
	v_mfma_f32_16x16x32_bf16 v[116:119], v[172:175], v[192:195], v[116:119]
	ds_read_b128 v[192:195], v75 offset:38912
	s_add_u32 m0, s88, 8192
	s_nop 0
	global_load_lds_dwordx4 v71, s[86:87]
	s_waitcnt lgkmcnt(5)
	v_mfma_f32_16x16x32_bf16 v[56:59], v[160:163], v[196:199], v[56:59]
	v_mfma_f32_16x16x32_bf16 v[24:27], v[164:167], v[196:199], v[24:27]
	v_mfma_f32_16x16x32_bf16 v[252:255], v[168:171], v[196:199], v[252:255]
	v_mfma_f32_16x16x32_bf16 v[120:123], v[172:175], v[196:199], v[120:123]
	ds_read_b128 v[196:199], v75 offset:40960
	s_add_u32 m0, s88, 12288
	s_nop 0
	global_load_lds_dwordx4 v74, s[86:87]
	s_add_u32 s86, s86, 128
	s_addc_u32 s87, s87, 0
	s_waitcnt lgkmcnt(5)
	v_mfma_f32_16x16x32_bf16 v[60:63], v[160:163], v[200:203], v[60:63]
	v_mfma_f32_16x16x32_bf16 v[28:31], v[164:167], v[200:203], v[28:31]
	v_mfma_f32_16x16x32_bf16 v[92:95], v[168:171], v[200:203], v[92:95]
	v_mfma_f32_16x16x32_bf16 v[124:127], v[172:175], v[200:203], v[124:127]
	s_waitcnt vmcnt(8)
	ds_read_b128 v[200:203], v75 offset:43008
	global_load_dwordx4 v[160:163], v66, s[84:85] offset:0
	s_waitcnt lgkmcnt(5)
	v_mfma_f32_16x16x32_bf16 v[32:35], v[76:79], v[176:179], v[32:35]
	v_mfma_f32_16x16x32_bf16 v[4:7], v[80:83], v[176:179], v[4:7]
	v_mfma_f32_16x16x32_bf16 v[188:191], v[84:87], v[176:179], v[188:191]
	v_mfma_f32_16x16x32_bf16 v[96:99], v[88:91], v[176:179], v[96:99]
	ds_read_b128 v[176:179], v75 offset:45056
	global_load_dwordx4 v[164:167], v67, s[84:85] offset:0
	s_waitcnt lgkmcnt(5)
	v_mfma_f32_16x16x32_bf16 v[36:39], v[76:79], v[180:183], v[36:39]
	v_mfma_f32_16x16x32_bf16 v[12:15], v[80:83], v[180:183], v[12:15]
	v_mfma_f32_16x16x32_bf16 v[208:211], v[84:87], v[180:183], v[208:211]
	v_mfma_f32_16x16x32_bf16 v[100:103], v[88:91], v[180:183], v[100:103]
	ds_read_b128 v[180:183], v75 offset:47104
	global_load_dwordx4 v[168:171], v66, s[92:93] offset:0
	s_waitcnt lgkmcnt(5)
	v_mfma_f32_16x16x32_bf16 v[40:43], v[76:79], v[184:187], v[40:43]
	v_mfma_f32_16x16x32_bf16 v[16:19], v[80:83], v[184:187], v[16:19]
	v_mfma_f32_16x16x32_bf16 v[232:235], v[84:87], v[184:187], v[232:235]
	v_mfma_f32_16x16x32_bf16 v[104:107], v[88:91], v[184:187], v[104:107]
	ds_read_b128 v[184:187], v212 offset:32768
	global_load_dwordx4 v[172:175], v67, s[92:93] offset:0
	s_waitcnt lgkmcnt(5)
	v_mfma_f32_16x16x32_bf16 v[44:47], v[76:79], v[192:195], v[44:47]
	v_mfma_f32_16x16x32_bf16 v[20:23], v[80:83], v[192:195], v[20:23]
	v_mfma_f32_16x16x32_bf16 v[236:239], v[84:87], v[192:195], v[236:239]
	v_mfma_f32_16x16x32_bf16 v[108:111], v[88:91], v[192:195], v[108:111]
	ds_read_b128 v[192:195], v212 offset:34816
	s_waitcnt lgkmcnt(5)
	v_mfma_f32_16x16x32_bf16 v[48:51], v[76:79], v[196:199], v[48:51]
	v_mfma_f32_16x16x32_bf16 v[0:3], v[80:83], v[196:199], v[0:3]
	v_mfma_f32_16x16x32_bf16 v[240:243], v[84:87], v[196:199], v[240:243]
	v_mfma_f32_16x16x32_bf16 v[112:115], v[88:91], v[196:199], v[112:115]
	ds_read_b128 v[196:199], v212 offset:36864
	s_waitcnt lgkmcnt(5)
	v_mfma_f32_16x16x32_bf16 v[52:55], v[76:79], v[200:203], v[52:55]
	v_mfma_f32_16x16x32_bf16 v[8:11], v[80:83], v[200:203], v[8:11]
	v_mfma_f32_16x16x32_bf16 v[248:251], v[84:87], v[200:203], v[248:251]
	v_mfma_f32_16x16x32_bf16 v[116:119], v[88:91], v[200:203], v[116:119]
	ds_read_b128 v[200:203], v212 offset:38912
	s_waitcnt lgkmcnt(5)
	v_mfma_f32_16x16x32_bf16 v[56:59], v[76:79], v[176:179], v[56:59]
	v_mfma_f32_16x16x32_bf16 v[24:27], v[80:83], v[176:179], v[24:27]
	v_mfma_f32_16x16x32_bf16 v[252:255], v[84:87], v[176:179], v[252:255]
	v_mfma_f32_16x16x32_bf16 v[120:123], v[88:91], v[176:179], v[120:123]
	ds_read_b128 v[176:179], v212 offset:40960
	s_waitcnt lgkmcnt(5)
	v_mfma_f32_16x16x32_bf16 v[60:63], v[76:79], v[180:183], v[60:63]
	v_mfma_f32_16x16x32_bf16 v[28:31], v[80:83], v[180:183], v[28:31]
	v_mfma_f32_16x16x32_bf16 v[92:95], v[84:87], v[180:183], v[92:95]
	v_mfma_f32_16x16x32_bf16 v[124:127], v[88:91], v[180:183], v[124:127]
	s_waitcnt vmcnt(16)
	s_barrier
	s_waitcnt vmcnt(8)
	ds_read_b128 v[180:183], v212 offset:43008
	global_load_dwordx4 v[76:79], v66, s[84:85] offset:1024
	s_waitcnt lgkmcnt(5)
	v_mfma_f32_16x16x32_bf16 v[32:35], v[140:143], v[184:187], v[32:35]
	v_mfma_f32_16x16x32_bf16 v[4:7], v[144:147], v[184:187], v[4:7]
	v_mfma_f32_16x16x32_bf16 v[188:191], v[148:151], v[184:187], v[188:191]
	v_mfma_f32_16x16x32_bf16 v[96:99], v[204:207], v[184:187], v[96:99]
	ds_read_b128 v[184:187], v212 offset:45056
	global_load_dwordx4 v[80:83], v67, s[84:85] offset:1024
	s_waitcnt lgkmcnt(5)
	v_mfma_f32_16x16x32_bf16 v[36:39], v[140:143], v[192:195], v[36:39]
	v_mfma_f32_16x16x32_bf16 v[12:15], v[144:147], v[192:195], v[12:15]
	v_mfma_f32_16x16x32_bf16 v[208:211], v[148:151], v[192:195], v[208:211]
	v_mfma_f32_16x16x32_bf16 v[100:103], v[204:207], v[192:195], v[100:103]
	ds_read_b128 v[192:195], v212 offset:47104
	global_load_dwordx4 v[84:87], v66, s[92:93] offset:1024
	s_waitcnt lgkmcnt(5)
	v_mfma_f32_16x16x32_bf16 v[40:43], v[140:143], v[196:199], v[40:43]
	v_mfma_f32_16x16x32_bf16 v[16:19], v[144:147], v[196:199], v[16:19]
	v_mfma_f32_16x16x32_bf16 v[232:235], v[148:151], v[196:199], v[232:235]
	v_mfma_f32_16x16x32_bf16 v[104:107], v[204:207], v[196:199], v[104:107]
	ds_read_b128 v[196:199], v75 offset:49152
	global_load_dwordx4 v[88:91], v67, s[92:93] offset:1024
	s_add_u32 s84, s84, 0x800
	s_addc_u32 s85, s85, 0
	s_add_u32 s92, s92, 0x800
	s_addc_u32 s93, s93, 0
	s_waitcnt lgkmcnt(5)
	v_mfma_f32_16x16x32_bf16 v[44:47], v[140:143], v[200:203], v[44:47]
	v_mfma_f32_16x16x32_bf16 v[20:23], v[144:147], v[200:203], v[20:23]
	v_mfma_f32_16x16x32_bf16 v[236:239], v[148:151], v[200:203], v[236:239]
	v_mfma_f32_16x16x32_bf16 v[108:111], v[204:207], v[200:203], v[108:111]
	ds_read_b128 v[200:203], v75 offset:51200
	s_add_u32 m0, s88, 16384
	s_nop 0
	global_load_lds_dwordx4 v68, s[86:87]
	s_waitcnt lgkmcnt(5)
	v_mfma_f32_16x16x32_bf16 v[48:51], v[140:143], v[176:179], v[48:51]
	v_mfma_f32_16x16x32_bf16 v[0:3], v[144:147], v[176:179], v[0:3]
	v_mfma_f32_16x16x32_bf16 v[240:243], v[148:151], v[176:179], v[240:243]
	v_mfma_f32_16x16x32_bf16 v[112:115], v[204:207], v[176:179], v[112:115]
	ds_read_b128 v[176:179], v75 offset:53248
	s_add_u32 m0, s88, 20480
	s_nop 0
	global_load_lds_dwordx4 v69, s[86:87]
	s_waitcnt lgkmcnt(5)
	v_mfma_f32_16x16x32_bf16 v[52:55], v[140:143], v[180:183], v[52:55]
	v_mfma_f32_16x16x32_bf16 v[8:11], v[144:147], v[180:183], v[8:11]
	v_mfma_f32_16x16x32_bf16 v[248:251], v[148:151], v[180:183], v[248:251]
	v_mfma_f32_16x16x32_bf16 v[116:119], v[204:207], v[180:183], v[116:119]
	ds_read_b128 v[180:183], v75 offset:55296
	s_add_u32 m0, s88, 24576
	s_nop 0
	global_load_lds_dwordx4 v71, s[86:87]
	s_waitcnt lgkmcnt(5)
	v_mfma_f32_16x16x32_bf16 v[56:59], v[140:143], v[184:187], v[56:59]
	v_mfma_f32_16x16x32_bf16 v[24:27], v[144:147], v[184:187], v[24:27]
	v_mfma_f32_16x16x32_bf16 v[252:255], v[148:151], v[184:187], v[252:255]
	v_mfma_f32_16x16x32_bf16 v[120:123], v[204:207], v[184:187], v[120:123]
	ds_read_b128 v[184:187], v75 offset:57344
	s_add_u32 m0, s88, 28672
	s_nop 0
	global_load_lds_dwordx4 v74, s[86:87]
	s_add_u32 s86, s86, 128
	s_addc_u32 s87, s87, 0
	s_waitcnt lgkmcnt(5)
	v_mfma_f32_16x16x32_bf16 v[60:63], v[140:143], v[192:195], v[60:63]
	v_mfma_f32_16x16x32_bf16 v[28:31], v[144:147], v[192:195], v[28:31]
	v_mfma_f32_16x16x32_bf16 v[92:95], v[148:151], v[192:195], v[92:95]
	v_mfma_f32_16x16x32_bf16 v[124:127], v[204:207], v[192:195], v[124:127]
	s_waitcnt vmcnt(8)
	ds_read_b128 v[192:195], v75 offset:59392
	global_load_dwordx4 v[140:143], v66, s[84:85] offset:0
	s_waitcnt lgkmcnt(5)
	v_mfma_f32_16x16x32_bf16 v[32:35], v[160:163], v[196:199], v[32:35]
	v_mfma_f32_16x16x32_bf16 v[4:7], v[164:167], v[196:199], v[4:7]
	v_mfma_f32_16x16x32_bf16 v[188:191], v[168:171], v[196:199], v[188:191]
	v_mfma_f32_16x16x32_bf16 v[96:99], v[172:175], v[196:199], v[96:99]
	ds_read_b128 v[196:199], v75 offset:61440
	global_load_dwordx4 v[144:147], v67, s[84:85] offset:0
	s_waitcnt lgkmcnt(5)
	v_mfma_f32_16x16x32_bf16 v[36:39], v[160:163], v[200:203], v[36:39]
	v_mfma_f32_16x16x32_bf16 v[12:15], v[164:167], v[200:203], v[12:15]
	v_mfma_f32_16x16x32_bf16 v[208:211], v[168:171], v[200:203], v[208:211]
	v_mfma_f32_16x16x32_bf16 v[100:103], v[172:175], v[200:203], v[100:103]
	ds_read_b128 v[200:203], v75 offset:63488
	global_load_dwordx4 v[148:151], v66, s[92:93] offset:0
	s_waitcnt lgkmcnt(5)
	v_mfma_f32_16x16x32_bf16 v[40:43], v[160:163], v[176:179], v[40:43]
	v_mfma_f32_16x16x32_bf16 v[16:19], v[164:167], v[176:179], v[16:19]
	v_mfma_f32_16x16x32_bf16 v[232:235], v[168:171], v[176:179], v[232:235]
	v_mfma_f32_16x16x32_bf16 v[104:107], v[172:175], v[176:179], v[104:107]
	ds_read_b128 v[176:179], v212 offset:49152
	global_load_dwordx4 v[204:207], v67, s[92:93] offset:0
	s_waitcnt lgkmcnt(5)
	v_mfma_f32_16x16x32_bf16 v[44:47], v[160:163], v[180:183], v[44:47]
	v_mfma_f32_16x16x32_bf16 v[20:23], v[164:167], v[180:183], v[20:23]
	v_mfma_f32_16x16x32_bf16 v[236:239], v[168:171], v[180:183], v[236:239]
	v_mfma_f32_16x16x32_bf16 v[108:111], v[172:175], v[180:183], v[108:111]
	ds_read_b128 v[180:183], v212 offset:51200
	s_waitcnt lgkmcnt(5)
	v_mfma_f32_16x16x32_bf16 v[48:51], v[160:163], v[184:187], v[48:51]
	v_mfma_f32_16x16x32_bf16 v[0:3], v[164:167], v[184:187], v[0:3]
	v_mfma_f32_16x16x32_bf16 v[240:243], v[168:171], v[184:187], v[240:243]
	v_mfma_f32_16x16x32_bf16 v[112:115], v[172:175], v[184:187], v[112:115]
	ds_read_b128 v[184:187], v212 offset:53248
	s_waitcnt lgkmcnt(5)
	v_mfma_f32_16x16x32_bf16 v[52:55], v[160:163], v[192:195], v[52:55]
	v_mfma_f32_16x16x32_bf16 v[8:11], v[164:167], v[192:195], v[8:11]
	v_mfma_f32_16x16x32_bf16 v[248:251], v[168:171], v[192:195], v[248:251]
	v_mfma_f32_16x16x32_bf16 v[116:119], v[172:175], v[192:195], v[116:119]
	ds_read_b128 v[192:195], v212 offset:55296
	s_waitcnt lgkmcnt(5)
	v_mfma_f32_16x16x32_bf16 v[56:59], v[160:163], v[196:199], v[56:59]
	v_mfma_f32_16x16x32_bf16 v[24:27], v[164:167], v[196:199], v[24:27]
	v_mfma_f32_16x16x32_bf16 v[252:255], v[168:171], v[196:199], v[252:255]
	v_mfma_f32_16x16x32_bf16 v[120:123], v[172:175], v[196:199], v[120:123]
	ds_read_b128 v[196:199], v212 offset:57344
	s_waitcnt lgkmcnt(5)
	v_mfma_f32_16x16x32_bf16 v[60:63], v[160:163], v[200:203], v[60:63]
	v_mfma_f32_16x16x32_bf16 v[28:31], v[164:167], v[200:203], v[28:31]
	v_mfma_f32_16x16x32_bf16 v[92:95], v[168:171], v[200:203], v[92:95]
	v_mfma_f32_16x16x32_bf16 v[124:127], v[172:175], v[200:203], v[124:127]
	s_waitcnt vmcnt(16)
	s_barrier
	s_waitcnt vmcnt(8)
	ds_read_b128 v[200:203], v212 offset:59392
	global_load_dwordx4 v[160:163], v66, s[84:85] offset:1024
	s_waitcnt lgkmcnt(5)
	v_mfma_f32_16x16x32_bf16 v[32:35], v[76:79], v[176:179], v[32:35]
	v_mfma_f32_16x16x32_bf16 v[4:7], v[80:83], v[176:179], v[4:7]
	v_mfma_f32_16x16x32_bf16 v[188:191], v[84:87], v[176:179], v[188:191]
	v_mfma_f32_16x16x32_bf16 v[96:99], v[88:91], v[176:179], v[96:99]
	ds_read_b128 v[176:179], v212 offset:61440
	global_load_dwordx4 v[164:167], v67, s[84:85] offset:1024
	s_waitcnt lgkmcnt(5)
	v_mfma_f32_16x16x32_bf16 v[36:39], v[76:79], v[180:183], v[36:39]
	v_mfma_f32_16x16x32_bf16 v[12:15], v[80:83], v[180:183], v[12:15]
	v_mfma_f32_16x16x32_bf16 v[208:211], v[84:87], v[180:183], v[208:211]
	v_mfma_f32_16x16x32_bf16 v[100:103], v[88:91], v[180:183], v[100:103]
	ds_read_b128 v[180:183], v212 offset:63488
	global_load_dwordx4 v[168:171], v66, s[92:93] offset:1024
	s_waitcnt lgkmcnt(5)
	v_mfma_f32_16x16x32_bf16 v[40:43], v[76:79], v[184:187], v[40:43]
	v_mfma_f32_16x16x32_bf16 v[16:19], v[80:83], v[184:187], v[16:19]
	v_mfma_f32_16x16x32_bf16 v[232:235], v[84:87], v[184:187], v[232:235]
	v_mfma_f32_16x16x32_bf16 v[104:107], v[88:91], v[184:187], v[104:107]
	ds_read_b128 v[184:187], v75 offset:0
	global_load_dwordx4 v[172:175], v67, s[92:93] offset:1024
	s_add_u32 s84, s84, 0x800
	s_addc_u32 s85, s85, 0
	s_add_u32 s92, s92, 0x800
	s_addc_u32 s93, s93, 0
	s_waitcnt lgkmcnt(5)
	v_mfma_f32_16x16x32_bf16 v[44:47], v[76:79], v[192:195], v[44:47]
	v_mfma_f32_16x16x32_bf16 v[20:23], v[80:83], v[192:195], v[20:23]
	v_mfma_f32_16x16x32_bf16 v[236:239], v[84:87], v[192:195], v[236:239]
	v_mfma_f32_16x16x32_bf16 v[108:111], v[88:91], v[192:195], v[108:111]
	ds_read_b128 v[192:195], v75 offset:2048
	s_add_u32 m0, s88, 32768
	s_nop 0
	global_load_lds_dwordx4 v68, s[86:87]
	s_waitcnt lgkmcnt(5)
	v_mfma_f32_16x16x32_bf16 v[48:51], v[76:79], v[196:199], v[48:51]
	v_mfma_f32_16x16x32_bf16 v[0:3], v[80:83], v[196:199], v[0:3]
	v_mfma_f32_16x16x32_bf16 v[240:243], v[84:87], v[196:199], v[240:243]
	v_mfma_f32_16x16x32_bf16 v[112:115], v[88:91], v[196:199], v[112:115]
	ds_read_b128 v[196:199], v75 offset:4096
	s_add_u32 m0, s88, 36864
	s_nop 0
	global_load_lds_dwordx4 v69, s[86:87]
	s_waitcnt lgkmcnt(5)
	v_mfma_f32_16x16x32_bf16 v[52:55], v[76:79], v[200:203], v[52:55]
	v_mfma_f32_16x16x32_bf16 v[8:11], v[80:83], v[200:203], v[8:11]
	v_mfma_f32_16x16x32_bf16 v[248:251], v[84:87], v[200:203], v[248:251]
	v_mfma_f32_16x16x32_bf16 v[116:119], v[88:91], v[200:203], v[116:119]
	ds_read_b128 v[200:203], v75 offset:6144
	s_add_u32 m0, s88, 40960
	s_nop 0
	global_load_lds_dwordx4 v71, s[86:87]
	s_waitcnt lgkmcnt(5)
	v_mfma_f32_16x16x32_bf16 v[56:59], v[76:79], v[176:179], v[56:59]
	v_mfma_f32_16x16x32_bf16 v[24:27], v[80:83], v[176:179], v[24:27]
	v_mfma_f32_16x16x32_bf16 v[252:255], v[84:87], v[176:179], v[252:255]
	v_mfma_f32_16x16x32_bf16 v[120:123], v[88:91], v[176:179], v[120:123]
	ds_read_b128 v[176:179], v75 offset:8192
	s_add_u32 m0, s88, 45056
	s_nop 0
	global_load_lds_dwordx4 v74, s[86:87]
	s_add_u32 s86, s86, 128
	s_addc_u32 s87, s87, 0
	s_waitcnt lgkmcnt(5)
	v_mfma_f32_16x16x32_bf16 v[60:63], v[76:79], v[180:183], v[60:63]
	v_mfma_f32_16x16x32_bf16 v[28:31], v[80:83], v[180:183], v[28:31]
	v_mfma_f32_16x16x32_bf16 v[92:95], v[84:87], v[180:183], v[92:95]
	v_mfma_f32_16x16x32_bf16 v[124:127], v[88:91], v[180:183], v[124:127]
	s_waitcnt vmcnt(8)
	ds_read_b128 v[180:183], v75 offset:10240
	global_load_dwordx4 v[76:79], v66, s[84:85] offset:0
	s_waitcnt lgkmcnt(5)
	v_mfma_f32_16x16x32_bf16 v[32:35], v[140:143], v[184:187], v[32:35]
	v_mfma_f32_16x16x32_bf16 v[4:7], v[144:147], v[184:187], v[4:7]
	v_mfma_f32_16x16x32_bf16 v[188:191], v[148:151], v[184:187], v[188:191]
	v_mfma_f32_16x16x32_bf16 v[96:99], v[204:207], v[184:187], v[96:99]
	ds_read_b128 v[184:187], v75 offset:12288
	global_load_dwordx4 v[80:83], v67, s[84:85] offset:0
	s_waitcnt lgkmcnt(5)
	v_mfma_f32_16x16x32_bf16 v[36:39], v[140:143], v[192:195], v[36:39]
	v_mfma_f32_16x16x32_bf16 v[12:15], v[144:147], v[192:195], v[12:15]
	v_mfma_f32_16x16x32_bf16 v[208:211], v[148:151], v[192:195], v[208:211]
	v_mfma_f32_16x16x32_bf16 v[100:103], v[204:207], v[192:195], v[100:103]
	ds_read_b128 v[192:195], v75 offset:14336
	global_load_dwordx4 v[84:87], v66, s[92:93] offset:0
	s_waitcnt lgkmcnt(5)
	v_mfma_f32_16x16x32_bf16 v[40:43], v[140:143], v[196:199], v[40:43]
	v_mfma_f32_16x16x32_bf16 v[16:19], v[144:147], v[196:199], v[16:19]
	v_mfma_f32_16x16x32_bf16 v[232:235], v[148:151], v[196:199], v[232:235]
	v_mfma_f32_16x16x32_bf16 v[104:107], v[204:207], v[196:199], v[104:107]
	ds_read_b128 v[196:199], v212 offset:0
	global_load_dwordx4 v[88:91], v67, s[92:93] offset:0
	s_waitcnt lgkmcnt(5)
	v_mfma_f32_16x16x32_bf16 v[44:47], v[140:143], v[200:203], v[44:47]
	v_mfma_f32_16x16x32_bf16 v[20:23], v[144:147], v[200:203], v[20:23]
	v_mfma_f32_16x16x32_bf16 v[236:239], v[148:151], v[200:203], v[236:239]
	v_mfma_f32_16x16x32_bf16 v[108:111], v[204:207], v[200:203], v[108:111]
	ds_read_b128 v[200:203], v212 offset:2048
	s_waitcnt lgkmcnt(5)
	v_mfma_f32_16x16x32_bf16 v[48:51], v[140:143], v[176:179], v[48:51]
	v_mfma_f32_16x16x32_bf16 v[0:3], v[144:147], v[176:179], v[0:3]
	v_mfma_f32_16x16x32_bf16 v[240:243], v[148:151], v[176:179], v[240:243]
	v_mfma_f32_16x16x32_bf16 v[112:115], v[204:207], v[176:179], v[112:115]
	ds_read_b128 v[176:179], v212 offset:4096
	s_waitcnt lgkmcnt(5)
	v_mfma_f32_16x16x32_bf16 v[52:55], v[140:143], v[180:183], v[52:55]
	v_mfma_f32_16x16x32_bf16 v[8:11], v[144:147], v[180:183], v[8:11]
	v_mfma_f32_16x16x32_bf16 v[248:251], v[148:151], v[180:183], v[248:251]
	v_mfma_f32_16x16x32_bf16 v[116:119], v[204:207], v[180:183], v[116:119]
	ds_read_b128 v[180:183], v212 offset:6144
	s_waitcnt lgkmcnt(5)
	v_mfma_f32_16x16x32_bf16 v[56:59], v[140:143], v[184:187], v[56:59]
	v_mfma_f32_16x16x32_bf16 v[24:27], v[144:147], v[184:187], v[24:27]
	v_mfma_f32_16x16x32_bf16 v[252:255], v[148:151], v[184:187], v[252:255]
	v_mfma_f32_16x16x32_bf16 v[120:123], v[204:207], v[184:187], v[120:123]
	ds_read_b128 v[184:187], v212 offset:8192
	s_waitcnt lgkmcnt(5)
	v_mfma_f32_16x16x32_bf16 v[60:63], v[140:143], v[192:195], v[60:63]
	v_mfma_f32_16x16x32_bf16 v[28:31], v[144:147], v[192:195], v[28:31]
	v_mfma_f32_16x16x32_bf16 v[92:95], v[148:151], v[192:195], v[92:95]
	v_mfma_f32_16x16x32_bf16 v[124:127], v[204:207], v[192:195], v[124:127]
	s_waitcnt vmcnt(16)
	s_barrier
	s_waitcnt vmcnt(8)
	ds_read_b128 v[192:195], v212 offset:10240
	global_load_dwordx4 v[140:143], v66, s[84:85] offset:1024
	s_waitcnt lgkmcnt(5)
	v_mfma_f32_16x16x32_bf16 v[32:35], v[160:163], v[196:199], v[32:35]
	v_mfma_f32_16x16x32_bf16 v[4:7], v[164:167], v[196:199], v[4:7]
	v_mfma_f32_16x16x32_bf16 v[188:191], v[168:171], v[196:199], v[188:191]
	v_mfma_f32_16x16x32_bf16 v[96:99], v[172:175], v[196:199], v[96:99]
	ds_read_b128 v[196:199], v212 offset:12288
	global_load_dwordx4 v[144:147], v67, s[84:85] offset:1024
	s_waitcnt lgkmcnt(5)
	v_mfma_f32_16x16x32_bf16 v[36:39], v[160:163], v[200:203], v[36:39]
	v_mfma_f32_16x16x32_bf16 v[12:15], v[164:167], v[200:203], v[12:15]
	v_mfma_f32_16x16x32_bf16 v[208:211], v[168:171], v[200:203], v[208:211]
	v_mfma_f32_16x16x32_bf16 v[100:103], v[172:175], v[200:203], v[100:103]
	ds_read_b128 v[200:203], v212 offset:14336
	global_load_dwordx4 v[148:151], v66, s[92:93] offset:1024
	s_waitcnt lgkmcnt(5)
	v_mfma_f32_16x16x32_bf16 v[40:43], v[160:163], v[176:179], v[40:43]
	v_mfma_f32_16x16x32_bf16 v[16:19], v[164:167], v[176:179], v[16:19]
	v_mfma_f32_16x16x32_bf16 v[232:235], v[168:171], v[176:179], v[232:235]
	v_mfma_f32_16x16x32_bf16 v[104:107], v[172:175], v[176:179], v[104:107]
	ds_read_b128 v[176:179], v75 offset:16384
	global_load_dwordx4 v[204:207], v67, s[92:93] offset:1024
	s_add_u32 s84, s84, 0x800
	s_addc_u32 s85, s85, 0
	s_add_u32 s92, s92, 0x800
	s_addc_u32 s93, s93, 0
	s_waitcnt lgkmcnt(5)
	v_mfma_f32_16x16x32_bf16 v[44:47], v[160:163], v[180:183], v[44:47]
	v_mfma_f32_16x16x32_bf16 v[20:23], v[164:167], v[180:183], v[20:23]
	v_mfma_f32_16x16x32_bf16 v[236:239], v[168:171], v[180:183], v[236:239]
	v_mfma_f32_16x16x32_bf16 v[108:111], v[172:175], v[180:183], v[108:111]
	ds_read_b128 v[180:183], v75 offset:18432
	s_add_u32 m0, s88, 49152
	s_nop 0
	global_load_lds_dwordx4 v68, s[86:87]
	s_waitcnt lgkmcnt(5)
	v_mfma_f32_16x16x32_bf16 v[48:51], v[160:163], v[184:187], v[48:51]
	v_mfma_f32_16x16x32_bf16 v[0:3], v[164:167], v[184:187], v[0:3]
	v_mfma_f32_16x16x32_bf16 v[240:243], v[168:171], v[184:187], v[240:243]
	v_mfma_f32_16x16x32_bf16 v[112:115], v[172:175], v[184:187], v[112:115]
	ds_read_b128 v[184:187], v75 offset:20480
	s_add_u32 m0, s88, 53248
	s_nop 0
	global_load_lds_dwordx4 v69, s[86:87]
	s_waitcnt lgkmcnt(5)
	v_mfma_f32_16x16x32_bf16 v[52:55], v[160:163], v[192:195], v[52:55]
	v_mfma_f32_16x16x32_bf16 v[8:11], v[164:167], v[192:195], v[8:11]
	v_mfma_f32_16x16x32_bf16 v[248:251], v[168:171], v[192:195], v[248:251]
	v_mfma_f32_16x16x32_bf16 v[116:119], v[172:175], v[192:195], v[116:119]
	ds_read_b128 v[192:195], v75 offset:22528
	s_add_u32 m0, s88, 57344
	s_nop 0
	global_load_lds_dwordx4 v71, s[86:87]
	s_waitcnt lgkmcnt(5)
	v_mfma_f32_16x16x32_bf16 v[56:59], v[160:163], v[196:199], v[56:59]
	v_mfma_f32_16x16x32_bf16 v[24:27], v[164:167], v[196:199], v[24:27]
	v_mfma_f32_16x16x32_bf16 v[252:255], v[168:171], v[196:199], v[252:255]
	v_mfma_f32_16x16x32_bf16 v[120:123], v[172:175], v[196:199], v[120:123]
	ds_read_b128 v[196:199], v75 offset:24576
	s_add_u32 m0, s88, 61440
	s_nop 0
	global_load_lds_dwordx4 v74, s[86:87]
	s_add_u32 s86, s86, 128
	s_addc_u32 s87, s87, 0
	s_waitcnt lgkmcnt(5)
	v_mfma_f32_16x16x32_bf16 v[60:63], v[160:163], v[200:203], v[60:63]
	v_mfma_f32_16x16x32_bf16 v[28:31], v[164:167], v[200:203], v[28:31]
	v_mfma_f32_16x16x32_bf16 v[92:95], v[168:171], v[200:203], v[92:95]
	v_mfma_f32_16x16x32_bf16 v[124:127], v[172:175], v[200:203], v[124:127]
	s_waitcnt vmcnt(8)
	ds_read_b128 v[200:203], v75 offset:26624
	global_load_dwordx4 v[160:163], v66, s[84:85] offset:0
	s_waitcnt lgkmcnt(5)
	v_mfma_f32_16x16x32_bf16 v[32:35], v[76:79], v[176:179], v[32:35]
	v_mfma_f32_16x16x32_bf16 v[4:7], v[80:83], v[176:179], v[4:7]
	v_mfma_f32_16x16x32_bf16 v[188:191], v[84:87], v[176:179], v[188:191]
	v_mfma_f32_16x16x32_bf16 v[96:99], v[88:91], v[176:179], v[96:99]
	ds_read_b128 v[176:179], v75 offset:28672
	global_load_dwordx4 v[164:167], v67, s[84:85] offset:0
	s_waitcnt lgkmcnt(5)
	v_mfma_f32_16x16x32_bf16 v[36:39], v[76:79], v[180:183], v[36:39]
	v_mfma_f32_16x16x32_bf16 v[12:15], v[80:83], v[180:183], v[12:15]
	v_mfma_f32_16x16x32_bf16 v[208:211], v[84:87], v[180:183], v[208:211]
	v_mfma_f32_16x16x32_bf16 v[100:103], v[88:91], v[180:183], v[100:103]
	ds_read_b128 v[180:183], v75 offset:30720
	global_load_dwordx4 v[168:171], v66, s[92:93] offset:0
	s_waitcnt lgkmcnt(5)
	v_mfma_f32_16x16x32_bf16 v[40:43], v[76:79], v[184:187], v[40:43]
	v_mfma_f32_16x16x32_bf16 v[16:19], v[80:83], v[184:187], v[16:19]
	v_mfma_f32_16x16x32_bf16 v[232:235], v[84:87], v[184:187], v[232:235]
	v_mfma_f32_16x16x32_bf16 v[104:107], v[88:91], v[184:187], v[104:107]
	ds_read_b128 v[184:187], v212 offset:16384
	global_load_dwordx4 v[172:175], v67, s[92:93] offset:0
	s_waitcnt lgkmcnt(5)
	v_mfma_f32_16x16x32_bf16 v[44:47], v[76:79], v[192:195], v[44:47]
	v_mfma_f32_16x16x32_bf16 v[20:23], v[80:83], v[192:195], v[20:23]
	v_mfma_f32_16x16x32_bf16 v[236:239], v[84:87], v[192:195], v[236:239]
	v_mfma_f32_16x16x32_bf16 v[108:111], v[88:91], v[192:195], v[108:111]
	ds_read_b128 v[192:195], v212 offset:18432
	s_waitcnt lgkmcnt(5)
	v_mfma_f32_16x16x32_bf16 v[48:51], v[76:79], v[196:199], v[48:51]
	v_mfma_f32_16x16x32_bf16 v[0:3], v[80:83], v[196:199], v[0:3]
	v_mfma_f32_16x16x32_bf16 v[240:243], v[84:87], v[196:199], v[240:243]
	v_mfma_f32_16x16x32_bf16 v[112:115], v[88:91], v[196:199], v[112:115]
	ds_read_b128 v[196:199], v212 offset:20480
	s_waitcnt lgkmcnt(5)
	v_mfma_f32_16x16x32_bf16 v[52:55], v[76:79], v[200:203], v[52:55]
	v_mfma_f32_16x16x32_bf16 v[8:11], v[80:83], v[200:203], v[8:11]
	v_mfma_f32_16x16x32_bf16 v[248:251], v[84:87], v[200:203], v[248:251]
	v_mfma_f32_16x16x32_bf16 v[116:119], v[88:91], v[200:203], v[116:119]
	ds_read_b128 v[200:203], v212 offset:22528
	s_waitcnt lgkmcnt(5)
	v_mfma_f32_16x16x32_bf16 v[56:59], v[76:79], v[176:179], v[56:59]
	v_mfma_f32_16x16x32_bf16 v[24:27], v[80:83], v[176:179], v[24:27]
	v_mfma_f32_16x16x32_bf16 v[252:255], v[84:87], v[176:179], v[252:255]
	v_mfma_f32_16x16x32_bf16 v[120:123], v[88:91], v[176:179], v[120:123]
	ds_read_b128 v[176:179], v212 offset:24576
	s_waitcnt lgkmcnt(5)
	v_mfma_f32_16x16x32_bf16 v[60:63], v[76:79], v[180:183], v[60:63]
	v_mfma_f32_16x16x32_bf16 v[28:31], v[80:83], v[180:183], v[28:31]
	v_mfma_f32_16x16x32_bf16 v[92:95], v[84:87], v[180:183], v[92:95]
	v_mfma_f32_16x16x32_bf16 v[124:127], v[88:91], v[180:183], v[124:127]
	s_waitcnt vmcnt(16)
	s_barrier
	s_waitcnt vmcnt(8)
	ds_read_b128 v[180:183], v212 offset:26624
	global_load_dwordx4 v[76:79], v66, s[84:85] offset:1024
	s_waitcnt lgkmcnt(5)
	v_mfma_f32_16x16x32_bf16 v[32:35], v[140:143], v[184:187], v[32:35]
	v_mfma_f32_16x16x32_bf16 v[4:7], v[144:147], v[184:187], v[4:7]
	v_mfma_f32_16x16x32_bf16 v[188:191], v[148:151], v[184:187], v[188:191]
	v_mfma_f32_16x16x32_bf16 v[96:99], v[204:207], v[184:187], v[96:99]
	ds_read_b128 v[184:187], v212 offset:28672
	global_load_dwordx4 v[80:83], v67, s[84:85] offset:1024
	s_waitcnt lgkmcnt(5)
	v_mfma_f32_16x16x32_bf16 v[36:39], v[140:143], v[192:195], v[36:39]
	v_mfma_f32_16x16x32_bf16 v[12:15], v[144:147], v[192:195], v[12:15]
	v_mfma_f32_16x16x32_bf16 v[208:211], v[148:151], v[192:195], v[208:211]
	v_mfma_f32_16x16x32_bf16 v[100:103], v[204:207], v[192:195], v[100:103]
	ds_read_b128 v[192:195], v212 offset:30720
	global_load_dwordx4 v[84:87], v66, s[92:93] offset:1024
	s_waitcnt lgkmcnt(5)
	v_mfma_f32_16x16x32_bf16 v[40:43], v[140:143], v[196:199], v[40:43]
	v_mfma_f32_16x16x32_bf16 v[16:19], v[144:147], v[196:199], v[16:19]
	v_mfma_f32_16x16x32_bf16 v[232:235], v[148:151], v[196:199], v[232:235]
	v_mfma_f32_16x16x32_bf16 v[104:107], v[204:207], v[196:199], v[104:107]
	ds_read_b128 v[196:199], v75 offset:32768
	global_load_dwordx4 v[88:91], v67, s[92:93] offset:1024
	s_add_u32 s84, s84, 0x800
	s_addc_u32 s85, s85, 0
	s_add_u32 s92, s92, 0x800
	s_addc_u32 s93, s93, 0
	s_waitcnt lgkmcnt(5)
	v_mfma_f32_16x16x32_bf16 v[44:47], v[140:143], v[200:203], v[44:47]
	v_mfma_f32_16x16x32_bf16 v[20:23], v[144:147], v[200:203], v[20:23]
	v_mfma_f32_16x16x32_bf16 v[236:239], v[148:151], v[200:203], v[236:239]
	v_mfma_f32_16x16x32_bf16 v[108:111], v[204:207], v[200:203], v[108:111]
	ds_read_b128 v[200:203], v75 offset:34816
	s_add_u32 m0, s88, 0
	s_nop 0
	global_load_lds_dwordx4 v68, s[86:87]
	s_waitcnt lgkmcnt(5)
	v_mfma_f32_16x16x32_bf16 v[48:51], v[140:143], v[176:179], v[48:51]
	v_mfma_f32_16x16x32_bf16 v[0:3], v[144:147], v[176:179], v[0:3]
	v_mfma_f32_16x16x32_bf16 v[240:243], v[148:151], v[176:179], v[240:243]
	v_mfma_f32_16x16x32_bf16 v[112:115], v[204:207], v[176:179], v[112:115]
	ds_read_b128 v[176:179], v75 offset:36864
	s_add_u32 m0, s88, 4096
	s_nop 0
	global_load_lds_dwordx4 v69, s[86:87]
	s_waitcnt lgkmcnt(5)
	v_mfma_f32_16x16x32_bf16 v[52:55], v[140:143], v[180:183], v[52:55]
	v_mfma_f32_16x16x32_bf16 v[8:11], v[144:147], v[180:183], v[8:11]
	v_mfma_f32_16x16x32_bf16 v[248:251], v[148:151], v[180:183], v[248:251]
	v_mfma_f32_16x16x32_bf16 v[116:119], v[204:207], v[180:183], v[116:119]
	ds_read_b128 v[180:183], v75 offset:38912
	s_add_u32 m0, s88, 8192
	s_nop 0
	global_load_lds_dwordx4 v71, s[86:87]
	s_waitcnt lgkmcnt(5)
	v_mfma_f32_16x16x32_bf16 v[56:59], v[140:143], v[184:187], v[56:59]
	v_mfma_f32_16x16x32_bf16 v[24:27], v[144:147], v[184:187], v[24:27]
	v_mfma_f32_16x16x32_bf16 v[252:255], v[148:151], v[184:187], v[252:255]
	v_mfma_f32_16x16x32_bf16 v[120:123], v[204:207], v[184:187], v[120:123]
	ds_read_b128 v[184:187], v75 offset:40960
	s_add_u32 m0, s88, 12288
	s_nop 0
	global_load_lds_dwordx4 v74, s[86:87]
	s_add_u32 s86, s86, 128
	s_addc_u32 s87, s87, 0
	s_waitcnt lgkmcnt(5)
	v_mfma_f32_16x16x32_bf16 v[60:63], v[140:143], v[192:195], v[60:63]
	v_mfma_f32_16x16x32_bf16 v[28:31], v[144:147], v[192:195], v[28:31]
	v_mfma_f32_16x16x32_bf16 v[92:95], v[148:151], v[192:195], v[92:95]
	v_mfma_f32_16x16x32_bf16 v[124:127], v[204:207], v[192:195], v[124:127]
	s_waitcnt vmcnt(8)
	ds_read_b128 v[192:195], v75 offset:43008
	global_load_dwordx4 v[140:143], v66, s[84:85] offset:0
	s_waitcnt lgkmcnt(5)
	v_mfma_f32_16x16x32_bf16 v[32:35], v[160:163], v[196:199], v[32:35]
	v_mfma_f32_16x16x32_bf16 v[4:7], v[164:167], v[196:199], v[4:7]
	v_mfma_f32_16x16x32_bf16 v[188:191], v[168:171], v[196:199], v[188:191]
	v_mfma_f32_16x16x32_bf16 v[96:99], v[172:175], v[196:199], v[96:99]
	ds_read_b128 v[196:199], v75 offset:45056
	global_load_dwordx4 v[144:147], v67, s[84:85] offset:0
	s_waitcnt lgkmcnt(5)
	v_mfma_f32_16x16x32_bf16 v[36:39], v[160:163], v[200:203], v[36:39]
	v_mfma_f32_16x16x32_bf16 v[12:15], v[164:167], v[200:203], v[12:15]
	v_mfma_f32_16x16x32_bf16 v[208:211], v[168:171], v[200:203], v[208:211]
	v_mfma_f32_16x16x32_bf16 v[100:103], v[172:175], v[200:203], v[100:103]
	ds_read_b128 v[200:203], v75 offset:47104
	global_load_dwordx4 v[148:151], v66, s[92:93] offset:0
	s_waitcnt lgkmcnt(5)
	v_mfma_f32_16x16x32_bf16 v[40:43], v[160:163], v[176:179], v[40:43]
	v_mfma_f32_16x16x32_bf16 v[16:19], v[164:167], v[176:179], v[16:19]
	v_mfma_f32_16x16x32_bf16 v[232:235], v[168:171], v[176:179], v[232:235]
	v_mfma_f32_16x16x32_bf16 v[104:107], v[172:175], v[176:179], v[104:107]
	ds_read_b128 v[176:179], v212 offset:32768
	global_load_dwordx4 v[204:207], v67, s[92:93] offset:0
	s_waitcnt lgkmcnt(5)
	v_mfma_f32_16x16x32_bf16 v[44:47], v[160:163], v[180:183], v[44:47]
	v_mfma_f32_16x16x32_bf16 v[20:23], v[164:167], v[180:183], v[20:23]
	v_mfma_f32_16x16x32_bf16 v[236:239], v[168:171], v[180:183], v[236:239]
	v_mfma_f32_16x16x32_bf16 v[108:111], v[172:175], v[180:183], v[108:111]
	ds_read_b128 v[180:183], v212 offset:34816
	s_waitcnt lgkmcnt(5)
	v_mfma_f32_16x16x32_bf16 v[48:51], v[160:163], v[184:187], v[48:51]
	v_mfma_f32_16x16x32_bf16 v[0:3], v[164:167], v[184:187], v[0:3]
	v_mfma_f32_16x16x32_bf16 v[240:243], v[168:171], v[184:187], v[240:243]
	v_mfma_f32_16x16x32_bf16 v[112:115], v[172:175], v[184:187], v[112:115]
	ds_read_b128 v[184:187], v212 offset:36864
	s_waitcnt lgkmcnt(5)
	v_mfma_f32_16x16x32_bf16 v[52:55], v[160:163], v[192:195], v[52:55]
	v_mfma_f32_16x16x32_bf16 v[8:11], v[164:167], v[192:195], v[8:11]
	v_mfma_f32_16x16x32_bf16 v[248:251], v[168:171], v[192:195], v[248:251]
	v_mfma_f32_16x16x32_bf16 v[116:119], v[172:175], v[192:195], v[116:119]
	ds_read_b128 v[192:195], v212 offset:38912
	s_waitcnt lgkmcnt(5)
	v_mfma_f32_16x16x32_bf16 v[56:59], v[160:163], v[196:199], v[56:59]
	v_mfma_f32_16x16x32_bf16 v[24:27], v[164:167], v[196:199], v[24:27]
	v_mfma_f32_16x16x32_bf16 v[252:255], v[168:171], v[196:199], v[252:255]
	v_mfma_f32_16x16x32_bf16 v[120:123], v[172:175], v[196:199], v[120:123]
	ds_read_b128 v[196:199], v212 offset:40960
	s_waitcnt lgkmcnt(5)
	v_mfma_f32_16x16x32_bf16 v[60:63], v[160:163], v[200:203], v[60:63]
	v_mfma_f32_16x16x32_bf16 v[28:31], v[164:167], v[200:203], v[28:31]
	v_mfma_f32_16x16x32_bf16 v[92:95], v[168:171], v[200:203], v[92:95]
	v_mfma_f32_16x16x32_bf16 v[124:127], v[172:175], v[200:203], v[124:127]
	s_waitcnt vmcnt(16)
	s_barrier
	s_waitcnt vmcnt(8)
	ds_read_b128 v[200:203], v212 offset:43008
	global_load_dwordx4 v[160:163], v66, s[84:85] offset:1024
	s_waitcnt lgkmcnt(5)
	v_mfma_f32_16x16x32_bf16 v[32:35], v[76:79], v[176:179], v[32:35]
	v_mfma_f32_16x16x32_bf16 v[4:7], v[80:83], v[176:179], v[4:7]
	v_mfma_f32_16x16x32_bf16 v[188:191], v[84:87], v[176:179], v[188:191]
	v_mfma_f32_16x16x32_bf16 v[96:99], v[88:91], v[176:179], v[96:99]
	ds_read_b128 v[176:179], v212 offset:45056
	global_load_dwordx4 v[164:167], v67, s[84:85] offset:1024
	s_waitcnt lgkmcnt(5)
	v_mfma_f32_16x16x32_bf16 v[36:39], v[76:79], v[180:183], v[36:39]
	v_mfma_f32_16x16x32_bf16 v[12:15], v[80:83], v[180:183], v[12:15]
	v_mfma_f32_16x16x32_bf16 v[208:211], v[84:87], v[180:183], v[208:211]
	v_mfma_f32_16x16x32_bf16 v[100:103], v[88:91], v[180:183], v[100:103]
	ds_read_b128 v[180:183], v212 offset:47104
	global_load_dwordx4 v[168:171], v66, s[92:93] offset:1024
	s_waitcnt lgkmcnt(5)
	v_mfma_f32_16x16x32_bf16 v[40:43], v[76:79], v[184:187], v[40:43]
	v_mfma_f32_16x16x32_bf16 v[16:19], v[80:83], v[184:187], v[16:19]
	v_mfma_f32_16x16x32_bf16 v[232:235], v[84:87], v[184:187], v[232:235]
	v_mfma_f32_16x16x32_bf16 v[104:107], v[88:91], v[184:187], v[104:107]
	ds_read_b128 v[184:187], v75 offset:49152
	global_load_dwordx4 v[172:175], v67, s[92:93] offset:1024
	s_add_u32 s84, s84, 0x800
	s_addc_u32 s85, s85, 0
	s_add_u32 s92, s92, 0x800
	s_addc_u32 s93, s93, 0
	s_waitcnt lgkmcnt(5)
	v_mfma_f32_16x16x32_bf16 v[44:47], v[76:79], v[192:195], v[44:47]
	v_mfma_f32_16x16x32_bf16 v[20:23], v[80:83], v[192:195], v[20:23]
	v_mfma_f32_16x16x32_bf16 v[236:239], v[84:87], v[192:195], v[236:239]
	v_mfma_f32_16x16x32_bf16 v[108:111], v[88:91], v[192:195], v[108:111]
	ds_read_b128 v[192:195], v75 offset:51200
	s_add_u32 m0, s88, 16384
	s_nop 0
	global_load_lds_dwordx4 v68, s[86:87]
	s_waitcnt lgkmcnt(5)
	v_mfma_f32_16x16x32_bf16 v[48:51], v[76:79], v[196:199], v[48:51]
	v_mfma_f32_16x16x32_bf16 v[0:3], v[80:83], v[196:199], v[0:3]
	v_mfma_f32_16x16x32_bf16 v[240:243], v[84:87], v[196:199], v[240:243]
	v_mfma_f32_16x16x32_bf16 v[112:115], v[88:91], v[196:199], v[112:115]
	ds_read_b128 v[196:199], v75 offset:53248
	s_add_u32 m0, s88, 20480
	s_nop 0
	global_load_lds_dwordx4 v69, s[86:87]
	s_waitcnt lgkmcnt(5)
	v_mfma_f32_16x16x32_bf16 v[52:55], v[76:79], v[200:203], v[52:55]
	v_mfma_f32_16x16x32_bf16 v[8:11], v[80:83], v[200:203], v[8:11]
	v_mfma_f32_16x16x32_bf16 v[248:251], v[84:87], v[200:203], v[248:251]
	v_mfma_f32_16x16x32_bf16 v[116:119], v[88:91], v[200:203], v[116:119]
	ds_read_b128 v[200:203], v75 offset:55296
	s_add_u32 m0, s88, 24576
	s_nop 0
	global_load_lds_dwordx4 v71, s[86:87]
	s_waitcnt lgkmcnt(5)
	v_mfma_f32_16x16x32_bf16 v[56:59], v[76:79], v[176:179], v[56:59]
	v_mfma_f32_16x16x32_bf16 v[24:27], v[80:83], v[176:179], v[24:27]
	v_mfma_f32_16x16x32_bf16 v[252:255], v[84:87], v[176:179], v[252:255]
	v_mfma_f32_16x16x32_bf16 v[120:123], v[88:91], v[176:179], v[120:123]
	ds_read_b128 v[176:179], v75 offset:57344
	s_add_u32 m0, s88, 28672
	s_nop 0
	global_load_lds_dwordx4 v74, s[86:87]
	s_add_u32 s86, s86, 128
	s_addc_u32 s87, s87, 0
	s_waitcnt lgkmcnt(5)
	v_mfma_f32_16x16x32_bf16 v[60:63], v[76:79], v[180:183], v[60:63]
	v_mfma_f32_16x16x32_bf16 v[28:31], v[80:83], v[180:183], v[28:31]
	v_mfma_f32_16x16x32_bf16 v[92:95], v[84:87], v[180:183], v[92:95]
	v_mfma_f32_16x16x32_bf16 v[124:127], v[88:91], v[180:183], v[124:127]
	s_waitcnt vmcnt(8)
	ds_read_b128 v[180:183], v75 offset:59392
	global_load_dwordx4 v[76:79], v66, s[84:85] offset:0
	s_waitcnt lgkmcnt(5)
	v_mfma_f32_16x16x32_bf16 v[32:35], v[140:143], v[184:187], v[32:35]
	v_mfma_f32_16x16x32_bf16 v[4:7], v[144:147], v[184:187], v[4:7]
	v_mfma_f32_16x16x32_bf16 v[188:191], v[148:151], v[184:187], v[188:191]
	v_mfma_f32_16x16x32_bf16 v[96:99], v[204:207], v[184:187], v[96:99]
	ds_read_b128 v[184:187], v75 offset:61440
	global_load_dwordx4 v[80:83], v67, s[84:85] offset:0
	s_waitcnt lgkmcnt(5)
	v_mfma_f32_16x16x32_bf16 v[36:39], v[140:143], v[192:195], v[36:39]
	v_mfma_f32_16x16x32_bf16 v[12:15], v[144:147], v[192:195], v[12:15]
	v_mfma_f32_16x16x32_bf16 v[208:211], v[148:151], v[192:195], v[208:211]
	v_mfma_f32_16x16x32_bf16 v[100:103], v[204:207], v[192:195], v[100:103]
	ds_read_b128 v[192:195], v75 offset:63488
	global_load_dwordx4 v[84:87], v66, s[92:93] offset:0
	s_waitcnt lgkmcnt(5)
	v_mfma_f32_16x16x32_bf16 v[40:43], v[140:143], v[196:199], v[40:43]
	v_mfma_f32_16x16x32_bf16 v[16:19], v[144:147], v[196:199], v[16:19]
	v_mfma_f32_16x16x32_bf16 v[232:235], v[148:151], v[196:199], v[232:235]
	v_mfma_f32_16x16x32_bf16 v[104:107], v[204:207], v[196:199], v[104:107]
	ds_read_b128 v[196:199], v212 offset:49152
	global_load_dwordx4 v[88:91], v67, s[92:93] offset:0
	s_waitcnt lgkmcnt(5)
	v_mfma_f32_16x16x32_bf16 v[44:47], v[140:143], v[200:203], v[44:47]
	v_mfma_f32_16x16x32_bf16 v[20:23], v[144:147], v[200:203], v[20:23]
	v_mfma_f32_16x16x32_bf16 v[236:239], v[148:151], v[200:203], v[236:239]
	v_mfma_f32_16x16x32_bf16 v[108:111], v[204:207], v[200:203], v[108:111]
	ds_read_b128 v[200:203], v212 offset:51200
	s_waitcnt lgkmcnt(5)
	v_mfma_f32_16x16x32_bf16 v[48:51], v[140:143], v[176:179], v[48:51]
	v_mfma_f32_16x16x32_bf16 v[0:3], v[144:147], v[176:179], v[0:3]
	v_mfma_f32_16x16x32_bf16 v[240:243], v[148:151], v[176:179], v[240:243]
	v_mfma_f32_16x16x32_bf16 v[112:115], v[204:207], v[176:179], v[112:115]
	ds_read_b128 v[176:179], v212 offset:53248
	s_waitcnt lgkmcnt(5)
	v_mfma_f32_16x16x32_bf16 v[52:55], v[140:143], v[180:183], v[52:55]
	v_mfma_f32_16x16x32_bf16 v[8:11], v[144:147], v[180:183], v[8:11]
	v_mfma_f32_16x16x32_bf16 v[248:251], v[148:151], v[180:183], v[248:251]
	v_mfma_f32_16x16x32_bf16 v[116:119], v[204:207], v[180:183], v[116:119]
	ds_read_b128 v[180:183], v212 offset:55296
	s_waitcnt lgkmcnt(5)
	v_mfma_f32_16x16x32_bf16 v[56:59], v[140:143], v[184:187], v[56:59]
	v_mfma_f32_16x16x32_bf16 v[24:27], v[144:147], v[184:187], v[24:27]
	v_mfma_f32_16x16x32_bf16 v[252:255], v[148:151], v[184:187], v[252:255]
	v_mfma_f32_16x16x32_bf16 v[120:123], v[204:207], v[184:187], v[120:123]
	ds_read_b128 v[184:187], v212 offset:57344
	s_waitcnt lgkmcnt(5)
	v_mfma_f32_16x16x32_bf16 v[60:63], v[140:143], v[192:195], v[60:63]
	v_mfma_f32_16x16x32_bf16 v[28:31], v[144:147], v[192:195], v[28:31]
	v_mfma_f32_16x16x32_bf16 v[92:95], v[148:151], v[192:195], v[92:95]
	v_mfma_f32_16x16x32_bf16 v[124:127], v[204:207], v[192:195], v[124:127]
	s_waitcnt vmcnt(16)
	s_barrier
	s_waitcnt vmcnt(8)
	ds_read_b128 v[192:195], v212 offset:59392
	global_load_dwordx4 v[140:143], v66, s[84:85] offset:1024
	s_waitcnt lgkmcnt(5)
	v_mfma_f32_16x16x32_bf16 v[32:35], v[160:163], v[196:199], v[32:35]
	v_mfma_f32_16x16x32_bf16 v[4:7], v[164:167], v[196:199], v[4:7]
	v_mfma_f32_16x16x32_bf16 v[188:191], v[168:171], v[196:199], v[188:191]
	v_mfma_f32_16x16x32_bf16 v[96:99], v[172:175], v[196:199], v[96:99]
	ds_read_b128 v[196:199], v212 offset:61440
	global_load_dwordx4 v[144:147], v67, s[84:85] offset:1024
	s_waitcnt lgkmcnt(5)
	v_mfma_f32_16x16x32_bf16 v[36:39], v[160:163], v[200:203], v[36:39]
	v_mfma_f32_16x16x32_bf16 v[12:15], v[164:167], v[200:203], v[12:15]
	v_mfma_f32_16x16x32_bf16 v[208:211], v[168:171], v[200:203], v[208:211]
	v_mfma_f32_16x16x32_bf16 v[100:103], v[172:175], v[200:203], v[100:103]
	ds_read_b128 v[200:203], v212 offset:63488
	global_load_dwordx4 v[148:151], v66, s[92:93] offset:1024
	s_waitcnt lgkmcnt(5)
	v_mfma_f32_16x16x32_bf16 v[40:43], v[160:163], v[176:179], v[40:43]
	v_mfma_f32_16x16x32_bf16 v[16:19], v[164:167], v[176:179], v[16:19]
	v_mfma_f32_16x16x32_bf16 v[232:235], v[168:171], v[176:179], v[232:235]
	v_mfma_f32_16x16x32_bf16 v[104:107], v[172:175], v[176:179], v[104:107]
	ds_read_b128 v[176:179], v75 offset:0
	global_load_dwordx4 v[204:207], v67, s[92:93] offset:1024
	s_add_u32 s84, s84, 0x800
	s_addc_u32 s85, s85, 0
	s_add_u32 s92, s92, 0x800
	s_addc_u32 s93, s93, 0
	s_waitcnt lgkmcnt(5)
	v_mfma_f32_16x16x32_bf16 v[44:47], v[160:163], v[180:183], v[44:47]
	v_mfma_f32_16x16x32_bf16 v[20:23], v[164:167], v[180:183], v[20:23]
	v_mfma_f32_16x16x32_bf16 v[236:239], v[168:171], v[180:183], v[236:239]
	v_mfma_f32_16x16x32_bf16 v[108:111], v[172:175], v[180:183], v[108:111]
	ds_read_b128 v[180:183], v75 offset:2048
	s_add_u32 m0, s88, 32768
	s_nop 0
	global_load_lds_dwordx4 v68, s[86:87]
	s_waitcnt lgkmcnt(5)
	v_mfma_f32_16x16x32_bf16 v[48:51], v[160:163], v[184:187], v[48:51]
	v_mfma_f32_16x16x32_bf16 v[0:3], v[164:167], v[184:187], v[0:3]
	v_mfma_f32_16x16x32_bf16 v[240:243], v[168:171], v[184:187], v[240:243]
	v_mfma_f32_16x16x32_bf16 v[112:115], v[172:175], v[184:187], v[112:115]
	ds_read_b128 v[184:187], v75 offset:4096
	s_add_u32 m0, s88, 36864
	s_nop 0
	global_load_lds_dwordx4 v69, s[86:87]
	s_waitcnt lgkmcnt(5)
	v_mfma_f32_16x16x32_bf16 v[52:55], v[160:163], v[192:195], v[52:55]
	v_mfma_f32_16x16x32_bf16 v[8:11], v[164:167], v[192:195], v[8:11]
	v_mfma_f32_16x16x32_bf16 v[248:251], v[168:171], v[192:195], v[248:251]
	v_mfma_f32_16x16x32_bf16 v[116:119], v[172:175], v[192:195], v[116:119]
	ds_read_b128 v[192:195], v75 offset:6144
	s_add_u32 m0, s88, 40960
	s_nop 0
	global_load_lds_dwordx4 v71, s[86:87]
	s_waitcnt lgkmcnt(5)
	v_mfma_f32_16x16x32_bf16 v[56:59], v[160:163], v[196:199], v[56:59]
	v_mfma_f32_16x16x32_bf16 v[24:27], v[164:167], v[196:199], v[24:27]
	v_mfma_f32_16x16x32_bf16 v[252:255], v[168:171], v[196:199], v[252:255]
	v_mfma_f32_16x16x32_bf16 v[120:123], v[172:175], v[196:199], v[120:123]
	ds_read_b128 v[196:199], v75 offset:8192
	s_add_u32 m0, s88, 45056
	s_nop 0
	global_load_lds_dwordx4 v74, s[86:87]
	s_add_u32 s86, s86, 128
	s_addc_u32 s87, s87, 0
	s_waitcnt lgkmcnt(5)
	v_mfma_f32_16x16x32_bf16 v[60:63], v[160:163], v[200:203], v[60:63]
	v_mfma_f32_16x16x32_bf16 v[28:31], v[164:167], v[200:203], v[28:31]
	v_mfma_f32_16x16x32_bf16 v[92:95], v[168:171], v[200:203], v[92:95]
	v_mfma_f32_16x16x32_bf16 v[124:127], v[172:175], v[200:203], v[124:127]
	s_waitcnt vmcnt(8)
	ds_read_b128 v[200:203], v75 offset:10240
	global_load_dwordx4 v[160:163], v66, s[84:85] offset:0
	s_waitcnt lgkmcnt(5)
	v_mfma_f32_16x16x32_bf16 v[32:35], v[76:79], v[176:179], v[32:35]
	v_mfma_f32_16x16x32_bf16 v[4:7], v[80:83], v[176:179], v[4:7]
	v_mfma_f32_16x16x32_bf16 v[188:191], v[84:87], v[176:179], v[188:191]
	v_mfma_f32_16x16x32_bf16 v[96:99], v[88:91], v[176:179], v[96:99]
	ds_read_b128 v[176:179], v75 offset:12288
	global_load_dwordx4 v[164:167], v67, s[84:85] offset:0
	s_waitcnt lgkmcnt(5)
	v_mfma_f32_16x16x32_bf16 v[36:39], v[76:79], v[180:183], v[36:39]
	v_mfma_f32_16x16x32_bf16 v[12:15], v[80:83], v[180:183], v[12:15]
	v_mfma_f32_16x16x32_bf16 v[208:211], v[84:87], v[180:183], v[208:211]
	v_mfma_f32_16x16x32_bf16 v[100:103], v[88:91], v[180:183], v[100:103]
	ds_read_b128 v[180:183], v75 offset:14336
	global_load_dwordx4 v[168:171], v66, s[92:93] offset:0
	s_waitcnt lgkmcnt(5)
	v_mfma_f32_16x16x32_bf16 v[40:43], v[76:79], v[184:187], v[40:43]
	v_mfma_f32_16x16x32_bf16 v[16:19], v[80:83], v[184:187], v[16:19]
	v_mfma_f32_16x16x32_bf16 v[232:235], v[84:87], v[184:187], v[232:235]
	v_mfma_f32_16x16x32_bf16 v[104:107], v[88:91], v[184:187], v[104:107]
	ds_read_b128 v[184:187], v212 offset:0
	global_load_dwordx4 v[172:175], v67, s[92:93] offset:0
	s_waitcnt lgkmcnt(5)
	v_mfma_f32_16x16x32_bf16 v[44:47], v[76:79], v[192:195], v[44:47]
	v_mfma_f32_16x16x32_bf16 v[20:23], v[80:83], v[192:195], v[20:23]
	v_mfma_f32_16x16x32_bf16 v[236:239], v[84:87], v[192:195], v[236:239]
	v_mfma_f32_16x16x32_bf16 v[108:111], v[88:91], v[192:195], v[108:111]
	ds_read_b128 v[192:195], v212 offset:2048
	s_waitcnt lgkmcnt(5)
	v_mfma_f32_16x16x32_bf16 v[48:51], v[76:79], v[196:199], v[48:51]
	v_mfma_f32_16x16x32_bf16 v[0:3], v[80:83], v[196:199], v[0:3]
	v_mfma_f32_16x16x32_bf16 v[240:243], v[84:87], v[196:199], v[240:243]
	v_mfma_f32_16x16x32_bf16 v[112:115], v[88:91], v[196:199], v[112:115]
	ds_read_b128 v[196:199], v212 offset:4096
	s_waitcnt lgkmcnt(5)
	v_mfma_f32_16x16x32_bf16 v[52:55], v[76:79], v[200:203], v[52:55]
	v_mfma_f32_16x16x32_bf16 v[8:11], v[80:83], v[200:203], v[8:11]
	v_mfma_f32_16x16x32_bf16 v[248:251], v[84:87], v[200:203], v[248:251]
	v_mfma_f32_16x16x32_bf16 v[116:119], v[88:91], v[200:203], v[116:119]
	ds_read_b128 v[200:203], v212 offset:6144
	s_waitcnt lgkmcnt(5)
	v_mfma_f32_16x16x32_bf16 v[56:59], v[76:79], v[176:179], v[56:59]
	v_mfma_f32_16x16x32_bf16 v[24:27], v[80:83], v[176:179], v[24:27]
	v_mfma_f32_16x16x32_bf16 v[252:255], v[84:87], v[176:179], v[252:255]
	v_mfma_f32_16x16x32_bf16 v[120:123], v[88:91], v[176:179], v[120:123]
	ds_read_b128 v[176:179], v212 offset:8192
	s_waitcnt lgkmcnt(5)
	v_mfma_f32_16x16x32_bf16 v[60:63], v[76:79], v[180:183], v[60:63]
	v_mfma_f32_16x16x32_bf16 v[28:31], v[80:83], v[180:183], v[28:31]
	v_mfma_f32_16x16x32_bf16 v[92:95], v[84:87], v[180:183], v[92:95]
	v_mfma_f32_16x16x32_bf16 v[124:127], v[88:91], v[180:183], v[124:127]
	s_waitcnt vmcnt(16)
	s_barrier
	s_waitcnt vmcnt(8)
	ds_read_b128 v[180:183], v212 offset:10240
	global_load_dwordx4 v[76:79], v66, s[84:85] offset:1024
	s_waitcnt lgkmcnt(5)
	v_mfma_f32_16x16x32_bf16 v[32:35], v[140:143], v[184:187], v[32:35]
	v_mfma_f32_16x16x32_bf16 v[4:7], v[144:147], v[184:187], v[4:7]
	v_mfma_f32_16x16x32_bf16 v[188:191], v[148:151], v[184:187], v[188:191]
	v_mfma_f32_16x16x32_bf16 v[96:99], v[204:207], v[184:187], v[96:99]
	ds_read_b128 v[184:187], v212 offset:12288
	global_load_dwordx4 v[80:83], v67, s[84:85] offset:1024
	s_waitcnt lgkmcnt(5)
	v_mfma_f32_16x16x32_bf16 v[36:39], v[140:143], v[192:195], v[36:39]
	v_mfma_f32_16x16x32_bf16 v[12:15], v[144:147], v[192:195], v[12:15]
	v_mfma_f32_16x16x32_bf16 v[208:211], v[148:151], v[192:195], v[208:211]
	v_mfma_f32_16x16x32_bf16 v[100:103], v[204:207], v[192:195], v[100:103]
	ds_read_b128 v[192:195], v212 offset:14336
	global_load_dwordx4 v[84:87], v66, s[92:93] offset:1024
	s_waitcnt lgkmcnt(5)
	v_mfma_f32_16x16x32_bf16 v[40:43], v[140:143], v[196:199], v[40:43]
	v_mfma_f32_16x16x32_bf16 v[16:19], v[144:147], v[196:199], v[16:19]
	v_mfma_f32_16x16x32_bf16 v[232:235], v[148:151], v[196:199], v[232:235]
	v_mfma_f32_16x16x32_bf16 v[104:107], v[204:207], v[196:199], v[104:107]
	ds_read_b128 v[196:199], v75 offset:16384
	global_load_dwordx4 v[88:91], v67, s[92:93] offset:1024
	s_add_u32 s84, s84, 0x800
	s_addc_u32 s85, s85, 0
	s_add_u32 s92, s92, 0x800
	s_addc_u32 s93, s93, 0
	s_waitcnt lgkmcnt(5)
	v_mfma_f32_16x16x32_bf16 v[44:47], v[140:143], v[200:203], v[44:47]
	v_mfma_f32_16x16x32_bf16 v[20:23], v[144:147], v[200:203], v[20:23]
	v_mfma_f32_16x16x32_bf16 v[236:239], v[148:151], v[200:203], v[236:239]
	v_mfma_f32_16x16x32_bf16 v[108:111], v[204:207], v[200:203], v[108:111]
	ds_read_b128 v[200:203], v75 offset:18432
	s_add_u32 m0, s88, 49152
	s_nop 0
	global_load_lds_dwordx4 v68, s[86:87]
	s_waitcnt lgkmcnt(5)
	v_mfma_f32_16x16x32_bf16 v[48:51], v[140:143], v[176:179], v[48:51]
	v_mfma_f32_16x16x32_bf16 v[0:3], v[144:147], v[176:179], v[0:3]
	v_mfma_f32_16x16x32_bf16 v[240:243], v[148:151], v[176:179], v[240:243]
	v_mfma_f32_16x16x32_bf16 v[112:115], v[204:207], v[176:179], v[112:115]
	ds_read_b128 v[176:179], v75 offset:20480
	s_add_u32 m0, s88, 53248
	s_nop 0
	global_load_lds_dwordx4 v69, s[86:87]
	s_waitcnt lgkmcnt(5)
	v_mfma_f32_16x16x32_bf16 v[52:55], v[140:143], v[180:183], v[52:55]
	v_mfma_f32_16x16x32_bf16 v[8:11], v[144:147], v[180:183], v[8:11]
	v_mfma_f32_16x16x32_bf16 v[248:251], v[148:151], v[180:183], v[248:251]
	v_mfma_f32_16x16x32_bf16 v[116:119], v[204:207], v[180:183], v[116:119]
	ds_read_b128 v[180:183], v75 offset:22528
	s_add_u32 m0, s88, 57344
	s_nop 0
	global_load_lds_dwordx4 v71, s[86:87]
	s_waitcnt lgkmcnt(5)
	v_mfma_f32_16x16x32_bf16 v[56:59], v[140:143], v[184:187], v[56:59]
	v_mfma_f32_16x16x32_bf16 v[24:27], v[144:147], v[184:187], v[24:27]
	v_mfma_f32_16x16x32_bf16 v[252:255], v[148:151], v[184:187], v[252:255]
	v_mfma_f32_16x16x32_bf16 v[120:123], v[204:207], v[184:187], v[120:123]
	ds_read_b128 v[184:187], v75 offset:24576
	s_add_u32 m0, s88, 61440
	s_nop 0
	global_load_lds_dwordx4 v74, s[86:87]
	s_add_u32 s86, s86, 128
	s_addc_u32 s87, s87, 0
	s_waitcnt lgkmcnt(5)
	v_mfma_f32_16x16x32_bf16 v[60:63], v[140:143], v[192:195], v[60:63]
	v_mfma_f32_16x16x32_bf16 v[28:31], v[144:147], v[192:195], v[28:31]
	v_mfma_f32_16x16x32_bf16 v[92:95], v[148:151], v[192:195], v[92:95]
	v_mfma_f32_16x16x32_bf16 v[124:127], v[204:207], v[192:195], v[124:127]
	s_waitcnt vmcnt(8)
	ds_read_b128 v[192:195], v75 offset:26624
	global_load_dwordx4 v[140:143], v66, s[84:85] offset:0
	s_waitcnt lgkmcnt(5)
	v_mfma_f32_16x16x32_bf16 v[32:35], v[160:163], v[196:199], v[32:35]
	v_mfma_f32_16x16x32_bf16 v[4:7], v[164:167], v[196:199], v[4:7]
	v_mfma_f32_16x16x32_bf16 v[188:191], v[168:171], v[196:199], v[188:191]
	v_mfma_f32_16x16x32_bf16 v[96:99], v[172:175], v[196:199], v[96:99]
	ds_read_b128 v[196:199], v75 offset:28672
	global_load_dwordx4 v[144:147], v67, s[84:85] offset:0
	s_waitcnt lgkmcnt(5)
	v_mfma_f32_16x16x32_bf16 v[36:39], v[160:163], v[200:203], v[36:39]
	v_mfma_f32_16x16x32_bf16 v[12:15], v[164:167], v[200:203], v[12:15]
	v_mfma_f32_16x16x32_bf16 v[208:211], v[168:171], v[200:203], v[208:211]
	v_mfma_f32_16x16x32_bf16 v[100:103], v[172:175], v[200:203], v[100:103]
	ds_read_b128 v[200:203], v75 offset:30720
	global_load_dwordx4 v[148:151], v66, s[92:93] offset:0
	s_waitcnt lgkmcnt(5)
	v_mfma_f32_16x16x32_bf16 v[40:43], v[160:163], v[176:179], v[40:43]
	v_mfma_f32_16x16x32_bf16 v[16:19], v[164:167], v[176:179], v[16:19]
	v_mfma_f32_16x16x32_bf16 v[232:235], v[168:171], v[176:179], v[232:235]
	v_mfma_f32_16x16x32_bf16 v[104:107], v[172:175], v[176:179], v[104:107]
	ds_read_b128 v[176:179], v212 offset:16384
	global_load_dwordx4 v[204:207], v67, s[92:93] offset:0
	s_waitcnt lgkmcnt(5)
	v_mfma_f32_16x16x32_bf16 v[44:47], v[160:163], v[180:183], v[44:47]
	v_mfma_f32_16x16x32_bf16 v[20:23], v[164:167], v[180:183], v[20:23]
	v_mfma_f32_16x16x32_bf16 v[236:239], v[168:171], v[180:183], v[236:239]
	v_mfma_f32_16x16x32_bf16 v[108:111], v[172:175], v[180:183], v[108:111]
	ds_read_b128 v[180:183], v212 offset:18432
	s_waitcnt lgkmcnt(5)
	v_mfma_f32_16x16x32_bf16 v[48:51], v[160:163], v[184:187], v[48:51]
	v_mfma_f32_16x16x32_bf16 v[0:3], v[164:167], v[184:187], v[0:3]
	v_mfma_f32_16x16x32_bf16 v[240:243], v[168:171], v[184:187], v[240:243]
	v_mfma_f32_16x16x32_bf16 v[112:115], v[172:175], v[184:187], v[112:115]
	ds_read_b128 v[184:187], v212 offset:20480
	s_waitcnt lgkmcnt(5)
	v_mfma_f32_16x16x32_bf16 v[52:55], v[160:163], v[192:195], v[52:55]
	v_mfma_f32_16x16x32_bf16 v[8:11], v[164:167], v[192:195], v[8:11]
	v_mfma_f32_16x16x32_bf16 v[248:251], v[168:171], v[192:195], v[248:251]
	v_mfma_f32_16x16x32_bf16 v[116:119], v[172:175], v[192:195], v[116:119]
	ds_read_b128 v[192:195], v212 offset:22528
	s_waitcnt lgkmcnt(5)
	v_mfma_f32_16x16x32_bf16 v[56:59], v[160:163], v[196:199], v[56:59]
	v_mfma_f32_16x16x32_bf16 v[24:27], v[164:167], v[196:199], v[24:27]
	v_mfma_f32_16x16x32_bf16 v[252:255], v[168:171], v[196:199], v[252:255]
	v_mfma_f32_16x16x32_bf16 v[120:123], v[172:175], v[196:199], v[120:123]
	ds_read_b128 v[196:199], v212 offset:24576
	s_waitcnt lgkmcnt(5)
	v_mfma_f32_16x16x32_bf16 v[60:63], v[160:163], v[200:203], v[60:63]
	v_mfma_f32_16x16x32_bf16 v[28:31], v[164:167], v[200:203], v[28:31]
	v_mfma_f32_16x16x32_bf16 v[92:95], v[168:171], v[200:203], v[92:95]
	v_mfma_f32_16x16x32_bf16 v[124:127], v[172:175], v[200:203], v[124:127]
	s_waitcnt vmcnt(16)
	s_barrier
	s_waitcnt vmcnt(8)
	ds_read_b128 v[200:203], v212 offset:26624
	global_load_dwordx4 v[160:163], v66, s[84:85] offset:1024
	s_waitcnt lgkmcnt(5)
	v_mfma_f32_16x16x32_bf16 v[32:35], v[76:79], v[176:179], v[32:35]
	v_mfma_f32_16x16x32_bf16 v[4:7], v[80:83], v[176:179], v[4:7]
	v_mfma_f32_16x16x32_bf16 v[188:191], v[84:87], v[176:179], v[188:191]
	v_mfma_f32_16x16x32_bf16 v[96:99], v[88:91], v[176:179], v[96:99]
	ds_read_b128 v[176:179], v212 offset:28672
	global_load_dwordx4 v[164:167], v67, s[84:85] offset:1024
	s_waitcnt lgkmcnt(5)
	v_mfma_f32_16x16x32_bf16 v[36:39], v[76:79], v[180:183], v[36:39]
	v_mfma_f32_16x16x32_bf16 v[12:15], v[80:83], v[180:183], v[12:15]
	v_mfma_f32_16x16x32_bf16 v[208:211], v[84:87], v[180:183], v[208:211]
	v_mfma_f32_16x16x32_bf16 v[100:103], v[88:91], v[180:183], v[100:103]
	ds_read_b128 v[180:183], v212 offset:30720
	global_load_dwordx4 v[168:171], v66, s[92:93] offset:1024
	s_waitcnt lgkmcnt(5)
	v_mfma_f32_16x16x32_bf16 v[40:43], v[76:79], v[184:187], v[40:43]
	v_mfma_f32_16x16x32_bf16 v[16:19], v[80:83], v[184:187], v[16:19]
	v_mfma_f32_16x16x32_bf16 v[232:235], v[84:87], v[184:187], v[232:235]
	v_mfma_f32_16x16x32_bf16 v[104:107], v[88:91], v[184:187], v[104:107]
	ds_read_b128 v[184:187], v75 offset:32768
	global_load_dwordx4 v[172:175], v67, s[92:93] offset:1024
	s_add_u32 s84, s84, 0x800
	s_addc_u32 s85, s85, 0
	s_add_u32 s92, s92, 0x800
	s_addc_u32 s93, s93, 0
	s_waitcnt lgkmcnt(5)
	v_mfma_f32_16x16x32_bf16 v[44:47], v[76:79], v[192:195], v[44:47]
	v_mfma_f32_16x16x32_bf16 v[20:23], v[80:83], v[192:195], v[20:23]
	v_mfma_f32_16x16x32_bf16 v[236:239], v[84:87], v[192:195], v[236:239]
	v_mfma_f32_16x16x32_bf16 v[108:111], v[88:91], v[192:195], v[108:111]
	ds_read_b128 v[192:195], v75 offset:34816
	s_waitcnt lgkmcnt(5)
	v_mfma_f32_16x16x32_bf16 v[48:51], v[76:79], v[196:199], v[48:51]
	v_mfma_f32_16x16x32_bf16 v[0:3], v[80:83], v[196:199], v[0:3]
	v_mfma_f32_16x16x32_bf16 v[240:243], v[84:87], v[196:199], v[240:243]
	v_mfma_f32_16x16x32_bf16 v[112:115], v[88:91], v[196:199], v[112:115]
	ds_read_b128 v[196:199], v75 offset:36864
	s_waitcnt lgkmcnt(5)
	v_mfma_f32_16x16x32_bf16 v[52:55], v[76:79], v[200:203], v[52:55]
	v_mfma_f32_16x16x32_bf16 v[8:11], v[80:83], v[200:203], v[8:11]
	v_mfma_f32_16x16x32_bf16 v[248:251], v[84:87], v[200:203], v[248:251]
	v_mfma_f32_16x16x32_bf16 v[116:119], v[88:91], v[200:203], v[116:119]
	ds_read_b128 v[200:203], v75 offset:38912
	s_waitcnt lgkmcnt(5)
	v_mfma_f32_16x16x32_bf16 v[56:59], v[76:79], v[176:179], v[56:59]
	v_mfma_f32_16x16x32_bf16 v[24:27], v[80:83], v[176:179], v[24:27]
	v_mfma_f32_16x16x32_bf16 v[252:255], v[84:87], v[176:179], v[252:255]
	v_mfma_f32_16x16x32_bf16 v[120:123], v[88:91], v[176:179], v[120:123]
	ds_read_b128 v[176:179], v75 offset:40960
	s_waitcnt lgkmcnt(5)
	v_mfma_f32_16x16x32_bf16 v[60:63], v[76:79], v[180:183], v[60:63]
	v_mfma_f32_16x16x32_bf16 v[28:31], v[80:83], v[180:183], v[28:31]
	v_mfma_f32_16x16x32_bf16 v[92:95], v[84:87], v[180:183], v[92:95]
	v_mfma_f32_16x16x32_bf16 v[124:127], v[88:91], v[180:183], v[124:127]
	s_waitcnt vmcnt(4)
	ds_read_b128 v[180:183], v75 offset:43008
	global_load_dwordx4 v[76:79], v66, s[84:85] offset:0
	s_waitcnt lgkmcnt(5)
	v_mfma_f32_16x16x32_bf16 v[32:35], v[140:143], v[184:187], v[32:35]
	v_mfma_f32_16x16x32_bf16 v[4:7], v[144:147], v[184:187], v[4:7]
	v_mfma_f32_16x16x32_bf16 v[188:191], v[148:151], v[184:187], v[188:191]
	v_mfma_f32_16x16x32_bf16 v[96:99], v[204:207], v[184:187], v[96:99]
	ds_read_b128 v[184:187], v75 offset:45056
	global_load_dwordx4 v[80:83], v67, s[84:85] offset:0
	s_waitcnt lgkmcnt(5)
	v_mfma_f32_16x16x32_bf16 v[36:39], v[140:143], v[192:195], v[36:39]
	v_mfma_f32_16x16x32_bf16 v[12:15], v[144:147], v[192:195], v[12:15]
	v_mfma_f32_16x16x32_bf16 v[208:211], v[148:151], v[192:195], v[208:211]
	v_mfma_f32_16x16x32_bf16 v[100:103], v[204:207], v[192:195], v[100:103]
	ds_read_b128 v[192:195], v75 offset:47104
	global_load_dwordx4 v[84:87], v66, s[92:93] offset:0
	s_waitcnt lgkmcnt(5)
	v_mfma_f32_16x16x32_bf16 v[40:43], v[140:143], v[196:199], v[40:43]
	v_mfma_f32_16x16x32_bf16 v[16:19], v[144:147], v[196:199], v[16:19]
	v_mfma_f32_16x16x32_bf16 v[232:235], v[148:151], v[196:199], v[232:235]
	v_mfma_f32_16x16x32_bf16 v[104:107], v[204:207], v[196:199], v[104:107]
	ds_read_b128 v[196:199], v212 offset:32768
	global_load_dwordx4 v[88:91], v67, s[92:93] offset:0
	s_waitcnt lgkmcnt(5)
	v_mfma_f32_16x16x32_bf16 v[44:47], v[140:143], v[200:203], v[44:47]
	v_mfma_f32_16x16x32_bf16 v[20:23], v[144:147], v[200:203], v[20:23]
	v_mfma_f32_16x16x32_bf16 v[236:239], v[148:151], v[200:203], v[236:239]
	v_mfma_f32_16x16x32_bf16 v[108:111], v[204:207], v[200:203], v[108:111]
	ds_read_b128 v[200:203], v212 offset:34816
	s_waitcnt lgkmcnt(5)
	v_mfma_f32_16x16x32_bf16 v[48:51], v[140:143], v[176:179], v[48:51]
	v_mfma_f32_16x16x32_bf16 v[0:3], v[144:147], v[176:179], v[0:3]
	v_mfma_f32_16x16x32_bf16 v[240:243], v[148:151], v[176:179], v[240:243]
	v_mfma_f32_16x16x32_bf16 v[112:115], v[204:207], v[176:179], v[112:115]
	ds_read_b128 v[176:179], v212 offset:36864
	s_waitcnt lgkmcnt(5)
	v_mfma_f32_16x16x32_bf16 v[52:55], v[140:143], v[180:183], v[52:55]
	v_mfma_f32_16x16x32_bf16 v[8:11], v[144:147], v[180:183], v[8:11]
	v_mfma_f32_16x16x32_bf16 v[248:251], v[148:151], v[180:183], v[248:251]
	v_mfma_f32_16x16x32_bf16 v[116:119], v[204:207], v[180:183], v[116:119]
	ds_read_b128 v[180:183], v212 offset:38912
	s_waitcnt lgkmcnt(5)
	v_mfma_f32_16x16x32_bf16 v[56:59], v[140:143], v[184:187], v[56:59]
	v_mfma_f32_16x16x32_bf16 v[24:27], v[144:147], v[184:187], v[24:27]
	v_mfma_f32_16x16x32_bf16 v[252:255], v[148:151], v[184:187], v[252:255]
	v_mfma_f32_16x16x32_bf16 v[120:123], v[204:207], v[184:187], v[120:123]
	ds_read_b128 v[184:187], v212 offset:40960
	s_waitcnt lgkmcnt(5)
	v_mfma_f32_16x16x32_bf16 v[60:63], v[140:143], v[192:195], v[60:63]
	v_mfma_f32_16x16x32_bf16 v[28:31], v[144:147], v[192:195], v[28:31]
	v_mfma_f32_16x16x32_bf16 v[92:95], v[148:151], v[192:195], v[92:95]
	v_mfma_f32_16x16x32_bf16 v[124:127], v[204:207], v[192:195], v[124:127]
	s_waitcnt vmcnt(12)
	s_barrier
	s_waitcnt vmcnt(4)
	ds_read_b128 v[192:195], v212 offset:43008
	global_load_dwordx4 v[140:143], v66, s[84:85] offset:1024
	s_waitcnt lgkmcnt(5)
	v_mfma_f32_16x16x32_bf16 v[32:35], v[160:163], v[196:199], v[32:35]
	v_mfma_f32_16x16x32_bf16 v[4:7], v[164:167], v[196:199], v[4:7]
	v_mfma_f32_16x16x32_bf16 v[188:191], v[168:171], v[196:199], v[188:191]
	v_mfma_f32_16x16x32_bf16 v[96:99], v[172:175], v[196:199], v[96:99]
	ds_read_b128 v[196:199], v212 offset:45056
	global_load_dwordx4 v[144:147], v67, s[84:85] offset:1024
	s_waitcnt lgkmcnt(5)
	v_mfma_f32_16x16x32_bf16 v[36:39], v[160:163], v[200:203], v[36:39]
	v_mfma_f32_16x16x32_bf16 v[12:15], v[164:167], v[200:203], v[12:15]
	v_mfma_f32_16x16x32_bf16 v[208:211], v[168:171], v[200:203], v[208:211]
	v_mfma_f32_16x16x32_bf16 v[100:103], v[172:175], v[200:203], v[100:103]
	ds_read_b128 v[200:203], v212 offset:47104
	global_load_dwordx4 v[148:151], v66, s[92:93] offset:1024
	s_waitcnt lgkmcnt(5)
	v_mfma_f32_16x16x32_bf16 v[40:43], v[160:163], v[176:179], v[40:43]
	v_mfma_f32_16x16x32_bf16 v[16:19], v[164:167], v[176:179], v[16:19]
	v_mfma_f32_16x16x32_bf16 v[232:235], v[168:171], v[176:179], v[232:235]
	v_mfma_f32_16x16x32_bf16 v[104:107], v[172:175], v[176:179], v[104:107]
	ds_read_b128 v[176:179], v75 offset:49152
	global_load_dwordx4 v[204:207], v67, s[92:93] offset:1024
	s_add_u32 s84, s84, 0x800
	s_addc_u32 s85, s85, 0
	s_add_u32 s92, s92, 0x800
	s_addc_u32 s93, s93, 0
	s_waitcnt lgkmcnt(5)
	v_mfma_f32_16x16x32_bf16 v[44:47], v[160:163], v[180:183], v[44:47]
	v_mfma_f32_16x16x32_bf16 v[20:23], v[164:167], v[180:183], v[20:23]
	v_mfma_f32_16x16x32_bf16 v[236:239], v[168:171], v[180:183], v[236:239]
	v_mfma_f32_16x16x32_bf16 v[108:111], v[172:175], v[180:183], v[108:111]
	ds_read_b128 v[180:183], v75 offset:51200
	s_waitcnt lgkmcnt(5)
	v_mfma_f32_16x16x32_bf16 v[48:51], v[160:163], v[184:187], v[48:51]
	v_mfma_f32_16x16x32_bf16 v[0:3], v[164:167], v[184:187], v[0:3]
	v_mfma_f32_16x16x32_bf16 v[240:243], v[168:171], v[184:187], v[240:243]
	v_mfma_f32_16x16x32_bf16 v[112:115], v[172:175], v[184:187], v[112:115]
	ds_read_b128 v[184:187], v75 offset:53248
	s_waitcnt lgkmcnt(5)
	v_mfma_f32_16x16x32_bf16 v[52:55], v[160:163], v[192:195], v[52:55]
	v_mfma_f32_16x16x32_bf16 v[8:11], v[164:167], v[192:195], v[8:11]
	v_mfma_f32_16x16x32_bf16 v[248:251], v[168:171], v[192:195], v[248:251]
	v_mfma_f32_16x16x32_bf16 v[116:119], v[172:175], v[192:195], v[116:119]
	ds_read_b128 v[192:195], v75 offset:55296
	s_waitcnt lgkmcnt(5)
	v_mfma_f32_16x16x32_bf16 v[56:59], v[160:163], v[196:199], v[56:59]
	v_mfma_f32_16x16x32_bf16 v[24:27], v[164:167], v[196:199], v[24:27]
	v_mfma_f32_16x16x32_bf16 v[252:255], v[168:171], v[196:199], v[252:255]
	v_mfma_f32_16x16x32_bf16 v[120:123], v[172:175], v[196:199], v[120:123]
	ds_read_b128 v[196:199], v75 offset:57344
	s_waitcnt lgkmcnt(5)
	v_mfma_f32_16x16x32_bf16 v[60:63], v[160:163], v[200:203], v[60:63]
	v_mfma_f32_16x16x32_bf16 v[28:31], v[164:167], v[200:203], v[28:31]
	v_mfma_f32_16x16x32_bf16 v[92:95], v[168:171], v[200:203], v[92:95]
	v_mfma_f32_16x16x32_bf16 v[124:127], v[172:175], v[200:203], v[124:127]
	s_waitcnt vmcnt(4)
	ds_read_b128 v[200:203], v75 offset:59392
	s_waitcnt lgkmcnt(5)
	v_mfma_f32_16x16x32_bf16 v[32:35], v[76:79], v[176:179], v[32:35]
	v_mfma_f32_16x16x32_bf16 v[4:7], v[80:83], v[176:179], v[4:7]
	v_mfma_f32_16x16x32_bf16 v[188:191], v[84:87], v[176:179], v[188:191]
	v_mfma_f32_16x16x32_bf16 v[96:99], v[88:91], v[176:179], v[96:99]
	ds_read_b128 v[176:179], v75 offset:61440
	s_waitcnt lgkmcnt(5)
	v_mfma_f32_16x16x32_bf16 v[36:39], v[76:79], v[180:183], v[36:39]
	v_mfma_f32_16x16x32_bf16 v[12:15], v[80:83], v[180:183], v[12:15]
	v_mfma_f32_16x16x32_bf16 v[208:211], v[84:87], v[180:183], v[208:211]
	v_mfma_f32_16x16x32_bf16 v[100:103], v[88:91], v[180:183], v[100:103]
	ds_read_b128 v[180:183], v75 offset:63488
	s_waitcnt lgkmcnt(5)
	v_mfma_f32_16x16x32_bf16 v[40:43], v[76:79], v[184:187], v[40:43]
	v_mfma_f32_16x16x32_bf16 v[16:19], v[80:83], v[184:187], v[16:19]
	v_mfma_f32_16x16x32_bf16 v[232:235], v[84:87], v[184:187], v[232:235]
	v_mfma_f32_16x16x32_bf16 v[104:107], v[88:91], v[184:187], v[104:107]
	ds_read_b128 v[184:187], v212 offset:49152
	s_waitcnt lgkmcnt(5)
	v_mfma_f32_16x16x32_bf16 v[44:47], v[76:79], v[192:195], v[44:47]
	v_mfma_f32_16x16x32_bf16 v[20:23], v[80:83], v[192:195], v[20:23]
	v_mfma_f32_16x16x32_bf16 v[236:239], v[84:87], v[192:195], v[236:239]
	v_mfma_f32_16x16x32_bf16 v[108:111], v[88:91], v[192:195], v[108:111]
	ds_read_b128 v[192:195], v212 offset:51200
	s_waitcnt lgkmcnt(5)
	v_mfma_f32_16x16x32_bf16 v[48:51], v[76:79], v[196:199], v[48:51]
	v_mfma_f32_16x16x32_bf16 v[0:3], v[80:83], v[196:199], v[0:3]
	v_mfma_f32_16x16x32_bf16 v[240:243], v[84:87], v[196:199], v[240:243]
	v_mfma_f32_16x16x32_bf16 v[112:115], v[88:91], v[196:199], v[112:115]
	ds_read_b128 v[196:199], v212 offset:53248
	s_waitcnt lgkmcnt(5)
	v_mfma_f32_16x16x32_bf16 v[52:55], v[76:79], v[200:203], v[52:55]
	v_mfma_f32_16x16x32_bf16 v[8:11], v[80:83], v[200:203], v[8:11]
	v_mfma_f32_16x16x32_bf16 v[248:251], v[84:87], v[200:203], v[248:251]
	v_mfma_f32_16x16x32_bf16 v[116:119], v[88:91], v[200:203], v[116:119]
	ds_read_b128 v[200:203], v212 offset:55296
	s_waitcnt lgkmcnt(5)
	v_mfma_f32_16x16x32_bf16 v[56:59], v[76:79], v[176:179], v[56:59]
	v_mfma_f32_16x16x32_bf16 v[24:27], v[80:83], v[176:179], v[24:27]
	v_mfma_f32_16x16x32_bf16 v[252:255], v[84:87], v[176:179], v[252:255]
	v_mfma_f32_16x16x32_bf16 v[120:123], v[88:91], v[176:179], v[120:123]
	ds_read_b128 v[176:179], v212 offset:57344
	s_waitcnt lgkmcnt(5)
	v_mfma_f32_16x16x32_bf16 v[60:63], v[76:79], v[180:183], v[60:63]
	v_mfma_f32_16x16x32_bf16 v[28:31], v[80:83], v[180:183], v[28:31]
	v_mfma_f32_16x16x32_bf16 v[92:95], v[84:87], v[180:183], v[92:95]
	v_mfma_f32_16x16x32_bf16 v[124:127], v[88:91], v[180:183], v[124:127]
	s_waitcnt vmcnt(0)
	ds_read_b128 v[180:183], v212 offset:59392
	s_waitcnt lgkmcnt(5)
	v_mfma_f32_16x16x32_bf16 v[32:35], v[140:143], v[184:187], v[32:35]
	v_mfma_f32_16x16x32_bf16 v[4:7], v[144:147], v[184:187], v[4:7]
	v_mfma_f32_16x16x32_bf16 v[188:191], v[148:151], v[184:187], v[188:191]
	v_mfma_f32_16x16x32_bf16 v[96:99], v[204:207], v[184:187], v[96:99]
	ds_read_b128 v[184:187], v212 offset:61440
	s_waitcnt lgkmcnt(5)
	v_mfma_f32_16x16x32_bf16 v[36:39], v[140:143], v[192:195], v[36:39]
	v_mfma_f32_16x16x32_bf16 v[12:15], v[144:147], v[192:195], v[12:15]
	v_mfma_f32_16x16x32_bf16 v[208:211], v[148:151], v[192:195], v[208:211]
	v_mfma_f32_16x16x32_bf16 v[100:103], v[204:207], v[192:195], v[100:103]
	ds_read_b128 v[192:195], v212 offset:63488
	s_waitcnt lgkmcnt(5)
	v_mfma_f32_16x16x32_bf16 v[40:43], v[140:143], v[196:199], v[40:43]
	v_mfma_f32_16x16x32_bf16 v[16:19], v[144:147], v[196:199], v[16:19]
	v_mfma_f32_16x16x32_bf16 v[232:235], v[148:151], v[196:199], v[232:235]
	v_mfma_f32_16x16x32_bf16 v[104:107], v[204:207], v[196:199], v[104:107]
	s_waitcnt lgkmcnt(4)
	v_mfma_f32_16x16x32_bf16 v[44:47], v[140:143], v[200:203], v[44:47]
	v_mfma_f32_16x16x32_bf16 v[20:23], v[144:147], v[200:203], v[20:23]
	v_mfma_f32_16x16x32_bf16 v[236:239], v[148:151], v[200:203], v[236:239]
	v_mfma_f32_16x16x32_bf16 v[108:111], v[204:207], v[200:203], v[108:111]
	s_waitcnt lgkmcnt(3)
	v_mfma_f32_16x16x32_bf16 v[48:51], v[140:143], v[176:179], v[48:51]
	v_mfma_f32_16x16x32_bf16 v[0:3], v[144:147], v[176:179], v[0:3]
	v_mfma_f32_16x16x32_bf16 v[240:243], v[148:151], v[176:179], v[240:243]
	v_mfma_f32_16x16x32_bf16 v[112:115], v[204:207], v[176:179], v[112:115]
	s_waitcnt lgkmcnt(2)
	v_mfma_f32_16x16x32_bf16 v[52:55], v[140:143], v[180:183], v[52:55]
	v_mfma_f32_16x16x32_bf16 v[8:11], v[144:147], v[180:183], v[8:11]
	v_mfma_f32_16x16x32_bf16 v[248:251], v[148:151], v[180:183], v[248:251]
	v_mfma_f32_16x16x32_bf16 v[116:119], v[204:207], v[180:183], v[116:119]
	s_waitcnt lgkmcnt(1)
	v_mfma_f32_16x16x32_bf16 v[56:59], v[140:143], v[184:187], v[56:59]
	v_mfma_f32_16x16x32_bf16 v[24:27], v[144:147], v[184:187], v[24:27]
	v_mfma_f32_16x16x32_bf16 v[252:255], v[148:151], v[184:187], v[252:255]
	v_mfma_f32_16x16x32_bf16 v[120:123], v[204:207], v[184:187], v[120:123]
	s_waitcnt lgkmcnt(0)
	v_mfma_f32_16x16x32_bf16 v[60:63], v[140:143], v[192:195], v[60:63]
	v_mfma_f32_16x16x32_bf16 v[28:31], v[144:147], v[192:195], v[28:31]
	v_mfma_f32_16x16x32_bf16 v[92:95], v[148:151], v[192:195], v[92:95]
	v_mfma_f32_16x16x32_bf16 v[124:127], v[204:207], v[192:195], v[124:127]
	s_nop 7
	s_nop 7
	s_waitcnt vmcnt(0) lgkmcnt(0)
	s_setprio 0
	s_barrier
	v_mov_b32_e32 v66, v92
	v_mov_b32_e32 v67, v93
	v_mov_b32_e32 v68, v94
	v_mov_b32_e32 v69, v95
	v_mov_b32_e32 v71, v96
	v_mov_b32_e32 v74, v97
	v_mov_b32_e32 v75, v98
	v_mov_b32_e32 v160, v99
	v_mov_b32_e32 v161, v100
	v_mov_b32_e32 v162, v101
	v_mov_b32_e32 v185, v102
	v_mov_b32_e32 v186, v103
	v_mov_b32_e32 v187, v104
	v_mov_b32_e32 v207, v105
	v_mov_b32_e32 v212, v106
	v_mov_b32_e32 v213, v107
	v_mov_b32_e32 v214, v108
	v_mov_b32_e32 v216, v109
	v_mov_b32_e32 v218, v110
	v_mov_b32_e32 v220, v111
	v_mov_b32_e32 v222, v112
	v_mov_b32_e32 v224, v113
	v_mov_b32_e32 v226, v114
	v_mov_b32_e32 v228, v115
	v_mov_b32_e32 v230, v116
	v_mov_b32_e32 v231, v117
	v_mov_b32_e32 v244, v118
	v_mov_b32_e32 v245, v119
	ds_write_b128 v129, v[120:123] offset:36864
	ds_write_b128 v129, v[124:127] offset:40960
	v_lshlrev_b32_e32 v77, 13, v135
	v_lshl_add_u32 v78, v134, 3, v138
	v_lshl_or_b32 v79, v134, 11, v77
	v_lshlrev_b32_e32 v81, 5, v138
	v_or3_b32 v163, v77, v137, v81
	v_lshl_or_b32 v164, v78, 2, v79
	v_add_u32_e32 v81, 0x60, v78
	v_add_u32_e32 v78, 0x70, v78
	v_and_b32_e32 v81, 0x7f, v81
	v_and_b32_e32 v78, 0x7f, v78
	v_lshl_or_b32 v165, v81, 2, v79
	v_lshl_or_b32 v166, v78, 2, v79
	v_add_u32_e32 v79, 8, v133
	v_and_b32_e32 v79, 0x78, v79
	v_lshlrev_b32_e32 v78, 9, v136
	v_lshlrev_b32_e32 v79, 2, v79
	v_or3_b32 v168, v77, v78, v79
	v_add_u32_e32 v79, 16, v133
	v_and_b32_e32 v79, 0x78, v79
	v_lshlrev_b32_e32 v78, 9, v132
	v_lshlrev_b32_e32 v79, 2, v79
	v_or3_b32 v170, v77, v78, v79
	v_add_u32_e32 v79, 24, v133
	v_and_b32_e32 v79, 0x78, v79
	v_lshlrev_b32_e32 v80, 5, v135
	v_lshlrev_b32_e32 v78, 9, v130
	v_lshlrev_b32_e32 v79, 2, v79
	v_or3_b32 v172, v77, v78, v79
	v_or_b32_e32 v77, 16, v80
	v_add_u32_e32 v81, 0x100, v131
	v_add_u32_e32 v82, 0x200, v131
	v_add_u32_e32 v83, 0x300, v131
	v_add_u32_e32 v84, 0x500, v131
	v_add_u32_e32 v85, 0x600, v131
	v_add_u32_e32 v86, 0x700, v131
	v_or_b32_e32 v174, v77, v134
	v_or_b32_e32 v175, v136, v77
	v_or_b32_e32 v176, v132, v77
	v_or_b32_e32 v177, v130, v77
	v_and_b32_e32 v77, 24, v153
	s_movk_i32 s94, 0x3c0
	v_lshrrev_b32_e32 v178, 4, v81
	v_lshrrev_b32_e32 v179, 4, v82
	v_lshrrev_b32_e32 v180, 4, v83
	v_lshrrev_b32_e32 v182, 4, v84
	v_lshrrev_b32_e32 v183, 4, v85
	v_lshrrev_b32_e32 v184, 4, v86
	v_or_b32_e32 v167, v134, v80
	v_or_b32_e32 v169, v136, v80
	v_or_b32_e32 v171, v132, v80
	v_or_b32_e32 v173, v130, v80
	v_and_or_b32 v77, v131, s94, v77
	v_mul_u32_u24_e32 v78, 0x110, v138
	v_lshlrev_b32_e32 v79, 4, v138
	v_mul_u32_u24_e32 v80, 0x110, v128
	v_mul_u32_u24_e32 v81, 0x110, v178
	v_mul_u32_u24_e32 v82, 0x110, v179
	v_mul_u32_u24_e32 v83, 0x110, v180
	v_mul_u32_u24_e32 v84, 0x110, v182
	v_mul_u32_u24_e32 v85, 0x110, v183
	v_mul_u32_u24_e32 v86, 0x110, v184
	v_or_b32_e32 v181, 64, v128
	v_lshlrev_b32_e32 v192, 2, v138
	v_add_u32_e32 v193, v77, v78
	v_add_u32_e32 v194, v79, v80
	v_add_u32_e32 v195, v79, v81
	v_add_u32_e32 v196, v79, v82
	v_add_u32_e32 v197, v79, v83
	v_add_u32_e32 v198, v79, v84
	v_add_u32_e32 v199, v79, v85
	v_add_u32_e32 v200, v79, v86
	v_mbcnt_hi_u32_b32 v201, -1, v155
	v_mov_b32_e32 v202, 0x3db504f3
	s_waitcnt lgkmcnt(0)
	s_mov_b64 s[58:59], -1
	s_cmp_lt_i32 s65, 4
	s_branch .Lmy_ip1_epi
